# speedup vs baseline: 1.0062x; 1.0062x over previous
.LBB0_65:
	ds_read_b128 v[128:131], v173
	ds_read_b128 v[132:135], v173 offset:1024
	ds_read_b128 v[158:161], v173 offset:2048
	ds_read_b128 v[178:181], v173 offset:3072
	ds_read_b128 v[182:185], v174
	ds_read_b128 v[186:189], v174 offset:1024
	ds_read_b128 v[190:193], v174 offset:2048
	ds_read_b128 v[194:197], v174 offset:3072
	s_add_u32 s3, s14, 0xfff80080
	s_addc_u32 s34, s15, -1
	s_cmp_eq_u32 s37, 28
	s_cselect_b32 s91, s0, s34
	s_cselect_b32 s90, s1, s3
	s_cselect_b32 s35, s7, s36
	s_cselect_b32 s34, s13, s24
	s_add_i32 m0, s27, 0xc000
	ds_read_b128 v[198:201], v175
	ds_read_b128 v[202:205], v175 offset:1024
	ds_read_b128 v[206:209], v175 offset:2048
	ds_read_b128 v[210:213], v175 offset:3072
	ds_read_b128 v[214:217], v175 offset:4096
	ds_read_b128 v[218:221], v175 offset:5120
	ds_read_b128 v[222:225], v175 offset:6144
	ds_read_b128 v[230:233], v175 offset:7168
	global_load_lds_dwordx4 v148, s[14:15]
	s_add_i32 m0, s27, 0xe000
	s_nop 0
	global_load_lds_dwordx4 v150, s[14:15]
	s_waitcnt vmcnt(8)
	s_waitcnt lgkmcnt(0)
	s_barrier
	s_setprio 1
	v_mfma_f32_16x16x32_bf16 v[124:127], v[128:131], v[198:201], v[124:127]
	v_mfma_f32_16x16x32_bf16 v[120:123], v[158:161], v[198:201], v[120:123]
	v_mfma_f32_16x16x32_bf16 v[108:111], v[128:131], v[206:209], v[108:111]
	v_mfma_f32_16x16x32_bf16 v[104:107], v[158:161], v[206:209], v[104:107]
	v_mfma_f32_16x16x32_bf16 v[92:95], v[128:131], v[214:217], v[92:95]
	v_mfma_f32_16x16x32_bf16 v[88:91], v[158:161], v[214:217], v[88:91]
	v_mfma_f32_16x16x32_bf16 v[76:79], v[128:131], v[222:225], v[76:79]
	v_mfma_f32_16x16x32_bf16 v[72:75], v[158:161], v[222:225], v[72:75]
	v_mfma_f32_16x16x32_bf16 v[124:127], v[132:135], v[202:205], v[124:127]
	v_mfma_f32_16x16x32_bf16 v[120:123], v[178:181], v[202:205], v[120:123]
	v_mfma_f32_16x16x32_bf16 v[108:111], v[132:135], v[210:213], v[108:111]
	v_mfma_f32_16x16x32_bf16 v[104:107], v[178:181], v[210:213], v[104:107]
	v_mfma_f32_16x16x32_bf16 v[92:95], v[132:135], v[218:221], v[92:95]
	v_mfma_f32_16x16x32_bf16 v[88:91], v[178:181], v[218:221], v[88:91]
	v_mfma_f32_16x16x32_bf16 v[76:79], v[132:135], v[230:233], v[76:79]
	v_mfma_f32_16x16x32_bf16 v[72:75], v[178:181], v[230:233], v[72:75]
	v_mfma_f32_16x16x32_bf16 v[116:119], v[182:185], v[198:201], v[116:119]
	v_mfma_f32_16x16x32_bf16 v[112:115], v[190:193], v[198:201], v[112:115]
	v_mfma_f32_16x16x32_bf16 v[100:103], v[182:185], v[206:209], v[100:103]
	v_mfma_f32_16x16x32_bf16 v[96:99], v[190:193], v[206:209], v[96:99]
	v_mfma_f32_16x16x32_bf16 v[84:87], v[182:185], v[214:217], v[84:87]
	v_mfma_f32_16x16x32_bf16 v[80:83], v[190:193], v[214:217], v[80:83]
	v_mfma_f32_16x16x32_bf16 v[68:71], v[182:185], v[222:225], v[68:71]
	v_mfma_f32_16x16x32_bf16 v[64:67], v[190:193], v[222:225], v[64:67]
	v_mfma_f32_16x16x32_bf16 v[116:119], v[186:189], v[202:205], v[116:119]
	v_mfma_f32_16x16x32_bf16 v[112:115], v[194:197], v[202:205], v[112:115]
	v_mfma_f32_16x16x32_bf16 v[100:103], v[186:189], v[210:213], v[100:103]
	v_mfma_f32_16x16x32_bf16 v[96:99], v[194:197], v[210:213], v[96:99]
	v_mfma_f32_16x16x32_bf16 v[84:87], v[186:189], v[218:221], v[84:87]
	v_mfma_f32_16x16x32_bf16 v[80:83], v[194:197], v[218:221], v[80:83]
	v_mfma_f32_16x16x32_bf16 v[68:71], v[186:189], v[230:233], v[68:71]
	v_mfma_f32_16x16x32_bf16 v[64:67], v[194:197], v[230:233], v[64:67]
	s_setprio 0
	s_barrier
	s_add_i32 s3, s78, s25
	s_mov_b32 m0, s3
	ds_read_b128 v[198:201], v175 offset:16384
	ds_read_b128 v[202:205], v175 offset:17408
	ds_read_b128 v[206:209], v175 offset:18432
	ds_read_b128 v[210:213], v175 offset:19456
	ds_read_b128 v[214:217], v175 offset:20480
	ds_read_b128 v[218:221], v175 offset:21504
	ds_read_b128 v[222:225], v175 offset:22528
	ds_read_b128 v[230:233], v175 offset:23552
	global_load_lds_dwordx4 v138, s[34:35]
	s_add_i32 m0, s3, 0x2000
	s_add_u32 s42, s34, 0x80000
	s_addc_u32 s43, s35, 0
	s_add_i32 s3, s79, s25
	global_load_lds_dwordx4 v142, s[34:35]
	s_mov_b32 m0, s3
	s_nop 0
	global_load_lds_dwordx4 v138, s[42:43]
	s_add_i32 m0, s3, 0x2000
	s_nop 0
	global_load_lds_dwordx4 v142, s[42:43]
	s_mov_b32 m0, s27
	s_nop 0
	global_load_lds_dwordx4 v136, s[90:91]
	s_mov_b32 m0, s30
	s_nop 0
	global_load_lds_dwordx4 v140, s[90:91]
	s_waitcnt vmcnt(8)
	s_waitcnt lgkmcnt(0)
	s_barrier
	s_setprio 1
	v_mfma_f32_16x16x32_bf16 v[60:63], v[128:131], v[198:201], v[60:63]
	v_mfma_f32_16x16x32_bf16 v[56:59], v[158:161], v[198:201], v[56:59]
	v_mfma_f32_16x16x32_bf16 v[44:47], v[128:131], v[206:209], v[44:47]
	v_mfma_f32_16x16x32_bf16 v[40:43], v[158:161], v[206:209], v[40:43]
	v_mfma_f32_16x16x32_bf16 v[28:31], v[128:131], v[214:217], v[28:31]
	v_mfma_f32_16x16x32_bf16 v[24:27], v[158:161], v[214:217], v[24:27]
	v_mfma_f32_16x16x32_bf16 v[12:15], v[128:131], v[222:225], v[12:15]
	v_mfma_f32_16x16x32_bf16 v[8:11], v[158:161], v[222:225], v[8:11]
	v_mfma_f32_16x16x32_bf16 v[60:63], v[132:135], v[202:205], v[60:63]
	v_mfma_f32_16x16x32_bf16 v[56:59], v[178:181], v[202:205], v[56:59]
	v_mfma_f32_16x16x32_bf16 v[44:47], v[132:135], v[210:213], v[44:47]
	v_mfma_f32_16x16x32_bf16 v[40:43], v[178:181], v[210:213], v[40:43]
	v_mfma_f32_16x16x32_bf16 v[28:31], v[132:135], v[218:221], v[28:31]
	v_mfma_f32_16x16x32_bf16 v[24:27], v[178:181], v[218:221], v[24:27]
	v_mfma_f32_16x16x32_bf16 v[12:15], v[132:135], v[230:233], v[12:15]
	v_mfma_f32_16x16x32_bf16 v[8:11], v[178:181], v[230:233], v[8:11]
	v_mfma_f32_16x16x32_bf16 v[52:55], v[182:185], v[198:201], v[52:55]
	v_mfma_f32_16x16x32_bf16 v[48:51], v[190:193], v[198:201], v[48:51]
	v_mfma_f32_16x16x32_bf16 v[36:39], v[182:185], v[206:209], v[36:39]
	v_mfma_f32_16x16x32_bf16 v[32:35], v[190:193], v[206:209], v[32:35]
	v_mfma_f32_16x16x32_bf16 v[20:23], v[182:185], v[214:217], v[20:23]
	v_mfma_f32_16x16x32_bf16 v[16:19], v[190:193], v[214:217], v[16:19]
	v_mfma_f32_16x16x32_bf16 v[4:7], v[182:185], v[222:225], v[4:7]
	v_mfma_f32_16x16x32_bf16 v[0:3], v[190:193], v[222:225], v[0:3]
	v_mfma_f32_16x16x32_bf16 v[52:55], v[186:189], v[202:205], v[52:55]
	v_mfma_f32_16x16x32_bf16 v[48:51], v[194:197], v[202:205], v[48:51]
	v_mfma_f32_16x16x32_bf16 v[36:39], v[186:189], v[210:213], v[36:39]
	v_mfma_f32_16x16x32_bf16 v[32:35], v[194:197], v[210:213], v[32:35]
	v_mfma_f32_16x16x32_bf16 v[20:23], v[186:189], v[218:221], v[20:23]
	v_mfma_f32_16x16x32_bf16 v[16:19], v[194:197], v[218:221], v[16:19]
	v_mfma_f32_16x16x32_bf16 v[4:7], v[186:189], v[230:233], v[4:7]
	v_mfma_f32_16x16x32_bf16 v[0:3], v[194:197], v[230:233], v[0:3]
	s_setprio 0
	s_barrier
	s_add_i32 s3, 0, 0x18000
	v_add_u32_e32 v144, s3, v165
	s_add_i32 s44, 0, 0x1c000
	ds_read_b128 v[128:131], v144
	ds_read_b128 v[132:135], v144 offset:1024
	ds_read_b128 v[158:161], v144 offset:2048
	ds_read_b128 v[178:181], v144 offset:3072
	v_add_u32_e32 v144, s44, v165
	ds_read_b128 v[182:185], v144
	ds_read_b128 v[186:189], v144 offset:1024
	ds_read_b128 v[190:193], v144 offset:2048
	ds_read_b128 v[194:197], v144 offset:3072
	s_add_u32 s42, s90, 0x80000
	s_addc_u32 s43, s91, 0
	s_mov_b32 m0, s31
	ds_read_b128 v[198:201], v175 offset:32768
	ds_read_b128 v[202:205], v175 offset:33792
	ds_read_b128 v[206:209], v175 offset:34816
	ds_read_b128 v[210:213], v175 offset:35840
	ds_read_b128 v[214:217], v175 offset:36864
	ds_read_b128 v[218:221], v175 offset:37888
	ds_read_b128 v[222:225], v175 offset:38912
	ds_read_b128 v[230:233], v175 offset:39936
	global_load_lds_dwordx4 v136, s[42:43]
	s_mov_b32 m0, s33
	s_nop 0
	global_load_lds_dwordx4 v140, s[42:43]
	s_waitcnt vmcnt(8)
	s_waitcnt lgkmcnt(0)
	s_barrier
	s_setprio 1
	v_mfma_f32_16x16x32_bf16 v[124:127], v[128:131], v[198:201], v[124:127]
	v_mfma_f32_16x16x32_bf16 v[120:123], v[158:161], v[198:201], v[120:123]
	v_mfma_f32_16x16x32_bf16 v[108:111], v[128:131], v[206:209], v[108:111]
	v_mfma_f32_16x16x32_bf16 v[104:107], v[158:161], v[206:209], v[104:107]
	v_mfma_f32_16x16x32_bf16 v[92:95], v[128:131], v[214:217], v[92:95]
	v_mfma_f32_16x16x32_bf16 v[88:91], v[158:161], v[214:217], v[88:91]
	v_mfma_f32_16x16x32_bf16 v[76:79], v[128:131], v[222:225], v[76:79]
	v_mfma_f32_16x16x32_bf16 v[72:75], v[158:161], v[222:225], v[72:75]
	v_mfma_f32_16x16x32_bf16 v[124:127], v[132:135], v[202:205], v[124:127]
	v_mfma_f32_16x16x32_bf16 v[120:123], v[178:181], v[202:205], v[120:123]
	v_mfma_f32_16x16x32_bf16 v[108:111], v[132:135], v[210:213], v[108:111]
	v_mfma_f32_16x16x32_bf16 v[104:107], v[178:181], v[210:213], v[104:107]
	v_mfma_f32_16x16x32_bf16 v[92:95], v[132:135], v[218:221], v[92:95]
	v_mfma_f32_16x16x32_bf16 v[88:91], v[178:181], v[218:221], v[88:91]
	v_mfma_f32_16x16x32_bf16 v[76:79], v[132:135], v[230:233], v[76:79]
	v_mfma_f32_16x16x32_bf16 v[72:75], v[178:181], v[230:233], v[72:75]
	v_mfma_f32_16x16x32_bf16 v[116:119], v[182:185], v[198:201], v[116:119]
	v_mfma_f32_16x16x32_bf16 v[112:115], v[190:193], v[198:201], v[112:115]
	v_mfma_f32_16x16x32_bf16 v[100:103], v[182:185], v[206:209], v[100:103]
	v_mfma_f32_16x16x32_bf16 v[96:99], v[190:193], v[206:209], v[96:99]
	v_mfma_f32_16x16x32_bf16 v[84:87], v[182:185], v[214:217], v[84:87]
	v_mfma_f32_16x16x32_bf16 v[80:83], v[190:193], v[214:217], v[80:83]
	v_mfma_f32_16x16x32_bf16 v[68:71], v[182:185], v[222:225], v[68:71]
	v_mfma_f32_16x16x32_bf16 v[64:67], v[190:193], v[222:225], v[64:67]
	v_mfma_f32_16x16x32_bf16 v[116:119], v[186:189], v[202:205], v[116:119]
	v_mfma_f32_16x16x32_bf16 v[112:115], v[194:197], v[202:205], v[112:115]
	v_mfma_f32_16x16x32_bf16 v[100:103], v[186:189], v[210:213], v[100:103]
	v_mfma_f32_16x16x32_bf16 v[96:99], v[194:197], v[210:213], v[96:99]
	v_mfma_f32_16x16x32_bf16 v[84:87], v[186:189], v[218:221], v[84:87]
	v_mfma_f32_16x16x32_bf16 v[80:83], v[194:197], v[218:221], v[80:83]
	v_mfma_f32_16x16x32_bf16 v[68:71], v[186:189], v[230:233], v[68:71]
	v_mfma_f32_16x16x32_bf16 v[64:67], v[194:197], v[230:233], v[64:67]
	s_setprio 0
	s_barrier
	s_add_i32 s3, s3, s25
	s_add_u32 s34, s34, 0x80
	s_addc_u32 s35, s35, 0
	s_mov_b32 m0, s3
	ds_read_b128 v[198:201], v175 offset:49152
	ds_read_b128 v[202:205], v175 offset:50176
	ds_read_b128 v[206:209], v175 offset:51200
	ds_read_b128 v[210:213], v175 offset:52224
	ds_read_b128 v[214:217], v175 offset:53248
	ds_read_b128 v[218:221], v175 offset:54272
	ds_read_b128 v[222:225], v175 offset:55296
	ds_read_b128 v[230:233], v175 offset:56320
	global_load_lds_dwordx4 v138, s[34:35]
	s_add_i32 m0, s3, 0x2000
	s_add_i32 s3, s44, s25
	global_load_lds_dwordx4 v142, s[34:35]
	s_add_u32 s34, s34, 0x80000
	s_addc_u32 s35, s35, 0
	s_mov_b32 m0, s3
	s_nop 0
	global_load_lds_dwordx4 v138, s[34:35]
	s_add_i32 m0, s3, 0x2000
	s_nop 0
	global_load_lds_dwordx4 v142, s[34:35]
	s_add_u32 s90, s90, 0x80
	s_addc_u32 s91, s91, 0
	s_mov_b32 m0, s58
	s_nop 0
	global_load_lds_dwordx4 v136, s[90:91]
	s_mov_b32 m0, s59
	s_nop 0
	global_load_lds_dwordx4 v140, s[90:91]
	s_waitcnt vmcnt(8)
	s_waitcnt lgkmcnt(0)
	s_barrier
	s_setprio 1
	v_mfma_f32_16x16x32_bf16 v[60:63], v[128:131], v[198:201], v[60:63]
	v_mfma_f32_16x16x32_bf16 v[56:59], v[158:161], v[198:201], v[56:59]
	v_mfma_f32_16x16x32_bf16 v[44:47], v[128:131], v[206:209], v[44:47]
	v_mfma_f32_16x16x32_bf16 v[40:43], v[158:161], v[206:209], v[40:43]
	v_mfma_f32_16x16x32_bf16 v[28:31], v[128:131], v[214:217], v[28:31]
	v_mfma_f32_16x16x32_bf16 v[24:27], v[158:161], v[214:217], v[24:27]
	v_mfma_f32_16x16x32_bf16 v[12:15], v[128:131], v[222:225], v[12:15]
	v_mfma_f32_16x16x32_bf16 v[8:11], v[158:161], v[222:225], v[8:11]
	v_mfma_f32_16x16x32_bf16 v[60:63], v[132:135], v[202:205], v[60:63]
	v_mfma_f32_16x16x32_bf16 v[56:59], v[178:181], v[202:205], v[56:59]
	v_mfma_f32_16x16x32_bf16 v[44:47], v[132:135], v[210:213], v[44:47]
	v_mfma_f32_16x16x32_bf16 v[40:43], v[178:181], v[210:213], v[40:43]
	v_mfma_f32_16x16x32_bf16 v[28:31], v[132:135], v[218:221], v[28:31]
	v_mfma_f32_16x16x32_bf16 v[24:27], v[178:181], v[218:221], v[24:27]
	v_mfma_f32_16x16x32_bf16 v[12:15], v[132:135], v[230:233], v[12:15]
	v_mfma_f32_16x16x32_bf16 v[8:11], v[178:181], v[230:233], v[8:11]
	v_mfma_f32_16x16x32_bf16 v[52:55], v[182:185], v[198:201], v[52:55]
	v_mfma_f32_16x16x32_bf16 v[48:51], v[190:193], v[198:201], v[48:51]
	v_mfma_f32_16x16x32_bf16 v[36:39], v[182:185], v[206:209], v[36:39]
	v_mfma_f32_16x16x32_bf16 v[32:35], v[190:193], v[206:209], v[32:35]
	v_mfma_f32_16x16x32_bf16 v[20:23], v[182:185], v[214:217], v[20:23]
	v_mfma_f32_16x16x32_bf16 v[16:19], v[190:193], v[214:217], v[16:19]
	v_mfma_f32_16x16x32_bf16 v[4:7], v[182:185], v[222:225], v[4:7]
	v_mfma_f32_16x16x32_bf16 v[0:3], v[190:193], v[222:225], v[0:3]
	v_mfma_f32_16x16x32_bf16 v[52:55], v[186:189], v[202:205], v[52:55]
	v_mfma_f32_16x16x32_bf16 v[48:51], v[194:197], v[202:205], v[48:51]
	v_mfma_f32_16x16x32_bf16 v[36:39], v[186:189], v[210:213], v[36:39]
	v_mfma_f32_16x16x32_bf16 v[32:35], v[194:197], v[210:213], v[32:35]
	v_mfma_f32_16x16x32_bf16 v[20:23], v[186:189], v[218:221], v[20:23]
	v_mfma_f32_16x16x32_bf16 v[16:19], v[194:197], v[218:221], v[16:19]
	v_mfma_f32_16x16x32_bf16 v[4:7], v[186:189], v[230:233], v[4:7]
	v_mfma_f32_16x16x32_bf16 v[0:3], v[194:197], v[230:233], v[0:3]
	s_setprio 0
	s_add_i32 s37, s37, 2
	s_add_u32 s14, s14, 0x100
	s_addc_u32 s15, s15, 0
	s_add_u32 s24, s24, 0x100
	s_addc_u32 s36, s36, 0
	s_cmp_gt_u32 s37, 29
	s_barrier
	s_cbranch_scc0 .LBB0_65
	s_and_b64 vcc, exec, s[48:49]
	s_cbranch_vccz .LBB0_68
	s_barrier

.LBB0_539:
	ds_read_b128 v[144:147], v153
	ds_read_b128 v[156:159], v153 offset:1024
	ds_read_b128 v[160:163], v153 offset:2048
	ds_read_b128 v[164:167], v153 offset:3072
	ds_read_b128 v[168:171], v154
	ds_read_b128 v[172:175], v154 offset:1024
	ds_read_b128 v[176:179], v154 offset:2048
	ds_read_b128 v[180:183], v154 offset:3072
	s_add_u32 s3, s86, 0xfffc0080
	s_addc_u32 s37, s87, -1
	s_cmp_eq_u32 s36, 12
	s_cselect_b32 s91, s0, s37
	s_cselect_b32 s90, s1, s3
	s_cselect_b32 s89, s17, s35
	s_cselect_b32 s88, s27, s33
	s_add_i32 m0, s19, 0xc000
	ds_read_b128 v[184:187], v155
	ds_read_b128 v[188:191], v155 offset:1024
	ds_read_b128 v[192:195], v155 offset:2048
	ds_read_b128 v[196:199], v155 offset:3072
	ds_read_b128 v[200:203], v155 offset:4096
	ds_read_b128 v[204:207], v155 offset:5120
	ds_read_b128 v[208:211], v155 offset:6144
	ds_read_b128 v[212:215], v155 offset:7168
	global_load_lds_dwordx4 v136, s[86:87]
	s_add_i32 m0, s19, 0xe000
	s_nop 0
	global_load_lds_dwordx4 v138, s[86:87]
	s_waitcnt vmcnt(8)
	s_waitcnt lgkmcnt(0)
	s_barrier
	s_setprio 1
	v_mfma_f32_16x16x32_bf16 v[124:127], v[144:147], v[184:187], v[124:127]
	v_mfma_f32_16x16x32_bf16 v[120:123], v[160:163], v[184:187], v[120:123]
	v_mfma_f32_16x16x32_bf16 v[108:111], v[144:147], v[192:195], v[108:111]
	v_mfma_f32_16x16x32_bf16 v[104:107], v[160:163], v[192:195], v[104:107]
	v_mfma_f32_16x16x32_bf16 v[92:95], v[144:147], v[200:203], v[92:95]
	v_mfma_f32_16x16x32_bf16 v[88:91], v[160:163], v[200:203], v[88:91]
	v_mfma_f32_16x16x32_bf16 v[76:79], v[144:147], v[208:211], v[76:79]
	v_mfma_f32_16x16x32_bf16 v[72:75], v[160:163], v[208:211], v[72:75]
	v_mfma_f32_16x16x32_bf16 v[124:127], v[156:159], v[188:191], v[124:127]
	v_mfma_f32_16x16x32_bf16 v[120:123], v[164:167], v[188:191], v[120:123]
	v_mfma_f32_16x16x32_bf16 v[108:111], v[156:159], v[196:199], v[108:111]
	v_mfma_f32_16x16x32_bf16 v[104:107], v[164:167], v[196:199], v[104:107]
	v_mfma_f32_16x16x32_bf16 v[92:95], v[156:159], v[204:207], v[92:95]
	v_mfma_f32_16x16x32_bf16 v[88:91], v[164:167], v[204:207], v[88:91]
	v_mfma_f32_16x16x32_bf16 v[76:79], v[156:159], v[212:215], v[76:79]
	v_mfma_f32_16x16x32_bf16 v[72:75], v[164:167], v[212:215], v[72:75]
	v_mfma_f32_16x16x32_bf16 v[116:119], v[168:171], v[184:187], v[116:119]
	v_mfma_f32_16x16x32_bf16 v[112:115], v[176:179], v[184:187], v[112:115]
	v_mfma_f32_16x16x32_bf16 v[100:103], v[168:171], v[192:195], v[100:103]
	v_mfma_f32_16x16x32_bf16 v[96:99], v[176:179], v[192:195], v[96:99]
	v_mfma_f32_16x16x32_bf16 v[84:87], v[168:171], v[200:203], v[84:87]
	v_mfma_f32_16x16x32_bf16 v[80:83], v[176:179], v[200:203], v[80:83]
	v_mfma_f32_16x16x32_bf16 v[68:71], v[168:171], v[208:211], v[68:71]
	v_mfma_f32_16x16x32_bf16 v[64:67], v[176:179], v[208:211], v[64:67]
	v_mfma_f32_16x16x32_bf16 v[116:119], v[172:175], v[188:191], v[116:119]
	v_mfma_f32_16x16x32_bf16 v[112:115], v[180:183], v[188:191], v[112:115]
	v_mfma_f32_16x16x32_bf16 v[100:103], v[172:175], v[196:199], v[100:103]
	v_mfma_f32_16x16x32_bf16 v[96:99], v[180:183], v[196:199], v[96:99]
	v_mfma_f32_16x16x32_bf16 v[84:87], v[172:175], v[204:207], v[84:87]
	v_mfma_f32_16x16x32_bf16 v[80:83], v[180:183], v[204:207], v[80:83]
	v_mfma_f32_16x16x32_bf16 v[68:71], v[172:175], v[212:215], v[68:71]
	v_mfma_f32_16x16x32_bf16 v[64:67], v[180:183], v[212:215], v[64:67]
	s_setprio 0
	s_barrier
	s_add_i32 s3, s57, s18
	s_mov_b32 m0, s3
	ds_read_b128 v[184:187], v155 offset:16384
	ds_read_b128 v[188:191], v155 offset:17408
	ds_read_b128 v[192:195], v155 offset:18432
	ds_read_b128 v[196:199], v155 offset:19456
	ds_read_b128 v[200:203], v155 offset:20480
	ds_read_b128 v[204:207], v155 offset:21504
	ds_read_b128 v[208:211], v155 offset:22528
	ds_read_b128 v[212:215], v155 offset:23552
	global_load_lds_dwordx4 v130, s[88:89]
	s_add_i32 m0, s3, 0x2000
	s_add_u32 s42, s88, 0x40000
	s_addc_u32 s43, s89, 0
	s_add_i32 s3, s58, s18
	global_load_lds_dwordx4 v134, s[88:89]
	s_mov_b32 m0, s3
	s_nop 0
	global_load_lds_dwordx4 v130, s[42:43]
	s_add_i32 m0, s3, 0x2000
	s_nop 0
	global_load_lds_dwordx4 v134, s[42:43]
	s_mov_b32 m0, s19
	s_nop 0
	global_load_lds_dwordx4 v128, s[90:91]
	s_mov_b32 m0, s25
	s_nop 0
	global_load_lds_dwordx4 v132, s[90:91]
	s_waitcnt vmcnt(8)
	s_waitcnt lgkmcnt(0)
	s_barrier
	s_setprio 1
	v_mfma_f32_16x16x32_bf16 v[60:63], v[144:147], v[184:187], v[60:63]
	v_mfma_f32_16x16x32_bf16 v[56:59], v[160:163], v[184:187], v[56:59]
	v_mfma_f32_16x16x32_bf16 v[44:47], v[144:147], v[192:195], v[44:47]
	v_mfma_f32_16x16x32_bf16 v[40:43], v[160:163], v[192:195], v[40:43]
	v_mfma_f32_16x16x32_bf16 v[28:31], v[144:147], v[200:203], v[28:31]
	v_mfma_f32_16x16x32_bf16 v[24:27], v[160:163], v[200:203], v[24:27]
	v_mfma_f32_16x16x32_bf16 v[12:15], v[144:147], v[208:211], v[12:15]
	v_mfma_f32_16x16x32_bf16 v[8:11], v[160:163], v[208:211], v[8:11]
	v_mfma_f32_16x16x32_bf16 v[60:63], v[156:159], v[188:191], v[60:63]
	v_mfma_f32_16x16x32_bf16 v[56:59], v[164:167], v[188:191], v[56:59]
	v_mfma_f32_16x16x32_bf16 v[44:47], v[156:159], v[196:199], v[44:47]
	v_mfma_f32_16x16x32_bf16 v[40:43], v[164:167], v[196:199], v[40:43]
	v_mfma_f32_16x16x32_bf16 v[28:31], v[156:159], v[204:207], v[28:31]
	v_mfma_f32_16x16x32_bf16 v[24:27], v[164:167], v[204:207], v[24:27]
	v_mfma_f32_16x16x32_bf16 v[12:15], v[156:159], v[212:215], v[12:15]
	v_mfma_f32_16x16x32_bf16 v[8:11], v[164:167], v[212:215], v[8:11]
	v_mfma_f32_16x16x32_bf16 v[52:55], v[168:171], v[184:187], v[52:55]
	v_mfma_f32_16x16x32_bf16 v[48:51], v[176:179], v[184:187], v[48:51]
	v_mfma_f32_16x16x32_bf16 v[36:39], v[168:171], v[192:195], v[36:39]
	v_mfma_f32_16x16x32_bf16 v[32:35], v[176:179], v[192:195], v[32:35]
	v_mfma_f32_16x16x32_bf16 v[20:23], v[168:171], v[200:203], v[20:23]
	v_mfma_f32_16x16x32_bf16 v[16:19], v[176:179], v[200:203], v[16:19]
	v_mfma_f32_16x16x32_bf16 v[4:7], v[168:171], v[208:211], v[4:7]
	v_mfma_f32_16x16x32_bf16 v[0:3], v[176:179], v[208:211], v[0:3]
	v_mfma_f32_16x16x32_bf16 v[52:55], v[172:175], v[188:191], v[52:55]
	v_mfma_f32_16x16x32_bf16 v[48:51], v[180:183], v[188:191], v[48:51]
	v_mfma_f32_16x16x32_bf16 v[36:39], v[172:175], v[196:199], v[36:39]
	v_mfma_f32_16x16x32_bf16 v[32:35], v[180:183], v[196:199], v[32:35]
	v_mfma_f32_16x16x32_bf16 v[20:23], v[172:175], v[204:207], v[20:23]
	v_mfma_f32_16x16x32_bf16 v[16:19], v[180:183], v[204:207], v[16:19]
	v_mfma_f32_16x16x32_bf16 v[4:7], v[172:175], v[212:215], v[4:7]
	v_mfma_f32_16x16x32_bf16 v[0:3], v[180:183], v[212:215], v[0:3]
	s_setprio 0
	s_barrier
	s_add_i32 s3, 0, 0x18000
	s_add_i32 s37, 0, 0x1c000
	v_add_u32_e32 v164, s3, v151
	v_add_u32_e32 v180, s37, v151
	ds_read_b128 v[144:147], v164
	ds_read_b128 v[156:159], v164 offset:1024
	ds_read_b128 v[160:163], v164 offset:2048
	ds_read_b128 v[164:167], v164 offset:3072
	ds_read_b128 v[168:171], v180
	ds_read_b128 v[172:175], v180 offset:1024
	ds_read_b128 v[176:179], v180 offset:2048
	ds_read_b128 v[180:183], v180 offset:3072
	s_add_u32 s42, s90, 0x40000
	s_addc_u32 s43, s91, 0
	s_mov_b32 m0, s30
	ds_read_b128 v[184:187], v155 offset:32768
	ds_read_b128 v[188:191], v155 offset:33792
	ds_read_b128 v[192:195], v155 offset:34816
	ds_read_b128 v[196:199], v155 offset:35840
	ds_read_b128 v[200:203], v155 offset:36864
	ds_read_b128 v[204:207], v155 offset:37888
	ds_read_b128 v[208:211], v155 offset:38912
	ds_read_b128 v[212:215], v155 offset:39936
	global_load_lds_dwordx4 v128, s[42:43]
	v_lshl_add_u64 v[222:223], s[42:43], 0, v[132:133]
	s_mov_b32 m0, s31
	s_nop 0
	global_load_lds_dwordx4 v[222:223], off
	s_waitcnt vmcnt(8)
	s_waitcnt lgkmcnt(0)
	s_barrier
	s_setprio 1
	v_mfma_f32_16x16x32_bf16 v[124:127], v[144:147], v[184:187], v[124:127]
	v_mfma_f32_16x16x32_bf16 v[120:123], v[160:163], v[184:187], v[120:123]
	v_mfma_f32_16x16x32_bf16 v[108:111], v[144:147], v[192:195], v[108:111]
	v_mfma_f32_16x16x32_bf16 v[104:107], v[160:163], v[192:195], v[104:107]
	v_mfma_f32_16x16x32_bf16 v[92:95], v[144:147], v[200:203], v[92:95]
	v_mfma_f32_16x16x32_bf16 v[88:91], v[160:163], v[200:203], v[88:91]
	v_mfma_f32_16x16x32_bf16 v[76:79], v[144:147], v[208:211], v[76:79]
	v_mfma_f32_16x16x32_bf16 v[72:75], v[160:163], v[208:211], v[72:75]
	v_mfma_f32_16x16x32_bf16 v[124:127], v[156:159], v[188:191], v[124:127]
	v_mfma_f32_16x16x32_bf16 v[120:123], v[164:167], v[188:191], v[120:123]
	v_mfma_f32_16x16x32_bf16 v[108:111], v[156:159], v[196:199], v[108:111]
	v_mfma_f32_16x16x32_bf16 v[104:107], v[164:167], v[196:199], v[104:107]
	v_mfma_f32_16x16x32_bf16 v[92:95], v[156:159], v[204:207], v[92:95]
	v_mfma_f32_16x16x32_bf16 v[88:91], v[164:167], v[204:207], v[88:91]
	v_mfma_f32_16x16x32_bf16 v[76:79], v[156:159], v[212:215], v[76:79]
	v_mfma_f32_16x16x32_bf16 v[72:75], v[164:167], v[212:215], v[72:75]
	v_mfma_f32_16x16x32_bf16 v[116:119], v[168:171], v[184:187], v[116:119]
	v_mfma_f32_16x16x32_bf16 v[112:115], v[176:179], v[184:187], v[112:115]
	v_mfma_f32_16x16x32_bf16 v[100:103], v[168:171], v[192:195], v[100:103]
	v_mfma_f32_16x16x32_bf16 v[96:99], v[176:179], v[192:195], v[96:99]
	v_mfma_f32_16x16x32_bf16 v[84:87], v[168:171], v[200:203], v[84:87]
	v_mfma_f32_16x16x32_bf16 v[80:83], v[176:179], v[200:203], v[80:83]
	v_mfma_f32_16x16x32_bf16 v[68:71], v[168:171], v[208:211], v[68:71]
	v_mfma_f32_16x16x32_bf16 v[64:67], v[176:179], v[208:211], v[64:67]
	v_mfma_f32_16x16x32_bf16 v[116:119], v[172:175], v[188:191], v[116:119]
	v_mfma_f32_16x16x32_bf16 v[112:115], v[180:183], v[188:191], v[112:115]
	v_mfma_f32_16x16x32_bf16 v[100:103], v[172:175], v[196:199], v[100:103]
	v_mfma_f32_16x16x32_bf16 v[96:99], v[180:183], v[196:199], v[96:99]
	v_mfma_f32_16x16x32_bf16 v[84:87], v[172:175], v[204:207], v[84:87]
	v_mfma_f32_16x16x32_bf16 v[80:83], v[180:183], v[204:207], v[80:83]
	v_mfma_f32_16x16x32_bf16 v[68:71], v[172:175], v[212:215], v[68:71]
	v_mfma_f32_16x16x32_bf16 v[64:67], v[180:183], v[212:215], v[64:67]
	s_setprio 0
	s_barrier
	s_add_i32 s3, s3, s18
	s_add_u32 s42, s88, 0x80
	s_addc_u32 s43, s89, 0
	s_mov_b32 m0, s3
	ds_read_b128 v[184:187], v155 offset:49152
	ds_read_b128 v[188:191], v155 offset:50176
	ds_read_b128 v[192:195], v155 offset:51200
	ds_read_b128 v[196:199], v155 offset:52224
	ds_read_b128 v[200:203], v155 offset:53248
	ds_read_b128 v[204:207], v155 offset:54272
	ds_read_b128 v[208:211], v155 offset:55296
	ds_read_b128 v[212:215], v155 offset:56320
	global_load_lds_dwordx4 v130, s[42:43]
	s_add_i32 m0, s3, 0x2000
	s_add_i32 s3, s37, s18
	global_load_lds_dwordx4 v134, s[42:43]
	s_add_u32 s42, s42, 0x40000
	s_addc_u32 s43, s43, 0
	s_mov_b32 m0, s3
	s_nop 0
	global_load_lds_dwordx4 v130, s[42:43]
	s_add_i32 m0, s3, 0x2000
	s_nop 0
	global_load_lds_dwordx4 v134, s[42:43]
	s_add_u32 s90, s90, 0x80
	s_addc_u32 s91, s91, 0
	s_mov_b32 m0, s49
	s_nop 0
	global_load_lds_dwordx4 v128, s[90:91]
	s_mov_b32 m0, s56
	s_nop 0
	global_load_lds_dwordx4 v132, s[90:91]
	s_waitcnt vmcnt(8)
	s_waitcnt lgkmcnt(0)
	s_barrier
	s_setprio 1
	v_mfma_f32_16x16x32_bf16 v[60:63], v[144:147], v[184:187], v[60:63]
	v_mfma_f32_16x16x32_bf16 v[56:59], v[160:163], v[184:187], v[56:59]
	v_mfma_f32_16x16x32_bf16 v[44:47], v[144:147], v[192:195], v[44:47]
	v_mfma_f32_16x16x32_bf16 v[40:43], v[160:163], v[192:195], v[40:43]
	v_mfma_f32_16x16x32_bf16 v[28:31], v[144:147], v[200:203], v[28:31]
	v_mfma_f32_16x16x32_bf16 v[24:27], v[160:163], v[200:203], v[24:27]
	v_mfma_f32_16x16x32_bf16 v[12:15], v[144:147], v[208:211], v[12:15]
	v_mfma_f32_16x16x32_bf16 v[8:11], v[160:163], v[208:211], v[8:11]
	v_mfma_f32_16x16x32_bf16 v[60:63], v[156:159], v[188:191], v[60:63]
	v_mfma_f32_16x16x32_bf16 v[56:59], v[164:167], v[188:191], v[56:59]
	v_mfma_f32_16x16x32_bf16 v[44:47], v[156:159], v[196:199], v[44:47]
	v_mfma_f32_16x16x32_bf16 v[40:43], v[164:167], v[196:199], v[40:43]
	v_mfma_f32_16x16x32_bf16 v[28:31], v[156:159], v[204:207], v[28:31]
	v_mfma_f32_16x16x32_bf16 v[24:27], v[164:167], v[204:207], v[24:27]
	v_mfma_f32_16x16x32_bf16 v[12:15], v[156:159], v[212:215], v[12:15]
	v_mfma_f32_16x16x32_bf16 v[8:11], v[164:167], v[212:215], v[8:11]
	v_mfma_f32_16x16x32_bf16 v[52:55], v[168:171], v[184:187], v[52:55]
	v_mfma_f32_16x16x32_bf16 v[48:51], v[176:179], v[184:187], v[48:51]
	v_mfma_f32_16x16x32_bf16 v[36:39], v[168:171], v[192:195], v[36:39]
	v_mfma_f32_16x16x32_bf16 v[32:35], v[176:179], v[192:195], v[32:35]
	v_mfma_f32_16x16x32_bf16 v[20:23], v[168:171], v[200:203], v[20:23]
	v_mfma_f32_16x16x32_bf16 v[16:19], v[176:179], v[200:203], v[16:19]
	v_mfma_f32_16x16x32_bf16 v[4:7], v[168:171], v[208:211], v[4:7]
	v_mfma_f32_16x16x32_bf16 v[0:3], v[176:179], v[208:211], v[0:3]
	v_mfma_f32_16x16x32_bf16 v[52:55], v[172:175], v[188:191], v[52:55]
	v_mfma_f32_16x16x32_bf16 v[48:51], v[180:183], v[188:191], v[48:51]
	v_mfma_f32_16x16x32_bf16 v[36:39], v[172:175], v[196:199], v[36:39]
	v_mfma_f32_16x16x32_bf16 v[32:35], v[180:183], v[196:199], v[32:35]
	v_mfma_f32_16x16x32_bf16 v[20:23], v[172:175], v[204:207], v[20:23]
	v_mfma_f32_16x16x32_bf16 v[16:19], v[180:183], v[204:207], v[16:19]
	v_mfma_f32_16x16x32_bf16 v[4:7], v[172:175], v[212:215], v[4:7]
	v_mfma_f32_16x16x32_bf16 v[0:3], v[180:183], v[212:215], v[0:3]
	s_setprio 0
	s_add_i32 s36, s36, 2
	s_add_u32 s86, s86, 0x100
	s_addc_u32 s87, s87, 0
	s_add_u32 s33, s33, 0x100
	s_addc_u32 s35, s35, 0
	s_cmp_gt_u32 s36, 13
	s_barrier
	s_cbranch_scc0 .LBB0_539
	s_and_b64 vcc, exec, s[12:13]
	s_cbranch_vccz .LBB0_542
	s_barrier

.LBB0_563:
	ds_read_b128 v[144:147], v157
	ds_read_b128 v[148:151], v157 offset:1024
	ds_read_b128 v[160:163], v157 offset:2048
	ds_read_b128 v[164:167], v157 offset:3072
	ds_read_b128 v[168:171], v158
	ds_read_b128 v[172:175], v158 offset:1024
	ds_read_b128 v[176:179], v158 offset:2048
	ds_read_b128 v[180:183], v158 offset:3072
	s_add_u32 s3, s34, 0xfffe0080
	s_addc_u32 s42, s35, -1
	s_cmp_eq_u32 s37, 4
	s_cselect_b32 s91, s0, s42
	s_cselect_b32 s90, s1, s3
	s_cselect_b32 s89, s24, s36
	s_cselect_b32 s88, s27, s33
	s_add_i32 m0, s19, 0xc000
	ds_read_b128 v[184:187], v159
	ds_read_b128 v[188:191], v159 offset:1024
	ds_read_b128 v[192:195], v159 offset:2048
	ds_read_b128 v[196:199], v159 offset:3072
	ds_read_b128 v[200:203], v159 offset:4096
	ds_read_b128 v[204:207], v159 offset:5120
	ds_read_b128 v[208:211], v159 offset:6144
	ds_read_b128 v[212:215], v159 offset:7168
	global_load_lds_dwordx4 v136, s[34:35]
	s_add_i32 m0, s19, 0xe000
	s_nop 0
	global_load_lds_dwordx4 v138, s[34:35]
	s_waitcnt vmcnt(8)
	s_waitcnt lgkmcnt(0)
	s_barrier
	s_setprio 1
	v_mfma_f32_16x16x32_bf16 v[124:127], v[144:147], v[184:187], v[124:127]
	v_mfma_f32_16x16x32_bf16 v[120:123], v[160:163], v[184:187], v[120:123]
	v_mfma_f32_16x16x32_bf16 v[108:111], v[144:147], v[192:195], v[108:111]
	v_mfma_f32_16x16x32_bf16 v[104:107], v[160:163], v[192:195], v[104:107]
	v_mfma_f32_16x16x32_bf16 v[92:95], v[144:147], v[200:203], v[92:95]
	v_mfma_f32_16x16x32_bf16 v[88:91], v[160:163], v[200:203], v[88:91]
	v_mfma_f32_16x16x32_bf16 v[76:79], v[144:147], v[208:211], v[76:79]
	v_mfma_f32_16x16x32_bf16 v[72:75], v[160:163], v[208:211], v[72:75]
	v_mfma_f32_16x16x32_bf16 v[124:127], v[148:151], v[188:191], v[124:127]
	v_mfma_f32_16x16x32_bf16 v[120:123], v[164:167], v[188:191], v[120:123]
	v_mfma_f32_16x16x32_bf16 v[108:111], v[148:151], v[196:199], v[108:111]
	v_mfma_f32_16x16x32_bf16 v[104:107], v[164:167], v[196:199], v[104:107]
	v_mfma_f32_16x16x32_bf16 v[92:95], v[148:151], v[204:207], v[92:95]
	v_mfma_f32_16x16x32_bf16 v[88:91], v[164:167], v[204:207], v[88:91]
	v_mfma_f32_16x16x32_bf16 v[76:79], v[148:151], v[212:215], v[76:79]
	v_mfma_f32_16x16x32_bf16 v[72:75], v[164:167], v[212:215], v[72:75]
	v_mfma_f32_16x16x32_bf16 v[116:119], v[168:171], v[184:187], v[116:119]
	v_mfma_f32_16x16x32_bf16 v[112:115], v[176:179], v[184:187], v[112:115]
	v_mfma_f32_16x16x32_bf16 v[100:103], v[168:171], v[192:195], v[100:103]
	v_mfma_f32_16x16x32_bf16 v[96:99], v[176:179], v[192:195], v[96:99]
	v_mfma_f32_16x16x32_bf16 v[84:87], v[168:171], v[200:203], v[84:87]
	v_mfma_f32_16x16x32_bf16 v[80:83], v[176:179], v[200:203], v[80:83]
	v_mfma_f32_16x16x32_bf16 v[68:71], v[168:171], v[208:211], v[68:71]
	v_mfma_f32_16x16x32_bf16 v[64:67], v[176:179], v[208:211], v[64:67]
	v_mfma_f32_16x16x32_bf16 v[116:119], v[172:175], v[188:191], v[116:119]
	v_mfma_f32_16x16x32_bf16 v[112:115], v[180:183], v[188:191], v[112:115]
	v_mfma_f32_16x16x32_bf16 v[100:103], v[172:175], v[196:199], v[100:103]
	v_mfma_f32_16x16x32_bf16 v[96:99], v[180:183], v[196:199], v[96:99]
	v_mfma_f32_16x16x32_bf16 v[84:87], v[172:175], v[204:207], v[84:87]
	v_mfma_f32_16x16x32_bf16 v[80:83], v[180:183], v[204:207], v[80:83]
	v_mfma_f32_16x16x32_bf16 v[68:71], v[172:175], v[212:215], v[68:71]
	v_mfma_f32_16x16x32_bf16 v[64:67], v[180:183], v[212:215], v[64:67]
	s_setprio 0
	s_barrier
	s_add_i32 s3, s78, s18
	s_mov_b32 m0, s3
	ds_read_b128 v[184:187], v159 offset:16384
	ds_read_b128 v[188:191], v159 offset:17408
	ds_read_b128 v[192:195], v159 offset:18432
	ds_read_b128 v[196:199], v159 offset:19456
	ds_read_b128 v[200:203], v159 offset:20480
	ds_read_b128 v[204:207], v159 offset:21504
	ds_read_b128 v[208:211], v159 offset:22528
	ds_read_b128 v[212:215], v159 offset:23552
	global_load_lds_dwordx4 v130, s[88:89]
	s_add_i32 m0, s3, 0x2000
	s_add_u32 s42, s88, 0x20000
	s_addc_u32 s43, s89, 0
	s_add_i32 s3, s79, s18
	global_load_lds_dwordx4 v134, s[88:89]
	s_mov_b32 m0, s3
	s_nop 0
	global_load_lds_dwordx4 v130, s[42:43]
	s_add_i32 m0, s3, 0x2000
	s_nop 0
	global_load_lds_dwordx4 v134, s[42:43]
	s_mov_b32 m0, s19
	s_nop 0
	global_load_lds_dwordx4 v128, s[90:91]
	s_mov_b32 m0, s25
	s_nop 0
	global_load_lds_dwordx4 v132, s[90:91]
	s_waitcnt vmcnt(8)
	s_waitcnt lgkmcnt(0)
	s_barrier
	s_setprio 1
	v_mfma_f32_16x16x32_bf16 v[60:63], v[144:147], v[184:187], v[60:63]
	v_mfma_f32_16x16x32_bf16 v[56:59], v[160:163], v[184:187], v[56:59]
	v_mfma_f32_16x16x32_bf16 v[44:47], v[144:147], v[192:195], v[44:47]
	v_mfma_f32_16x16x32_bf16 v[40:43], v[160:163], v[192:195], v[40:43]
	v_mfma_f32_16x16x32_bf16 v[28:31], v[144:147], v[200:203], v[28:31]
	v_mfma_f32_16x16x32_bf16 v[24:27], v[160:163], v[200:203], v[24:27]
	v_mfma_f32_16x16x32_bf16 v[12:15], v[144:147], v[208:211], v[12:15]
	v_mfma_f32_16x16x32_bf16 v[8:11], v[160:163], v[208:211], v[8:11]
	v_mfma_f32_16x16x32_bf16 v[60:63], v[148:151], v[188:191], v[60:63]
	v_mfma_f32_16x16x32_bf16 v[56:59], v[164:167], v[188:191], v[56:59]
	v_mfma_f32_16x16x32_bf16 v[44:47], v[148:151], v[196:199], v[44:47]
	v_mfma_f32_16x16x32_bf16 v[40:43], v[164:167], v[196:199], v[40:43]
	v_mfma_f32_16x16x32_bf16 v[28:31], v[148:151], v[204:207], v[28:31]
	v_mfma_f32_16x16x32_bf16 v[24:27], v[164:167], v[204:207], v[24:27]
	v_mfma_f32_16x16x32_bf16 v[12:15], v[148:151], v[212:215], v[12:15]
	v_mfma_f32_16x16x32_bf16 v[8:11], v[164:167], v[212:215], v[8:11]
	v_mfma_f32_16x16x32_bf16 v[52:55], v[168:171], v[184:187], v[52:55]
	v_mfma_f32_16x16x32_bf16 v[48:51], v[176:179], v[184:187], v[48:51]
	v_mfma_f32_16x16x32_bf16 v[36:39], v[168:171], v[192:195], v[36:39]
	v_mfma_f32_16x16x32_bf16 v[32:35], v[176:179], v[192:195], v[32:35]
	v_mfma_f32_16x16x32_bf16 v[20:23], v[168:171], v[200:203], v[20:23]
	v_mfma_f32_16x16x32_bf16 v[16:19], v[176:179], v[200:203], v[16:19]
	v_mfma_f32_16x16x32_bf16 v[4:7], v[168:171], v[208:211], v[4:7]
	v_mfma_f32_16x16x32_bf16 v[0:3], v[176:179], v[208:211], v[0:3]
	v_mfma_f32_16x16x32_bf16 v[52:55], v[172:175], v[188:191], v[52:55]
	v_mfma_f32_16x16x32_bf16 v[48:51], v[180:183], v[188:191], v[48:51]
	v_mfma_f32_16x16x32_bf16 v[36:39], v[172:175], v[196:199], v[36:39]
	v_mfma_f32_16x16x32_bf16 v[32:35], v[180:183], v[196:199], v[32:35]
	v_mfma_f32_16x16x32_bf16 v[20:23], v[172:175], v[204:207], v[20:23]
	v_mfma_f32_16x16x32_bf16 v[16:19], v[180:183], v[204:207], v[16:19]
	v_mfma_f32_16x16x32_bf16 v[4:7], v[172:175], v[212:215], v[4:7]
	v_mfma_f32_16x16x32_bf16 v[0:3], v[180:183], v[212:215], v[0:3]
	s_setprio 0
	s_barrier
	s_add_i32 s3, 0, 0x18000
	s_add_i32 s44, 0, 0x1c000
	v_add_u32_e32 v164, s3, v155
	v_add_u32_e32 v180, s44, v155
	ds_read_b128 v[144:147], v164
	ds_read_b128 v[148:151], v164 offset:1024
	ds_read_b128 v[160:163], v164 offset:2048
	ds_read_b128 v[164:167], v164 offset:3072
	ds_read_b128 v[168:171], v180
	ds_read_b128 v[172:175], v180 offset:1024
	ds_read_b128 v[176:179], v180 offset:2048
	ds_read_b128 v[180:183], v180 offset:3072
	s_add_u32 s42, s90, 0x20000
	s_addc_u32 s43, s91, 0
	s_mov_b32 m0, s30
	ds_read_b128 v[184:187], v159 offset:32768
	ds_read_b128 v[188:191], v159 offset:33792
	ds_read_b128 v[192:195], v159 offset:34816
	ds_read_b128 v[196:199], v159 offset:35840
	ds_read_b128 v[200:203], v159 offset:36864
	ds_read_b128 v[204:207], v159 offset:37888
	ds_read_b128 v[208:211], v159 offset:38912
	ds_read_b128 v[212:215], v159 offset:39936
	global_load_lds_dwordx4 v128, s[42:43]
	v_lshl_add_u64 v[222:223], s[42:43], 0, v[132:133]
	s_mov_b32 m0, s31
	s_nop 0
	global_load_lds_dwordx4 v[222:223], off
	s_waitcnt vmcnt(8)
	s_waitcnt lgkmcnt(0)
	s_barrier
	s_setprio 1
	v_mfma_f32_16x16x32_bf16 v[124:127], v[144:147], v[184:187], v[124:127]
	v_mfma_f32_16x16x32_bf16 v[120:123], v[160:163], v[184:187], v[120:123]
	v_mfma_f32_16x16x32_bf16 v[108:111], v[144:147], v[192:195], v[108:111]
	v_mfma_f32_16x16x32_bf16 v[104:107], v[160:163], v[192:195], v[104:107]
	v_mfma_f32_16x16x32_bf16 v[92:95], v[144:147], v[200:203], v[92:95]
	v_mfma_f32_16x16x32_bf16 v[88:91], v[160:163], v[200:203], v[88:91]
	v_mfma_f32_16x16x32_bf16 v[76:79], v[144:147], v[208:211], v[76:79]
	v_mfma_f32_16x16x32_bf16 v[72:75], v[160:163], v[208:211], v[72:75]
	v_mfma_f32_16x16x32_bf16 v[124:127], v[148:151], v[188:191], v[124:127]
	v_mfma_f32_16x16x32_bf16 v[120:123], v[164:167], v[188:191], v[120:123]
	v_mfma_f32_16x16x32_bf16 v[108:111], v[148:151], v[196:199], v[108:111]
	v_mfma_f32_16x16x32_bf16 v[104:107], v[164:167], v[196:199], v[104:107]
	v_mfma_f32_16x16x32_bf16 v[92:95], v[148:151], v[204:207], v[92:95]
	v_mfma_f32_16x16x32_bf16 v[88:91], v[164:167], v[204:207], v[88:91]
	v_mfma_f32_16x16x32_bf16 v[76:79], v[148:151], v[212:215], v[76:79]
	v_mfma_f32_16x16x32_bf16 v[72:75], v[164:167], v[212:215], v[72:75]
	v_mfma_f32_16x16x32_bf16 v[116:119], v[168:171], v[184:187], v[116:119]
	v_mfma_f32_16x16x32_bf16 v[112:115], v[176:179], v[184:187], v[112:115]
	v_mfma_f32_16x16x32_bf16 v[100:103], v[168:171], v[192:195], v[100:103]
	v_mfma_f32_16x16x32_bf16 v[96:99], v[176:179], v[192:195], v[96:99]
	v_mfma_f32_16x16x32_bf16 v[84:87], v[168:171], v[200:203], v[84:87]
	v_mfma_f32_16x16x32_bf16 v[80:83], v[176:179], v[200:203], v[80:83]
	v_mfma_f32_16x16x32_bf16 v[68:71], v[168:171], v[208:211], v[68:71]
	v_mfma_f32_16x16x32_bf16 v[64:67], v[176:179], v[208:211], v[64:67]
	v_mfma_f32_16x16x32_bf16 v[116:119], v[172:175], v[188:191], v[116:119]
	v_mfma_f32_16x16x32_bf16 v[112:115], v[180:183], v[188:191], v[112:115]
	v_mfma_f32_16x16x32_bf16 v[100:103], v[172:175], v[196:199], v[100:103]
	v_mfma_f32_16x16x32_bf16 v[96:99], v[180:183], v[196:199], v[96:99]
	v_mfma_f32_16x16x32_bf16 v[84:87], v[172:175], v[204:207], v[84:87]
	v_mfma_f32_16x16x32_bf16 v[80:83], v[180:183], v[204:207], v[80:83]
	v_mfma_f32_16x16x32_bf16 v[68:71], v[172:175], v[212:215], v[68:71]
	v_mfma_f32_16x16x32_bf16 v[64:67], v[180:183], v[212:215], v[64:67]
	s_setprio 0
	s_barrier
	s_add_i32 s3, s3, s18
	s_add_u32 s42, s88, 0x80
	s_addc_u32 s43, s89, 0
	s_mov_b32 m0, s3
	ds_read_b128 v[184:187], v159 offset:49152
	ds_read_b128 v[188:191], v159 offset:50176
	ds_read_b128 v[192:195], v159 offset:51200
	ds_read_b128 v[196:199], v159 offset:52224
	ds_read_b128 v[200:203], v159 offset:53248
	ds_read_b128 v[204:207], v159 offset:54272
	ds_read_b128 v[208:211], v159 offset:55296
	ds_read_b128 v[212:215], v159 offset:56320
	global_load_lds_dwordx4 v130, s[42:43]
	s_add_i32 m0, s3, 0x2000
	s_add_i32 s3, s44, s18
	global_load_lds_dwordx4 v134, s[42:43]
	s_add_u32 s42, s42, 0x20000
	s_addc_u32 s43, s43, 0
	s_mov_b32 m0, s3
	s_nop 0
	global_load_lds_dwordx4 v130, s[42:43]
	s_add_i32 m0, s3, 0x2000
	s_nop 0
	global_load_lds_dwordx4 v134, s[42:43]
	s_add_u32 s90, s90, 0x80
	s_addc_u32 s91, s91, 0
	s_mov_b32 m0, s58
	s_nop 0
	global_load_lds_dwordx4 v128, s[90:91]
	s_mov_b32 m0, s59
	s_nop 0
	global_load_lds_dwordx4 v132, s[90:91]
	s_waitcnt vmcnt(8)
	s_waitcnt lgkmcnt(0)
	s_barrier
	s_setprio 1
	v_mfma_f32_16x16x32_bf16 v[60:63], v[144:147], v[184:187], v[60:63]
	v_mfma_f32_16x16x32_bf16 v[56:59], v[160:163], v[184:187], v[56:59]
	v_mfma_f32_16x16x32_bf16 v[44:47], v[144:147], v[192:195], v[44:47]
	v_mfma_f32_16x16x32_bf16 v[40:43], v[160:163], v[192:195], v[40:43]
	v_mfma_f32_16x16x32_bf16 v[28:31], v[144:147], v[200:203], v[28:31]
	v_mfma_f32_16x16x32_bf16 v[24:27], v[160:163], v[200:203], v[24:27]
	v_mfma_f32_16x16x32_bf16 v[12:15], v[144:147], v[208:211], v[12:15]
	v_mfma_f32_16x16x32_bf16 v[8:11], v[160:163], v[208:211], v[8:11]
	v_mfma_f32_16x16x32_bf16 v[60:63], v[148:151], v[188:191], v[60:63]
	v_mfma_f32_16x16x32_bf16 v[56:59], v[164:167], v[188:191], v[56:59]
	v_mfma_f32_16x16x32_bf16 v[44:47], v[148:151], v[196:199], v[44:47]
	v_mfma_f32_16x16x32_bf16 v[40:43], v[164:167], v[196:199], v[40:43]
	v_mfma_f32_16x16x32_bf16 v[28:31], v[148:151], v[204:207], v[28:31]
	v_mfma_f32_16x16x32_bf16 v[24:27], v[164:167], v[204:207], v[24:27]
	v_mfma_f32_16x16x32_bf16 v[12:15], v[148:151], v[212:215], v[12:15]
	v_mfma_f32_16x16x32_bf16 v[8:11], v[164:167], v[212:215], v[8:11]
	v_mfma_f32_16x16x32_bf16 v[52:55], v[168:171], v[184:187], v[52:55]
	v_mfma_f32_16x16x32_bf16 v[48:51], v[176:179], v[184:187], v[48:51]
	v_mfma_f32_16x16x32_bf16 v[36:39], v[168:171], v[192:195], v[36:39]
	v_mfma_f32_16x16x32_bf16 v[32:35], v[176:179], v[192:195], v[32:35]
	v_mfma_f32_16x16x32_bf16 v[20:23], v[168:171], v[200:203], v[20:23]
	v_mfma_f32_16x16x32_bf16 v[16:19], v[176:179], v[200:203], v[16:19]
	v_mfma_f32_16x16x32_bf16 v[4:7], v[168:171], v[208:211], v[4:7]
	v_mfma_f32_16x16x32_bf16 v[0:3], v[176:179], v[208:211], v[0:3]
	v_mfma_f32_16x16x32_bf16 v[52:55], v[172:175], v[188:191], v[52:55]
	v_mfma_f32_16x16x32_bf16 v[48:51], v[180:183], v[188:191], v[48:51]
	v_mfma_f32_16x16x32_bf16 v[36:39], v[172:175], v[196:199], v[36:39]
	v_mfma_f32_16x16x32_bf16 v[32:35], v[180:183], v[196:199], v[32:35]
	v_mfma_f32_16x16x32_bf16 v[20:23], v[172:175], v[204:207], v[20:23]
	v_mfma_f32_16x16x32_bf16 v[16:19], v[180:183], v[204:207], v[16:19]
	v_mfma_f32_16x16x32_bf16 v[4:7], v[172:175], v[212:215], v[4:7]
	v_mfma_f32_16x16x32_bf16 v[0:3], v[180:183], v[212:215], v[0:3]
	s_setprio 0
	s_add_i32 s37, s37, 2
	s_add_u32 s34, s34, 0x100
	s_addc_u32 s35, s35, 0
	s_add_u32 s33, s33, 0x100
	s_addc_u32 s36, s36, 0
	s_cmp_gt_u32 s37, 5
	s_barrier
	s_cbranch_scc0 .LBB0_563
	s_and_b64 vcc, exec, s[14:15]
	s_cbranch_vccz .LBB0_566
	s_barrier

.LBB0_639:
	ds_read_b128 v[140:143], v149
	ds_read_b128 v[152:155], v149 offset:1024
	ds_read_b128 v[156:159], v149 offset:2048
	ds_read_b128 v[160:163], v149 offset:3072
	ds_read_b128 v[164:167], v150
	ds_read_b128 v[168:171], v150 offset:1024
	ds_read_b128 v[172:175], v150 offset:2048
	ds_read_b128 v[176:179], v150 offset:3072
	s_add_u32 s3, s86, 0xfff80080
	s_addc_u32 s33, s87, -1
	s_cmp_eq_u32 s27, 28
	s_cselect_b32 s91, s0, s33
	s_cselect_b32 s90, s1, s3
	s_cselect_b32 s89, s15, s24
	s_cselect_b32 s88, s17, s19
	s_add_i32 m0, s30, 0xc000
	ds_read_b128 v[180:183], v151
	ds_read_b128 v[184:187], v151 offset:1024
	ds_read_b128 v[188:191], v151 offset:2048
	ds_read_b128 v[192:195], v151 offset:3072
	ds_read_b128 v[196:199], v151 offset:4096
	ds_read_b128 v[200:203], v151 offset:5120
	ds_read_b128 v[204:207], v151 offset:6144
	ds_read_b128 v[208:211], v151 offset:7168
	global_load_lds_dwordx4 v132, s[86:87]
	s_add_i32 m0, s30, 0xe000
	s_nop 0
	global_load_lds_dwordx4 v134, s[86:87]
	s_waitcnt vmcnt(8)
	s_waitcnt lgkmcnt(0)
	s_barrier
	s_setprio 1
	v_mfma_f32_16x16x32_bf16 v[124:127], v[140:143], v[180:183], v[124:127]
	v_mfma_f32_16x16x32_bf16 v[120:123], v[156:159], v[180:183], v[120:123]
	v_mfma_f32_16x16x32_bf16 v[108:111], v[140:143], v[188:191], v[108:111]
	v_mfma_f32_16x16x32_bf16 v[104:107], v[156:159], v[188:191], v[104:107]
	v_mfma_f32_16x16x32_bf16 v[92:95], v[140:143], v[196:199], v[92:95]
	v_mfma_f32_16x16x32_bf16 v[88:91], v[156:159], v[196:199], v[88:91]
	v_mfma_f32_16x16x32_bf16 v[76:79], v[140:143], v[204:207], v[76:79]
	v_mfma_f32_16x16x32_bf16 v[72:75], v[156:159], v[204:207], v[72:75]
	v_mfma_f32_16x16x32_bf16 v[124:127], v[152:155], v[184:187], v[124:127]
	v_mfma_f32_16x16x32_bf16 v[120:123], v[160:163], v[184:187], v[120:123]
	v_mfma_f32_16x16x32_bf16 v[108:111], v[152:155], v[192:195], v[108:111]
	v_mfma_f32_16x16x32_bf16 v[104:107], v[160:163], v[192:195], v[104:107]
	v_mfma_f32_16x16x32_bf16 v[92:95], v[152:155], v[200:203], v[92:95]
	v_mfma_f32_16x16x32_bf16 v[88:91], v[160:163], v[200:203], v[88:91]
	v_mfma_f32_16x16x32_bf16 v[76:79], v[152:155], v[208:211], v[76:79]
	v_mfma_f32_16x16x32_bf16 v[72:75], v[160:163], v[208:211], v[72:75]
	v_mfma_f32_16x16x32_bf16 v[116:119], v[164:167], v[180:183], v[116:119]
	v_mfma_f32_16x16x32_bf16 v[112:115], v[172:175], v[180:183], v[112:115]
	v_mfma_f32_16x16x32_bf16 v[100:103], v[164:167], v[188:191], v[100:103]
	v_mfma_f32_16x16x32_bf16 v[96:99], v[172:175], v[188:191], v[96:99]
	v_mfma_f32_16x16x32_bf16 v[84:87], v[164:167], v[196:199], v[84:87]
	v_mfma_f32_16x16x32_bf16 v[80:83], v[172:175], v[196:199], v[80:83]
	v_mfma_f32_16x16x32_bf16 v[68:71], v[164:167], v[204:207], v[68:71]
	v_mfma_f32_16x16x32_bf16 v[64:67], v[172:175], v[204:207], v[64:67]
	v_mfma_f32_16x16x32_bf16 v[116:119], v[168:171], v[184:187], v[116:119]
	v_mfma_f32_16x16x32_bf16 v[112:115], v[176:179], v[184:187], v[112:115]
	v_mfma_f32_16x16x32_bf16 v[100:103], v[168:171], v[192:195], v[100:103]
	v_mfma_f32_16x16x32_bf16 v[96:99], v[176:179], v[192:195], v[96:99]
	v_mfma_f32_16x16x32_bf16 v[84:87], v[168:171], v[200:203], v[84:87]
	v_mfma_f32_16x16x32_bf16 v[80:83], v[176:179], v[200:203], v[80:83]
	v_mfma_f32_16x16x32_bf16 v[68:71], v[168:171], v[208:211], v[68:71]
	v_mfma_f32_16x16x32_bf16 v[64:67], v[176:179], v[208:211], v[64:67]
	s_setprio 0
	s_barrier
	s_add_i32 s3, s59, s25
	s_mov_b32 m0, s3
	ds_read_b128 v[180:183], v151 offset:16384
	ds_read_b128 v[184:187], v151 offset:17408
	ds_read_b128 v[188:191], v151 offset:18432
	ds_read_b128 v[192:195], v151 offset:19456
	ds_read_b128 v[196:199], v151 offset:20480
	ds_read_b128 v[200:203], v151 offset:21504
	ds_read_b128 v[204:207], v151 offset:22528
	ds_read_b128 v[208:211], v151 offset:23552
	global_load_lds_dwordx4 v128, s[88:89]
	s_add_i32 m0, s3, 0x2000
	s_add_u32 s36, s88, 0x80000
	s_addc_u32 s37, s89, 0
	s_add_i32 s3, s68, s25
	global_load_lds_dwordx4 v130, s[88:89]
	s_mov_b32 m0, s3
	s_nop 0
	global_load_lds_dwordx4 v128, s[36:37]
	s_add_i32 m0, s3, 0x2000
	s_nop 0
	global_load_lds_dwordx4 v130, s[36:37]
	s_mov_b32 m0, s30
	s_nop 0
	global_load_lds_dwordx4 v128, s[90:91]
	s_mov_b32 m0, s31
	s_nop 0
	global_load_lds_dwordx4 v130, s[90:91]
	s_waitcnt vmcnt(8)
	s_waitcnt lgkmcnt(0)
	s_barrier
	s_setprio 1
	v_mfma_f32_16x16x32_bf16 v[60:63], v[140:143], v[180:183], v[60:63]
	v_mfma_f32_16x16x32_bf16 v[56:59], v[156:159], v[180:183], v[56:59]
	v_mfma_f32_16x16x32_bf16 v[44:47], v[140:143], v[188:191], v[44:47]
	v_mfma_f32_16x16x32_bf16 v[40:43], v[156:159], v[188:191], v[40:43]
	v_mfma_f32_16x16x32_bf16 v[28:31], v[140:143], v[196:199], v[28:31]
	v_mfma_f32_16x16x32_bf16 v[24:27], v[156:159], v[196:199], v[24:27]
	v_mfma_f32_16x16x32_bf16 v[12:15], v[140:143], v[204:207], v[12:15]
	v_mfma_f32_16x16x32_bf16 v[8:11], v[156:159], v[204:207], v[8:11]
	v_mfma_f32_16x16x32_bf16 v[60:63], v[152:155], v[184:187], v[60:63]
	v_mfma_f32_16x16x32_bf16 v[56:59], v[160:163], v[184:187], v[56:59]
	v_mfma_f32_16x16x32_bf16 v[44:47], v[152:155], v[192:195], v[44:47]
	v_mfma_f32_16x16x32_bf16 v[40:43], v[160:163], v[192:195], v[40:43]
	v_mfma_f32_16x16x32_bf16 v[28:31], v[152:155], v[200:203], v[28:31]
	v_mfma_f32_16x16x32_bf16 v[24:27], v[160:163], v[200:203], v[24:27]
	v_mfma_f32_16x16x32_bf16 v[12:15], v[152:155], v[208:211], v[12:15]
	v_mfma_f32_16x16x32_bf16 v[8:11], v[160:163], v[208:211], v[8:11]
	v_mfma_f32_16x16x32_bf16 v[52:55], v[164:167], v[180:183], v[52:55]
	v_mfma_f32_16x16x32_bf16 v[48:51], v[172:175], v[180:183], v[48:51]
	v_mfma_f32_16x16x32_bf16 v[36:39], v[164:167], v[188:191], v[36:39]
	v_mfma_f32_16x16x32_bf16 v[32:35], v[172:175], v[188:191], v[32:35]
	v_mfma_f32_16x16x32_bf16 v[20:23], v[164:167], v[196:199], v[20:23]
	v_mfma_f32_16x16x32_bf16 v[16:19], v[172:175], v[196:199], v[16:19]
	v_mfma_f32_16x16x32_bf16 v[4:7], v[164:167], v[204:207], v[4:7]
	v_mfma_f32_16x16x32_bf16 v[0:3], v[172:175], v[204:207], v[0:3]
	v_mfma_f32_16x16x32_bf16 v[52:55], v[168:171], v[184:187], v[52:55]
	v_mfma_f32_16x16x32_bf16 v[48:51], v[176:179], v[184:187], v[48:51]
	v_mfma_f32_16x16x32_bf16 v[36:39], v[168:171], v[192:195], v[36:39]
	v_mfma_f32_16x16x32_bf16 v[32:35], v[176:179], v[192:195], v[32:35]
	v_mfma_f32_16x16x32_bf16 v[20:23], v[168:171], v[200:203], v[20:23]
	v_mfma_f32_16x16x32_bf16 v[16:19], v[176:179], v[200:203], v[16:19]
	v_mfma_f32_16x16x32_bf16 v[4:7], v[168:171], v[208:211], v[4:7]
	v_mfma_f32_16x16x32_bf16 v[0:3], v[176:179], v[208:211], v[0:3]
	s_setprio 0
	s_barrier
	s_add_i32 s3, 0, 0x18000
	s_add_i32 s33, 0, 0x1c000
	v_add_u32_e32 v160, s3, v147
	v_add_u32_e32 v176, s33, v147
	ds_read_b128 v[140:143], v160
	ds_read_b128 v[152:155], v160 offset:1024
	ds_read_b128 v[156:159], v160 offset:2048
	ds_read_b128 v[160:163], v160 offset:3072
	ds_read_b128 v[164:167], v176
	ds_read_b128 v[168:171], v176 offset:1024
	ds_read_b128 v[172:175], v176 offset:2048
	ds_read_b128 v[176:179], v176 offset:3072
	s_add_u32 s36, s90, 0x80000
	s_addc_u32 s37, s91, 0
	s_mov_b32 m0, s48
	ds_read_b128 v[180:183], v151 offset:32768
	ds_read_b128 v[184:187], v151 offset:33792
	ds_read_b128 v[188:191], v151 offset:34816
	ds_read_b128 v[192:195], v151 offset:35840
	ds_read_b128 v[196:199], v151 offset:36864
	ds_read_b128 v[200:203], v151 offset:37888
	ds_read_b128 v[204:207], v151 offset:38912
	ds_read_b128 v[208:211], v151 offset:39936
	global_load_lds_dwordx4 v128, s[36:37]
	v_lshl_add_u64 v[218:219], s[36:37], 0, v[130:131]
	s_mov_b32 m0, s49
	s_nop 0
	global_load_lds_dwordx4 v[218:219], off
	s_waitcnt vmcnt(8)
	s_waitcnt lgkmcnt(0)
	s_barrier
	s_setprio 1
	v_mfma_f32_16x16x32_bf16 v[124:127], v[140:143], v[180:183], v[124:127]
	v_mfma_f32_16x16x32_bf16 v[120:123], v[156:159], v[180:183], v[120:123]
	v_mfma_f32_16x16x32_bf16 v[108:111], v[140:143], v[188:191], v[108:111]
	v_mfma_f32_16x16x32_bf16 v[104:107], v[156:159], v[188:191], v[104:107]
	v_mfma_f32_16x16x32_bf16 v[92:95], v[140:143], v[196:199], v[92:95]
	v_mfma_f32_16x16x32_bf16 v[88:91], v[156:159], v[196:199], v[88:91]
	v_mfma_f32_16x16x32_bf16 v[76:79], v[140:143], v[204:207], v[76:79]
	v_mfma_f32_16x16x32_bf16 v[72:75], v[156:159], v[204:207], v[72:75]
	v_mfma_f32_16x16x32_bf16 v[124:127], v[152:155], v[184:187], v[124:127]
	v_mfma_f32_16x16x32_bf16 v[120:123], v[160:163], v[184:187], v[120:123]
	v_mfma_f32_16x16x32_bf16 v[108:111], v[152:155], v[192:195], v[108:111]
	v_mfma_f32_16x16x32_bf16 v[104:107], v[160:163], v[192:195], v[104:107]
	v_mfma_f32_16x16x32_bf16 v[92:95], v[152:155], v[200:203], v[92:95]
	v_mfma_f32_16x16x32_bf16 v[88:91], v[160:163], v[200:203], v[88:91]
	v_mfma_f32_16x16x32_bf16 v[76:79], v[152:155], v[208:211], v[76:79]
	v_mfma_f32_16x16x32_bf16 v[72:75], v[160:163], v[208:211], v[72:75]
	v_mfma_f32_16x16x32_bf16 v[116:119], v[164:167], v[180:183], v[116:119]
	v_mfma_f32_16x16x32_bf16 v[112:115], v[172:175], v[180:183], v[112:115]
	v_mfma_f32_16x16x32_bf16 v[100:103], v[164:167], v[188:191], v[100:103]
	v_mfma_f32_16x16x32_bf16 v[96:99], v[172:175], v[188:191], v[96:99]
	v_mfma_f32_16x16x32_bf16 v[84:87], v[164:167], v[196:199], v[84:87]
	v_mfma_f32_16x16x32_bf16 v[80:83], v[172:175], v[196:199], v[80:83]
	v_mfma_f32_16x16x32_bf16 v[68:71], v[164:167], v[204:207], v[68:71]
	v_mfma_f32_16x16x32_bf16 v[64:67], v[172:175], v[204:207], v[64:67]
	v_mfma_f32_16x16x32_bf16 v[116:119], v[168:171], v[184:187], v[116:119]
	v_mfma_f32_16x16x32_bf16 v[112:115], v[176:179], v[184:187], v[112:115]
	v_mfma_f32_16x16x32_bf16 v[100:103], v[168:171], v[192:195], v[100:103]
	v_mfma_f32_16x16x32_bf16 v[96:99], v[176:179], v[192:195], v[96:99]
	v_mfma_f32_16x16x32_bf16 v[84:87], v[168:171], v[200:203], v[84:87]
	v_mfma_f32_16x16x32_bf16 v[80:83], v[176:179], v[200:203], v[80:83]
	v_mfma_f32_16x16x32_bf16 v[68:71], v[168:171], v[208:211], v[68:71]
	v_mfma_f32_16x16x32_bf16 v[64:67], v[176:179], v[208:211], v[64:67]
	s_setprio 0
	s_barrier
	s_add_i32 s3, s3, s25
	s_add_u32 s36, s88, 0x80
	s_addc_u32 s37, s89, 0
	s_mov_b32 m0, s3
	ds_read_b128 v[180:183], v151 offset:49152
	ds_read_b128 v[184:187], v151 offset:50176
	ds_read_b128 v[188:191], v151 offset:51200
	ds_read_b128 v[192:195], v151 offset:52224
	ds_read_b128 v[196:199], v151 offset:53248
	ds_read_b128 v[200:203], v151 offset:54272
	ds_read_b128 v[204:207], v151 offset:55296
	ds_read_b128 v[208:211], v151 offset:56320
	global_load_lds_dwordx4 v128, s[36:37]
	s_add_i32 m0, s3, 0x2000
	s_add_i32 s3, s33, s25
	global_load_lds_dwordx4 v130, s[36:37]
	s_add_u32 s36, s36, 0x80000
	s_addc_u32 s37, s37, 0
	s_mov_b32 m0, s3
	s_nop 0
	global_load_lds_dwordx4 v128, s[36:37]
	s_add_i32 m0, s3, 0x2000
	s_nop 0
	global_load_lds_dwordx4 v130, s[36:37]
	s_add_u32 s90, s90, 0x80
	s_addc_u32 s91, s91, 0
	s_mov_b32 m0, s57
	s_nop 0
	global_load_lds_dwordx4 v128, s[90:91]
	s_mov_b32 m0, s58
	s_nop 0
	global_load_lds_dwordx4 v130, s[90:91]
	s_waitcnt vmcnt(8)
	s_waitcnt lgkmcnt(0)
	s_barrier
	s_setprio 1
	v_mfma_f32_16x16x32_bf16 v[60:63], v[140:143], v[180:183], v[60:63]
	v_mfma_f32_16x16x32_bf16 v[56:59], v[156:159], v[180:183], v[56:59]
	v_mfma_f32_16x16x32_bf16 v[44:47], v[140:143], v[188:191], v[44:47]
	v_mfma_f32_16x16x32_bf16 v[40:43], v[156:159], v[188:191], v[40:43]
	v_mfma_f32_16x16x32_bf16 v[28:31], v[140:143], v[196:199], v[28:31]
	v_mfma_f32_16x16x32_bf16 v[24:27], v[156:159], v[196:199], v[24:27]
	v_mfma_f32_16x16x32_bf16 v[12:15], v[140:143], v[204:207], v[12:15]
	v_mfma_f32_16x16x32_bf16 v[8:11], v[156:159], v[204:207], v[8:11]
	v_mfma_f32_16x16x32_bf16 v[60:63], v[152:155], v[184:187], v[60:63]
	v_mfma_f32_16x16x32_bf16 v[56:59], v[160:163], v[184:187], v[56:59]
	v_mfma_f32_16x16x32_bf16 v[44:47], v[152:155], v[192:195], v[44:47]
	v_mfma_f32_16x16x32_bf16 v[40:43], v[160:163], v[192:195], v[40:43]
	v_mfma_f32_16x16x32_bf16 v[28:31], v[152:155], v[200:203], v[28:31]
	v_mfma_f32_16x16x32_bf16 v[24:27], v[160:163], v[200:203], v[24:27]
	v_mfma_f32_16x16x32_bf16 v[12:15], v[152:155], v[208:211], v[12:15]
	v_mfma_f32_16x16x32_bf16 v[8:11], v[160:163], v[208:211], v[8:11]
	v_mfma_f32_16x16x32_bf16 v[52:55], v[164:167], v[180:183], v[52:55]
	v_mfma_f32_16x16x32_bf16 v[48:51], v[172:175], v[180:183], v[48:51]
	v_mfma_f32_16x16x32_bf16 v[36:39], v[164:167], v[188:191], v[36:39]
	v_mfma_f32_16x16x32_bf16 v[32:35], v[172:175], v[188:191], v[32:35]
	v_mfma_f32_16x16x32_bf16 v[20:23], v[164:167], v[196:199], v[20:23]
	v_mfma_f32_16x16x32_bf16 v[16:19], v[172:175], v[196:199], v[16:19]
	v_mfma_f32_16x16x32_bf16 v[4:7], v[164:167], v[204:207], v[4:7]
	v_mfma_f32_16x16x32_bf16 v[0:3], v[172:175], v[204:207], v[0:3]
	v_mfma_f32_16x16x32_bf16 v[52:55], v[168:171], v[184:187], v[52:55]
	v_mfma_f32_16x16x32_bf16 v[48:51], v[176:179], v[184:187], v[48:51]
	v_mfma_f32_16x16x32_bf16 v[36:39], v[168:171], v[192:195], v[36:39]
	v_mfma_f32_16x16x32_bf16 v[32:35], v[176:179], v[192:195], v[32:35]
	v_mfma_f32_16x16x32_bf16 v[20:23], v[168:171], v[200:203], v[20:23]
	v_mfma_f32_16x16x32_bf16 v[16:19], v[176:179], v[200:203], v[16:19]
	v_mfma_f32_16x16x32_bf16 v[4:7], v[168:171], v[208:211], v[4:7]
	v_mfma_f32_16x16x32_bf16 v[0:3], v[176:179], v[208:211], v[0:3]
	s_setprio 0
	s_add_i32 s27, s27, 2
	s_add_u32 s86, s86, 0x100
	s_addc_u32 s87, s87, 0
	s_add_u32 s19, s19, 0x100
	s_addc_u32 s24, s24, 0
	s_cmp_gt_u32 s27, 29
	s_barrier
	s_cbranch_scc0 .LBB0_639
	s_and_b64 vcc, exec, s[12:13]
	s_cbranch_vccz .LBB0_642
	s_barrier

.LBB0_770:
	ds_read_b128 v[154:157], v150
	ds_read_b128 v[158:161], v150 offset:1024
	ds_read_b128 v[162:165], v150 offset:2048
	ds_read_b128 v[166:169], v150 offset:3072
	ds_read_b128 v[170:173], v151
	ds_read_b128 v[174:177], v151 offset:1024
	ds_read_b128 v[178:181], v151 offset:2048
	ds_read_b128 v[182:185], v151 offset:3072
	s_add_u32 s3, s88, 0xfff80080
	s_addc_u32 s37, s89, -1
	s_cmp_eq_u32 s36, 28
	s_cselect_b32 s91, s0, s37
	s_cselect_b32 s90, s1, s3
	s_cselect_b32 s81, s17, s35
	s_cselect_b32 s80, s27, s33
	s_add_i32 m0, s19, 0xc000
	ds_read_b128 v[186:189], v152
	ds_read_b128 v[190:193], v152 offset:1024
	ds_read_b128 v[194:197], v152 offset:2048
	ds_read_b128 v[198:201], v152 offset:3072
	ds_read_b128 v[202:205], v152 offset:4096
	ds_read_b128 v[206:209], v152 offset:5120
	ds_read_b128 v[210:213], v152 offset:6144
	ds_read_b128 v[214:217], v152 offset:7168
	global_load_lds_dwordx4 v138, s[88:89]
	s_add_i32 m0, s19, 0xe000
	s_nop 0
	global_load_lds_dwordx4 v140, s[88:89]
	s_waitcnt vmcnt(8)
	s_waitcnt lgkmcnt(0)
	s_barrier
	s_setprio 1
	v_mfma_f32_16x16x32_bf16 v[124:127], v[154:157], v[186:189], v[124:127]
	v_mfma_f32_16x16x32_bf16 v[120:123], v[162:165], v[186:189], v[120:123]
	v_mfma_f32_16x16x32_bf16 v[108:111], v[154:157], v[194:197], v[108:111]
	v_mfma_f32_16x16x32_bf16 v[104:107], v[162:165], v[194:197], v[104:107]
	v_mfma_f32_16x16x32_bf16 v[92:95], v[154:157], v[202:205], v[92:95]
	v_mfma_f32_16x16x32_bf16 v[88:91], v[162:165], v[202:205], v[88:91]
	v_mfma_f32_16x16x32_bf16 v[76:79], v[154:157], v[210:213], v[76:79]
	v_mfma_f32_16x16x32_bf16 v[72:75], v[162:165], v[210:213], v[72:75]
	v_mfma_f32_16x16x32_bf16 v[124:127], v[158:161], v[190:193], v[124:127]
	v_mfma_f32_16x16x32_bf16 v[120:123], v[166:169], v[190:193], v[120:123]
	v_mfma_f32_16x16x32_bf16 v[108:111], v[158:161], v[198:201], v[108:111]
	v_mfma_f32_16x16x32_bf16 v[104:107], v[166:169], v[198:201], v[104:107]
	v_mfma_f32_16x16x32_bf16 v[92:95], v[158:161], v[206:209], v[92:95]
	v_mfma_f32_16x16x32_bf16 v[88:91], v[166:169], v[206:209], v[88:91]
	v_mfma_f32_16x16x32_bf16 v[76:79], v[158:161], v[214:217], v[76:79]
	v_mfma_f32_16x16x32_bf16 v[72:75], v[166:169], v[214:217], v[72:75]
	v_mfma_f32_16x16x32_bf16 v[116:119], v[170:173], v[186:189], v[116:119]
	v_mfma_f32_16x16x32_bf16 v[112:115], v[178:181], v[186:189], v[112:115]
	v_mfma_f32_16x16x32_bf16 v[100:103], v[170:173], v[194:197], v[100:103]
	v_mfma_f32_16x16x32_bf16 v[96:99], v[178:181], v[194:197], v[96:99]
	v_mfma_f32_16x16x32_bf16 v[84:87], v[170:173], v[202:205], v[84:87]
	v_mfma_f32_16x16x32_bf16 v[80:83], v[178:181], v[202:205], v[80:83]
	v_mfma_f32_16x16x32_bf16 v[68:71], v[170:173], v[210:213], v[68:71]
	v_mfma_f32_16x16x32_bf16 v[64:67], v[178:181], v[210:213], v[64:67]
	v_mfma_f32_16x16x32_bf16 v[116:119], v[174:177], v[190:193], v[116:119]
	v_mfma_f32_16x16x32_bf16 v[112:115], v[182:185], v[190:193], v[112:115]
	v_mfma_f32_16x16x32_bf16 v[100:103], v[174:177], v[198:201], v[100:103]
	v_mfma_f32_16x16x32_bf16 v[96:99], v[182:185], v[198:201], v[96:99]
	v_mfma_f32_16x16x32_bf16 v[84:87], v[174:177], v[206:209], v[84:87]
	v_mfma_f32_16x16x32_bf16 v[80:83], v[182:185], v[206:209], v[80:83]
	v_mfma_f32_16x16x32_bf16 v[68:71], v[174:177], v[214:217], v[68:71]
	v_mfma_f32_16x16x32_bf16 v[64:67], v[182:185], v[214:217], v[64:67]
	s_setprio 0
	s_barrier
	s_add_i32 s3, s56, s18
	s_mov_b32 m0, s3
	ds_read_b128 v[186:189], v152 offset:16384
	ds_read_b128 v[190:193], v152 offset:17408
	ds_read_b128 v[194:197], v152 offset:18432
	ds_read_b128 v[198:201], v152 offset:19456
	ds_read_b128 v[202:205], v152 offset:20480
	ds_read_b128 v[206:209], v152 offset:21504
	ds_read_b128 v[210:213], v152 offset:22528
	ds_read_b128 v[214:217], v152 offset:23552
	global_load_lds_dwordx4 v130, s[80:81]
	s_add_i32 m0, s3, 0x2000
	s_add_u32 s42, s80, 0x80000
	s_addc_u32 s43, s81, 0
	s_add_i32 s3, s57, s18
	global_load_lds_dwordx4 v134, s[80:81]
	s_mov_b32 m0, s3
	s_nop 0
	global_load_lds_dwordx4 v130, s[42:43]
	s_add_i32 m0, s3, 0x2000
	s_nop 0
	global_load_lds_dwordx4 v134, s[42:43]
	s_mov_b32 m0, s19
	s_nop 0
	global_load_lds_dwordx4 v128, s[90:91]
	s_mov_b32 m0, s25
	s_nop 0
	global_load_lds_dwordx4 v132, s[90:91]
	s_waitcnt vmcnt(8)
	s_waitcnt lgkmcnt(0)
	s_barrier
	s_setprio 1
	v_mfma_f32_16x16x32_bf16 v[60:63], v[154:157], v[186:189], v[60:63]
	v_mfma_f32_16x16x32_bf16 v[56:59], v[162:165], v[186:189], v[56:59]
	v_mfma_f32_16x16x32_bf16 v[44:47], v[154:157], v[194:197], v[44:47]
	v_mfma_f32_16x16x32_bf16 v[40:43], v[162:165], v[194:197], v[40:43]
	v_mfma_f32_16x16x32_bf16 v[28:31], v[154:157], v[202:205], v[28:31]
	v_mfma_f32_16x16x32_bf16 v[24:27], v[162:165], v[202:205], v[24:27]
	v_mfma_f32_16x16x32_bf16 v[12:15], v[154:157], v[210:213], v[12:15]
	v_mfma_f32_16x16x32_bf16 v[8:11], v[162:165], v[210:213], v[8:11]
	v_mfma_f32_16x16x32_bf16 v[60:63], v[158:161], v[190:193], v[60:63]
	v_mfma_f32_16x16x32_bf16 v[56:59], v[166:169], v[190:193], v[56:59]
	v_mfma_f32_16x16x32_bf16 v[44:47], v[158:161], v[198:201], v[44:47]
	v_mfma_f32_16x16x32_bf16 v[40:43], v[166:169], v[198:201], v[40:43]
	v_mfma_f32_16x16x32_bf16 v[28:31], v[158:161], v[206:209], v[28:31]
	v_mfma_f32_16x16x32_bf16 v[24:27], v[166:169], v[206:209], v[24:27]
	v_mfma_f32_16x16x32_bf16 v[12:15], v[158:161], v[214:217], v[12:15]
	v_mfma_f32_16x16x32_bf16 v[8:11], v[166:169], v[214:217], v[8:11]
	v_mfma_f32_16x16x32_bf16 v[52:55], v[170:173], v[186:189], v[52:55]
	v_mfma_f32_16x16x32_bf16 v[48:51], v[178:181], v[186:189], v[48:51]
	v_mfma_f32_16x16x32_bf16 v[36:39], v[170:173], v[194:197], v[36:39]
	v_mfma_f32_16x16x32_bf16 v[32:35], v[178:181], v[194:197], v[32:35]
	v_mfma_f32_16x16x32_bf16 v[20:23], v[170:173], v[202:205], v[20:23]
	v_mfma_f32_16x16x32_bf16 v[16:19], v[178:181], v[202:205], v[16:19]
	v_mfma_f32_16x16x32_bf16 v[4:7], v[170:173], v[210:213], v[4:7]
	v_mfma_f32_16x16x32_bf16 v[0:3], v[178:181], v[210:213], v[0:3]
	v_mfma_f32_16x16x32_bf16 v[52:55], v[174:177], v[190:193], v[52:55]
	v_mfma_f32_16x16x32_bf16 v[48:51], v[182:185], v[190:193], v[48:51]
	v_mfma_f32_16x16x32_bf16 v[36:39], v[174:177], v[198:201], v[36:39]
	v_mfma_f32_16x16x32_bf16 v[32:35], v[182:185], v[198:201], v[32:35]
	v_mfma_f32_16x16x32_bf16 v[20:23], v[174:177], v[206:209], v[20:23]
	v_mfma_f32_16x16x32_bf16 v[16:19], v[182:185], v[206:209], v[16:19]
	v_mfma_f32_16x16x32_bf16 v[4:7], v[174:177], v[214:217], v[4:7]
	v_mfma_f32_16x16x32_bf16 v[0:3], v[182:185], v[214:217], v[0:3]
	s_setprio 0
	s_barrier
	s_add_i32 s3, 0, 0x18000
	v_add_u32_e32 v153, s3, v149
	s_add_i32 s37, 0, 0x1c000
	ds_read_b128 v[154:157], v153
	ds_read_b128 v[158:161], v153 offset:1024
	ds_read_b128 v[162:165], v153 offset:2048
	ds_read_b128 v[166:169], v153 offset:3072
	v_add_u32_e32 v153, s37, v149
	ds_read_b128 v[170:173], v153
	ds_read_b128 v[174:177], v153 offset:1024
	ds_read_b128 v[178:181], v153 offset:2048
	ds_read_b128 v[182:185], v153 offset:3072
	s_add_u32 s42, s90, 0x80000
	s_addc_u32 s43, s91, 0
	s_mov_b32 m0, s30
	ds_read_b128 v[186:189], v152 offset:32768
	ds_read_b128 v[190:193], v152 offset:33792
	ds_read_b128 v[194:197], v152 offset:34816
	ds_read_b128 v[198:201], v152 offset:35840
	ds_read_b128 v[202:205], v152 offset:36864
	ds_read_b128 v[206:209], v152 offset:37888
	ds_read_b128 v[210:213], v152 offset:38912
	ds_read_b128 v[214:217], v152 offset:39936
	global_load_lds_dwordx4 v128, s[42:43]
	v_lshl_add_u64 v[224:225], s[42:43], 0, v[132:133]
	s_mov_b32 m0, s31
	s_nop 0
	global_load_lds_dwordx4 v[224:225], off
	s_waitcnt vmcnt(8)
	s_waitcnt lgkmcnt(0)
	s_barrier
	s_setprio 1
	v_mfma_f32_16x16x32_bf16 v[124:127], v[154:157], v[186:189], v[124:127]
	v_mfma_f32_16x16x32_bf16 v[120:123], v[162:165], v[186:189], v[120:123]
	v_mfma_f32_16x16x32_bf16 v[108:111], v[154:157], v[194:197], v[108:111]
	v_mfma_f32_16x16x32_bf16 v[104:107], v[162:165], v[194:197], v[104:107]
	v_mfma_f32_16x16x32_bf16 v[92:95], v[154:157], v[202:205], v[92:95]
	v_mfma_f32_16x16x32_bf16 v[88:91], v[162:165], v[202:205], v[88:91]
	v_mfma_f32_16x16x32_bf16 v[76:79], v[154:157], v[210:213], v[76:79]
	v_mfma_f32_16x16x32_bf16 v[72:75], v[162:165], v[210:213], v[72:75]
	v_mfma_f32_16x16x32_bf16 v[124:127], v[158:161], v[190:193], v[124:127]
	v_mfma_f32_16x16x32_bf16 v[120:123], v[166:169], v[190:193], v[120:123]
	v_mfma_f32_16x16x32_bf16 v[108:111], v[158:161], v[198:201], v[108:111]
	v_mfma_f32_16x16x32_bf16 v[104:107], v[166:169], v[198:201], v[104:107]
	v_mfma_f32_16x16x32_bf16 v[92:95], v[158:161], v[206:209], v[92:95]
	v_mfma_f32_16x16x32_bf16 v[88:91], v[166:169], v[206:209], v[88:91]
	v_mfma_f32_16x16x32_bf16 v[76:79], v[158:161], v[214:217], v[76:79]
	v_mfma_f32_16x16x32_bf16 v[72:75], v[166:169], v[214:217], v[72:75]
	v_mfma_f32_16x16x32_bf16 v[116:119], v[170:173], v[186:189], v[116:119]
	v_mfma_f32_16x16x32_bf16 v[112:115], v[178:181], v[186:189], v[112:115]
	v_mfma_f32_16x16x32_bf16 v[100:103], v[170:173], v[194:197], v[100:103]
	v_mfma_f32_16x16x32_bf16 v[96:99], v[178:181], v[194:197], v[96:99]
	v_mfma_f32_16x16x32_bf16 v[84:87], v[170:173], v[202:205], v[84:87]
	v_mfma_f32_16x16x32_bf16 v[80:83], v[178:181], v[202:205], v[80:83]
	v_mfma_f32_16x16x32_bf16 v[68:71], v[170:173], v[210:213], v[68:71]
	v_mfma_f32_16x16x32_bf16 v[64:67], v[178:181], v[210:213], v[64:67]
	v_mfma_f32_16x16x32_bf16 v[116:119], v[174:177], v[190:193], v[116:119]
	v_mfma_f32_16x16x32_bf16 v[112:115], v[182:185], v[190:193], v[112:115]
	v_mfma_f32_16x16x32_bf16 v[100:103], v[174:177], v[198:201], v[100:103]
	v_mfma_f32_16x16x32_bf16 v[96:99], v[182:185], v[198:201], v[96:99]
	v_mfma_f32_16x16x32_bf16 v[84:87], v[174:177], v[206:209], v[84:87]
	v_mfma_f32_16x16x32_bf16 v[80:83], v[182:185], v[206:209], v[80:83]
	v_mfma_f32_16x16x32_bf16 v[68:71], v[174:177], v[214:217], v[68:71]
	v_mfma_f32_16x16x32_bf16 v[64:67], v[182:185], v[214:217], v[64:67]
	s_setprio 0
	s_barrier
	s_add_i32 s3, s3, s18
	s_add_u32 s42, s80, 0x80
	s_addc_u32 s43, s81, 0
	s_mov_b32 m0, s3
	ds_read_b128 v[186:189], v152 offset:49152
	ds_read_b128 v[190:193], v152 offset:50176
	ds_read_b128 v[194:197], v152 offset:51200
	ds_read_b128 v[198:201], v152 offset:52224
	ds_read_b128 v[202:205], v152 offset:53248
	ds_read_b128 v[206:209], v152 offset:54272
	ds_read_b128 v[210:213], v152 offset:55296
	ds_read_b128 v[214:217], v152 offset:56320
	global_load_lds_dwordx4 v130, s[42:43]
	s_add_i32 m0, s3, 0x2000
	s_add_i32 s3, s37, s18
	global_load_lds_dwordx4 v134, s[42:43]
	s_add_u32 s42, s42, 0x80000
	s_addc_u32 s43, s43, 0
	s_mov_b32 m0, s3
	s_nop 0
	global_load_lds_dwordx4 v130, s[42:43]
	s_add_i32 m0, s3, 0x2000
	s_nop 0
	global_load_lds_dwordx4 v134, s[42:43]
	s_add_u32 s90, s90, 0x80
	s_addc_u32 s91, s91, 0
	s_mov_b32 m0, s48
	s_nop 0
	global_load_lds_dwordx4 v128, s[90:91]
	s_mov_b32 m0, s49
	s_nop 0
	global_load_lds_dwordx4 v132, s[90:91]
	s_waitcnt vmcnt(8)
	s_waitcnt lgkmcnt(0)
	s_barrier
	s_setprio 1
	v_mfma_f32_16x16x32_bf16 v[60:63], v[154:157], v[186:189], v[60:63]
	v_mfma_f32_16x16x32_bf16 v[56:59], v[162:165], v[186:189], v[56:59]
	v_mfma_f32_16x16x32_bf16 v[44:47], v[154:157], v[194:197], v[44:47]
	v_mfma_f32_16x16x32_bf16 v[40:43], v[162:165], v[194:197], v[40:43]
	v_mfma_f32_16x16x32_bf16 v[28:31], v[154:157], v[202:205], v[28:31]
	v_mfma_f32_16x16x32_bf16 v[24:27], v[162:165], v[202:205], v[24:27]
	v_mfma_f32_16x16x32_bf16 v[12:15], v[154:157], v[210:213], v[12:15]
	v_mfma_f32_16x16x32_bf16 v[8:11], v[162:165], v[210:213], v[8:11]
	v_mfma_f32_16x16x32_bf16 v[60:63], v[158:161], v[190:193], v[60:63]
	v_mfma_f32_16x16x32_bf16 v[56:59], v[166:169], v[190:193], v[56:59]
	v_mfma_f32_16x16x32_bf16 v[44:47], v[158:161], v[198:201], v[44:47]
	v_mfma_f32_16x16x32_bf16 v[40:43], v[166:169], v[198:201], v[40:43]
	v_mfma_f32_16x16x32_bf16 v[28:31], v[158:161], v[206:209], v[28:31]
	v_mfma_f32_16x16x32_bf16 v[24:27], v[166:169], v[206:209], v[24:27]
	v_mfma_f32_16x16x32_bf16 v[12:15], v[158:161], v[214:217], v[12:15]
	v_mfma_f32_16x16x32_bf16 v[8:11], v[166:169], v[214:217], v[8:11]
	v_mfma_f32_16x16x32_bf16 v[52:55], v[170:173], v[186:189], v[52:55]
	v_mfma_f32_16x16x32_bf16 v[48:51], v[178:181], v[186:189], v[48:51]
	v_mfma_f32_16x16x32_bf16 v[36:39], v[170:173], v[194:197], v[36:39]
	v_mfma_f32_16x16x32_bf16 v[32:35], v[178:181], v[194:197], v[32:35]
	v_mfma_f32_16x16x32_bf16 v[20:23], v[170:173], v[202:205], v[20:23]
	v_mfma_f32_16x16x32_bf16 v[16:19], v[178:181], v[202:205], v[16:19]
	v_mfma_f32_16x16x32_bf16 v[4:7], v[170:173], v[210:213], v[4:7]
	v_mfma_f32_16x16x32_bf16 v[0:3], v[178:181], v[210:213], v[0:3]
	v_mfma_f32_16x16x32_bf16 v[52:55], v[174:177], v[190:193], v[52:55]
	v_mfma_f32_16x16x32_bf16 v[48:51], v[182:185], v[190:193], v[48:51]
	v_mfma_f32_16x16x32_bf16 v[36:39], v[174:177], v[198:201], v[36:39]
	v_mfma_f32_16x16x32_bf16 v[32:35], v[182:185], v[198:201], v[32:35]
	v_mfma_f32_16x16x32_bf16 v[20:23], v[174:177], v[206:209], v[20:23]
	v_mfma_f32_16x16x32_bf16 v[16:19], v[182:185], v[206:209], v[16:19]
	v_mfma_f32_16x16x32_bf16 v[4:7], v[174:177], v[214:217], v[4:7]
	v_mfma_f32_16x16x32_bf16 v[0:3], v[182:185], v[214:217], v[0:3]
	s_setprio 0
	s_add_i32 s36, s36, 2
	s_add_u32 s88, s88, 0x100
	s_addc_u32 s89, s89, 0
	s_add_u32 s33, s33, 0x100
	s_addc_u32 s35, s35, 0
	s_cmp_gt_u32 s36, 29
	s_barrier
	s_cbranch_scc0 .LBB0_770
	s_and_b64 vcc, exec, s[14:15]
	s_cbranch_vccz .LBB0_773
	s_barrier

.LBB0_846:
	ds_read_b128 v[140:143], v149
	ds_read_b128 v[152:155], v149 offset:1024
	ds_read_b128 v[156:159], v149 offset:2048
	ds_read_b128 v[160:163], v149 offset:3072
	ds_read_b128 v[164:167], v150
	ds_read_b128 v[168:171], v150 offset:1024
	ds_read_b128 v[172:175], v150 offset:2048
	ds_read_b128 v[176:179], v150 offset:3072
	s_add_u32 s3, s84, 0xffe00080
	s_addc_u32 s37, s85, -1
	s_cmpk_eq_i32 s36, 0x7c
	s_cselect_b32 s87, s0, s37
	s_cselect_b32 s86, s1, s3
	s_cselect_b32 s81, s15, s33
	s_cselect_b32 s80, s17, s27
	s_add_i32 m0, s19, 0xc000
	ds_read_b128 v[180:183], v151
	ds_read_b128 v[184:187], v151 offset:1024
	ds_read_b128 v[188:191], v151 offset:2048
	ds_read_b128 v[192:195], v151 offset:3072
	ds_read_b128 v[196:199], v151 offset:4096
	ds_read_b128 v[200:203], v151 offset:5120
	ds_read_b128 v[204:207], v151 offset:6144
	ds_read_b128 v[208:211], v151 offset:7168
	global_load_lds_dwordx4 v132, s[84:85]
	s_add_i32 m0, s19, 0xe000
	s_nop 0
	global_load_lds_dwordx4 v134, s[84:85]
	s_waitcnt vmcnt(8)
	s_waitcnt lgkmcnt(0)
	s_barrier
	s_setprio 1
	v_mfma_f32_16x16x32_bf16 v[124:127], v[140:143], v[180:183], v[124:127]
	v_mfma_f32_16x16x32_bf16 v[120:123], v[156:159], v[180:183], v[120:123]
	v_mfma_f32_16x16x32_bf16 v[112:115], v[140:143], v[188:191], v[112:115]
	v_mfma_f32_16x16x32_bf16 v[104:107], v[156:159], v[188:191], v[104:107]
	v_mfma_f32_16x16x32_bf16 v[96:99], v[140:143], v[196:199], v[96:99]
	v_mfma_f32_16x16x32_bf16 v[88:91], v[156:159], v[196:199], v[88:91]
	v_mfma_f32_16x16x32_bf16 v[80:83], v[140:143], v[204:207], v[80:83]
	v_mfma_f32_16x16x32_bf16 v[72:75], v[156:159], v[204:207], v[72:75]
	v_mfma_f32_16x16x32_bf16 v[124:127], v[152:155], v[184:187], v[124:127]
	v_mfma_f32_16x16x32_bf16 v[120:123], v[160:163], v[184:187], v[120:123]
	v_mfma_f32_16x16x32_bf16 v[112:115], v[152:155], v[192:195], v[112:115]
	v_mfma_f32_16x16x32_bf16 v[104:107], v[160:163], v[192:195], v[104:107]
	v_mfma_f32_16x16x32_bf16 v[96:99], v[152:155], v[200:203], v[96:99]
	v_mfma_f32_16x16x32_bf16 v[88:91], v[160:163], v[200:203], v[88:91]
	v_mfma_f32_16x16x32_bf16 v[80:83], v[152:155], v[208:211], v[80:83]
	v_mfma_f32_16x16x32_bf16 v[72:75], v[160:163], v[208:211], v[72:75]
	v_mfma_f32_16x16x32_bf16 v[116:119], v[164:167], v[180:183], v[116:119]
	v_mfma_f32_16x16x32_bf16 v[108:111], v[172:175], v[180:183], v[108:111]
	v_mfma_f32_16x16x32_bf16 v[100:103], v[164:167], v[188:191], v[100:103]
	v_mfma_f32_16x16x32_bf16 v[92:95], v[172:175], v[188:191], v[92:95]
	v_mfma_f32_16x16x32_bf16 v[84:87], v[164:167], v[196:199], v[84:87]
	v_mfma_f32_16x16x32_bf16 v[76:79], v[172:175], v[196:199], v[76:79]
	v_mfma_f32_16x16x32_bf16 v[68:71], v[164:167], v[204:207], v[68:71]
	v_mfma_f32_16x16x32_bf16 v[64:67], v[172:175], v[204:207], v[64:67]
	v_mfma_f32_16x16x32_bf16 v[116:119], v[168:171], v[184:187], v[116:119]
	v_mfma_f32_16x16x32_bf16 v[108:111], v[176:179], v[184:187], v[108:111]
	v_mfma_f32_16x16x32_bf16 v[100:103], v[168:171], v[192:195], v[100:103]
	v_mfma_f32_16x16x32_bf16 v[92:95], v[176:179], v[192:195], v[92:95]
	v_mfma_f32_16x16x32_bf16 v[84:87], v[168:171], v[200:203], v[84:87]
	v_mfma_f32_16x16x32_bf16 v[76:79], v[176:179], v[200:203], v[76:79]
	v_mfma_f32_16x16x32_bf16 v[68:71], v[168:171], v[208:211], v[68:71]
	v_mfma_f32_16x16x32_bf16 v[64:67], v[176:179], v[208:211], v[64:67]
	s_setprio 0
	s_barrier
	s_add_i32 s3, s57, s18
	s_mov_b32 m0, s3
	ds_read_b128 v[180:183], v151 offset:16384
	ds_read_b128 v[184:187], v151 offset:17408
	ds_read_b128 v[188:191], v151 offset:18432
	ds_read_b128 v[192:195], v151 offset:19456
	ds_read_b128 v[196:199], v151 offset:20480
	ds_read_b128 v[200:203], v151 offset:21504
	ds_read_b128 v[204:207], v151 offset:22528
	ds_read_b128 v[208:211], v151 offset:23552
	global_load_lds_dwordx4 v128, s[80:81]
	s_add_i32 m0, s3, 0x2000
	s_add_u32 s42, s80, 0x200000
	s_addc_u32 s43, s81, 0
	s_add_i32 s3, s58, s18
	global_load_lds_dwordx4 v130, s[80:81]
	s_mov_b32 m0, s3
	s_nop 0
	global_load_lds_dwordx4 v128, s[42:43]
	s_add_i32 m0, s3, 0x2000
	s_nop 0
	global_load_lds_dwordx4 v130, s[42:43]
	s_mov_b32 m0, s19
	s_nop 0
	global_load_lds_dwordx4 v128, s[86:87]
	s_mov_b32 m0, s25
	s_nop 0
	global_load_lds_dwordx4 v130, s[86:87]
	s_waitcnt vmcnt(8)
	s_waitcnt lgkmcnt(0)
	s_barrier
	s_setprio 1
	v_mfma_f32_16x16x32_bf16 v[60:63], v[140:143], v[180:183], v[60:63]
	v_mfma_f32_16x16x32_bf16 v[56:59], v[156:159], v[180:183], v[56:59]
	v_mfma_f32_16x16x32_bf16 v[48:51], v[140:143], v[188:191], v[48:51]
	v_mfma_f32_16x16x32_bf16 v[40:43], v[156:159], v[188:191], v[40:43]
	v_mfma_f32_16x16x32_bf16 v[32:35], v[140:143], v[196:199], v[32:35]
	v_mfma_f32_16x16x32_bf16 v[24:27], v[156:159], v[196:199], v[24:27]
	v_mfma_f32_16x16x32_bf16 v[16:19], v[140:143], v[204:207], v[16:19]
	v_mfma_f32_16x16x32_bf16 v[8:11], v[156:159], v[204:207], v[8:11]
	v_mfma_f32_16x16x32_bf16 v[60:63], v[152:155], v[184:187], v[60:63]
	v_mfma_f32_16x16x32_bf16 v[56:59], v[160:163], v[184:187], v[56:59]
	v_mfma_f32_16x16x32_bf16 v[48:51], v[152:155], v[192:195], v[48:51]
	v_mfma_f32_16x16x32_bf16 v[40:43], v[160:163], v[192:195], v[40:43]
	v_mfma_f32_16x16x32_bf16 v[32:35], v[152:155], v[200:203], v[32:35]
	v_mfma_f32_16x16x32_bf16 v[24:27], v[160:163], v[200:203], v[24:27]
	v_mfma_f32_16x16x32_bf16 v[16:19], v[152:155], v[208:211], v[16:19]
	v_mfma_f32_16x16x32_bf16 v[8:11], v[160:163], v[208:211], v[8:11]
	v_mfma_f32_16x16x32_bf16 v[52:55], v[164:167], v[180:183], v[52:55]
	v_mfma_f32_16x16x32_bf16 v[44:47], v[172:175], v[180:183], v[44:47]
	v_mfma_f32_16x16x32_bf16 v[36:39], v[164:167], v[188:191], v[36:39]
	v_mfma_f32_16x16x32_bf16 v[28:31], v[172:175], v[188:191], v[28:31]
	v_mfma_f32_16x16x32_bf16 v[20:23], v[164:167], v[196:199], v[20:23]
	v_mfma_f32_16x16x32_bf16 v[12:15], v[172:175], v[196:199], v[12:15]
	v_mfma_f32_16x16x32_bf16 v[4:7], v[164:167], v[204:207], v[4:7]
	v_mfma_f32_16x16x32_bf16 v[0:3], v[172:175], v[204:207], v[0:3]
	v_mfma_f32_16x16x32_bf16 v[52:55], v[168:171], v[184:187], v[52:55]
	v_mfma_f32_16x16x32_bf16 v[44:47], v[176:179], v[184:187], v[44:47]
	v_mfma_f32_16x16x32_bf16 v[36:39], v[168:171], v[192:195], v[36:39]
	v_mfma_f32_16x16x32_bf16 v[28:31], v[176:179], v[192:195], v[28:31]
	v_mfma_f32_16x16x32_bf16 v[20:23], v[168:171], v[200:203], v[20:23]
	v_mfma_f32_16x16x32_bf16 v[12:15], v[176:179], v[200:203], v[12:15]
	v_mfma_f32_16x16x32_bf16 v[4:7], v[168:171], v[208:211], v[4:7]
	v_mfma_f32_16x16x32_bf16 v[0:3], v[176:179], v[208:211], v[0:3]
	s_setprio 0
	s_barrier
	s_add_i32 s3, 0, 0x18000
	s_add_i32 s37, 0, 0x1c000
	v_add_u32_e32 v160, s3, v147
	v_add_u32_e32 v176, s37, v147
	ds_read_b128 v[140:143], v160
	ds_read_b128 v[152:155], v160 offset:1024
	ds_read_b128 v[156:159], v160 offset:2048
	ds_read_b128 v[160:163], v160 offset:3072
	ds_read_b128 v[164:167], v176
	ds_read_b128 v[168:171], v176 offset:1024
	ds_read_b128 v[172:175], v176 offset:2048
	ds_read_b128 v[176:179], v176 offset:3072
	s_add_u32 s42, s86, 0x200000
	s_addc_u32 s43, s87, 0
	s_mov_b32 m0, s30
	ds_read_b128 v[180:183], v151 offset:32768
	ds_read_b128 v[184:187], v151 offset:33792
	ds_read_b128 v[188:191], v151 offset:34816
	ds_read_b128 v[192:195], v151 offset:35840
	ds_read_b128 v[196:199], v151 offset:36864
	ds_read_b128 v[200:203], v151 offset:37888
	ds_read_b128 v[204:207], v151 offset:38912
	ds_read_b128 v[208:211], v151 offset:39936
	global_load_lds_dwordx4 v128, s[42:43]
	v_lshl_add_u64 v[218:219], s[42:43], 0, v[130:131]
	s_mov_b32 m0, s31
	s_nop 0
	global_load_lds_dwordx4 v[218:219], off
	s_waitcnt vmcnt(8)
	s_waitcnt lgkmcnt(0)
	s_barrier
	s_setprio 1
	v_mfma_f32_16x16x32_bf16 v[124:127], v[140:143], v[180:183], v[124:127]
	v_mfma_f32_16x16x32_bf16 v[120:123], v[156:159], v[180:183], v[120:123]
	v_mfma_f32_16x16x32_bf16 v[112:115], v[140:143], v[188:191], v[112:115]
	v_mfma_f32_16x16x32_bf16 v[104:107], v[156:159], v[188:191], v[104:107]
	v_mfma_f32_16x16x32_bf16 v[96:99], v[140:143], v[196:199], v[96:99]
	v_mfma_f32_16x16x32_bf16 v[88:91], v[156:159], v[196:199], v[88:91]
	v_mfma_f32_16x16x32_bf16 v[80:83], v[140:143], v[204:207], v[80:83]
	v_mfma_f32_16x16x32_bf16 v[72:75], v[156:159], v[204:207], v[72:75]
	v_mfma_f32_16x16x32_bf16 v[124:127], v[152:155], v[184:187], v[124:127]
	v_mfma_f32_16x16x32_bf16 v[120:123], v[160:163], v[184:187], v[120:123]
	v_mfma_f32_16x16x32_bf16 v[112:115], v[152:155], v[192:195], v[112:115]
	v_mfma_f32_16x16x32_bf16 v[104:107], v[160:163], v[192:195], v[104:107]
	v_mfma_f32_16x16x32_bf16 v[96:99], v[152:155], v[200:203], v[96:99]
	v_mfma_f32_16x16x32_bf16 v[88:91], v[160:163], v[200:203], v[88:91]
	v_mfma_f32_16x16x32_bf16 v[80:83], v[152:155], v[208:211], v[80:83]
	v_mfma_f32_16x16x32_bf16 v[72:75], v[160:163], v[208:211], v[72:75]
	v_mfma_f32_16x16x32_bf16 v[116:119], v[164:167], v[180:183], v[116:119]
	v_mfma_f32_16x16x32_bf16 v[108:111], v[172:175], v[180:183], v[108:111]
	v_mfma_f32_16x16x32_bf16 v[100:103], v[164:167], v[188:191], v[100:103]
	v_mfma_f32_16x16x32_bf16 v[92:95], v[172:175], v[188:191], v[92:95]
	v_mfma_f32_16x16x32_bf16 v[84:87], v[164:167], v[196:199], v[84:87]
	v_mfma_f32_16x16x32_bf16 v[76:79], v[172:175], v[196:199], v[76:79]
	v_mfma_f32_16x16x32_bf16 v[68:71], v[164:167], v[204:207], v[68:71]
	v_mfma_f32_16x16x32_bf16 v[64:67], v[172:175], v[204:207], v[64:67]
	v_mfma_f32_16x16x32_bf16 v[116:119], v[168:171], v[184:187], v[116:119]
	v_mfma_f32_16x16x32_bf16 v[108:111], v[176:179], v[184:187], v[108:111]
	v_mfma_f32_16x16x32_bf16 v[100:103], v[168:171], v[192:195], v[100:103]
	v_mfma_f32_16x16x32_bf16 v[92:95], v[176:179], v[192:195], v[92:95]
	v_mfma_f32_16x16x32_bf16 v[84:87], v[168:171], v[200:203], v[84:87]
	v_mfma_f32_16x16x32_bf16 v[76:79], v[176:179], v[200:203], v[76:79]
	v_mfma_f32_16x16x32_bf16 v[68:71], v[168:171], v[208:211], v[68:71]
	v_mfma_f32_16x16x32_bf16 v[64:67], v[176:179], v[208:211], v[64:67]
	s_setprio 0
	s_barrier
	s_add_i32 s3, s3, s18
	s_add_u32 s42, s80, 0x80
	s_addc_u32 s43, s81, 0
	s_mov_b32 m0, s3
	ds_read_b128 v[180:183], v151 offset:49152
	ds_read_b128 v[184:187], v151 offset:50176
	ds_read_b128 v[188:191], v151 offset:51200
	ds_read_b128 v[192:195], v151 offset:52224
	ds_read_b128 v[196:199], v151 offset:53248
	ds_read_b128 v[200:203], v151 offset:54272
	ds_read_b128 v[204:207], v151 offset:55296
	ds_read_b128 v[208:211], v151 offset:56320
	global_load_lds_dwordx4 v128, s[42:43]
	s_add_i32 m0, s3, 0x2000
	s_add_i32 s3, s37, s18
	global_load_lds_dwordx4 v130, s[42:43]
	s_add_u32 s42, s42, 0x200000
	s_addc_u32 s43, s43, 0
	s_mov_b32 m0, s3
	s_nop 0
	global_load_lds_dwordx4 v128, s[42:43]
	s_add_i32 m0, s3, 0x2000
	s_nop 0
	global_load_lds_dwordx4 v130, s[42:43]
	s_add_u32 s86, s86, 0x80
	s_addc_u32 s87, s87, 0
	s_mov_b32 m0, s49
	s_nop 0
	global_load_lds_dwordx4 v128, s[86:87]
	s_mov_b32 m0, s56
	s_nop 0
	global_load_lds_dwordx4 v130, s[86:87]
	s_waitcnt vmcnt(8)
	s_waitcnt lgkmcnt(0)
	s_barrier
	s_setprio 1
	v_mfma_f32_16x16x32_bf16 v[60:63], v[140:143], v[180:183], v[60:63]
	v_mfma_f32_16x16x32_bf16 v[56:59], v[156:159], v[180:183], v[56:59]
	v_mfma_f32_16x16x32_bf16 v[48:51], v[140:143], v[188:191], v[48:51]
	v_mfma_f32_16x16x32_bf16 v[40:43], v[156:159], v[188:191], v[40:43]
	v_mfma_f32_16x16x32_bf16 v[32:35], v[140:143], v[196:199], v[32:35]
	v_mfma_f32_16x16x32_bf16 v[24:27], v[156:159], v[196:199], v[24:27]
	v_mfma_f32_16x16x32_bf16 v[16:19], v[140:143], v[204:207], v[16:19]
	v_mfma_f32_16x16x32_bf16 v[8:11], v[156:159], v[204:207], v[8:11]
	v_mfma_f32_16x16x32_bf16 v[60:63], v[152:155], v[184:187], v[60:63]
	v_mfma_f32_16x16x32_bf16 v[56:59], v[160:163], v[184:187], v[56:59]
	v_mfma_f32_16x16x32_bf16 v[48:51], v[152:155], v[192:195], v[48:51]
	v_mfma_f32_16x16x32_bf16 v[40:43], v[160:163], v[192:195], v[40:43]
	v_mfma_f32_16x16x32_bf16 v[32:35], v[152:155], v[200:203], v[32:35]
	v_mfma_f32_16x16x32_bf16 v[24:27], v[160:163], v[200:203], v[24:27]
	v_mfma_f32_16x16x32_bf16 v[16:19], v[152:155], v[208:211], v[16:19]
	v_mfma_f32_16x16x32_bf16 v[8:11], v[160:163], v[208:211], v[8:11]
	v_mfma_f32_16x16x32_bf16 v[52:55], v[164:167], v[180:183], v[52:55]
	v_mfma_f32_16x16x32_bf16 v[44:47], v[172:175], v[180:183], v[44:47]
	v_mfma_f32_16x16x32_bf16 v[36:39], v[164:167], v[188:191], v[36:39]
	v_mfma_f32_16x16x32_bf16 v[28:31], v[172:175], v[188:191], v[28:31]
	v_mfma_f32_16x16x32_bf16 v[20:23], v[164:167], v[196:199], v[20:23]
	v_mfma_f32_16x16x32_bf16 v[12:15], v[172:175], v[196:199], v[12:15]
	v_mfma_f32_16x16x32_bf16 v[4:7], v[164:167], v[204:207], v[4:7]
	v_mfma_f32_16x16x32_bf16 v[0:3], v[172:175], v[204:207], v[0:3]
	v_mfma_f32_16x16x32_bf16 v[52:55], v[168:171], v[184:187], v[52:55]
	v_mfma_f32_16x16x32_bf16 v[44:47], v[176:179], v[184:187], v[44:47]
	v_mfma_f32_16x16x32_bf16 v[36:39], v[168:171], v[192:195], v[36:39]
	v_mfma_f32_16x16x32_bf16 v[28:31], v[176:179], v[192:195], v[28:31]
	v_mfma_f32_16x16x32_bf16 v[20:23], v[168:171], v[200:203], v[20:23]
	v_mfma_f32_16x16x32_bf16 v[12:15], v[176:179], v[200:203], v[12:15]
	v_mfma_f32_16x16x32_bf16 v[4:7], v[168:171], v[208:211], v[4:7]
	v_mfma_f32_16x16x32_bf16 v[0:3], v[176:179], v[208:211], v[0:3]
	s_setprio 0
	s_add_i32 s36, s36, 2
	s_add_u32 s84, s84, 0x100
	s_addc_u32 s85, s85, 0
	s_add_u32 s27, s27, 0x100
	s_addc_u32 s33, s33, 0
	s_cmpk_gt_u32 s36, 0x7d
	s_barrier
	s_cbranch_scc0 .LBB0_846
	s_and_b64 vcc, exec, s[12:13]
	s_cbranch_vccz .LBB0_849
	s_barrier

.LBB0_919:
	ds_read_b128 v[128:131], v173
	ds_read_b128 v[132:135], v173 offset:1024
	ds_read_b128 v[158:161], v173 offset:2048
	ds_read_b128 v[178:181], v173 offset:3072
	ds_read_b128 v[182:185], v174
	ds_read_b128 v[186:189], v174 offset:1024
	ds_read_b128 v[190:193], v174 offset:2048
	ds_read_b128 v[194:197], v174 offset:3072
	s_add_u32 s3, s34, 0xfff80080
	s_addc_u32 s27, s35, -1
	s_cmp_eq_u32 s24, 28
	s_cselect_b32 vcc_hi, s0, s27
	s_cselect_b32 vcc_lo, s1, s3
	s_cselect_b32 s81, s15, s19
	s_cselect_b32 s80, s17, s18
	s_add_i32 m0, s30, 0xc000
	ds_read_b128 v[198:201], v175
	ds_read_b128 v[202:205], v175 offset:1024
	ds_read_b128 v[206:209], v175 offset:2048
	ds_read_b128 v[210:213], v175 offset:3072
	ds_read_b128 v[214:217], v175 offset:4096
	ds_read_b128 v[218:221], v175 offset:5120
	ds_read_b128 v[222:225], v175 offset:6144
	ds_read_b128 v[230:233], v175 offset:7168
	global_load_lds_dwordx4 v148, s[34:35]
	s_add_i32 m0, s30, 0xe000
	s_nop 0
	global_load_lds_dwordx4 v150, s[34:35]
	s_waitcnt vmcnt(8)
	s_waitcnt lgkmcnt(0)
	s_barrier
	s_setprio 1
	v_mfma_f32_16x16x32_bf16 v[124:127], v[128:131], v[198:201], v[124:127]
	v_mfma_f32_16x16x32_bf16 v[120:123], v[158:161], v[198:201], v[120:123]
	v_mfma_f32_16x16x32_bf16 v[108:111], v[128:131], v[206:209], v[108:111]
	v_mfma_f32_16x16x32_bf16 v[104:107], v[158:161], v[206:209], v[104:107]
	v_mfma_f32_16x16x32_bf16 v[92:95], v[128:131], v[214:217], v[92:95]
	v_mfma_f32_16x16x32_bf16 v[88:91], v[158:161], v[214:217], v[88:91]
	v_mfma_f32_16x16x32_bf16 v[76:79], v[128:131], v[222:225], v[76:79]
	v_mfma_f32_16x16x32_bf16 v[72:75], v[158:161], v[222:225], v[72:75]
	v_mfma_f32_16x16x32_bf16 v[124:127], v[132:135], v[202:205], v[124:127]
	v_mfma_f32_16x16x32_bf16 v[120:123], v[178:181], v[202:205], v[120:123]
	v_mfma_f32_16x16x32_bf16 v[108:111], v[132:135], v[210:213], v[108:111]
	v_mfma_f32_16x16x32_bf16 v[104:107], v[178:181], v[210:213], v[104:107]
	v_mfma_f32_16x16x32_bf16 v[92:95], v[132:135], v[218:221], v[92:95]
	v_mfma_f32_16x16x32_bf16 v[88:91], v[178:181], v[218:221], v[88:91]
	v_mfma_f32_16x16x32_bf16 v[76:79], v[132:135], v[230:233], v[76:79]
	v_mfma_f32_16x16x32_bf16 v[72:75], v[178:181], v[230:233], v[72:75]
	v_mfma_f32_16x16x32_bf16 v[116:119], v[182:185], v[198:201], v[116:119]
	v_mfma_f32_16x16x32_bf16 v[112:115], v[190:193], v[198:201], v[112:115]
	v_mfma_f32_16x16x32_bf16 v[100:103], v[182:185], v[206:209], v[100:103]
	v_mfma_f32_16x16x32_bf16 v[96:99], v[190:193], v[206:209], v[96:99]
	v_mfma_f32_16x16x32_bf16 v[84:87], v[182:185], v[214:217], v[84:87]
	v_mfma_f32_16x16x32_bf16 v[80:83], v[190:193], v[214:217], v[80:83]
	v_mfma_f32_16x16x32_bf16 v[68:71], v[182:185], v[222:225], v[68:71]
	v_mfma_f32_16x16x32_bf16 v[64:67], v[190:193], v[222:225], v[64:67]
	v_mfma_f32_16x16x32_bf16 v[116:119], v[186:189], v[202:205], v[116:119]
	v_mfma_f32_16x16x32_bf16 v[112:115], v[194:197], v[202:205], v[112:115]
	v_mfma_f32_16x16x32_bf16 v[100:103], v[186:189], v[210:213], v[100:103]
	v_mfma_f32_16x16x32_bf16 v[96:99], v[194:197], v[210:213], v[96:99]
	v_mfma_f32_16x16x32_bf16 v[84:87], v[186:189], v[218:221], v[84:87]
	v_mfma_f32_16x16x32_bf16 v[80:83], v[194:197], v[218:221], v[80:83]
	v_mfma_f32_16x16x32_bf16 v[68:71], v[186:189], v[230:233], v[68:71]
	v_mfma_f32_16x16x32_bf16 v[64:67], v[194:197], v[230:233], v[64:67]
	s_setprio 0
	s_barrier
	s_add_i32 s3, s57, s25
	s_mov_b32 m0, s3
	ds_read_b128 v[198:201], v175 offset:16384
	ds_read_b128 v[202:205], v175 offset:17408
	ds_read_b128 v[206:209], v175 offset:18432
	ds_read_b128 v[210:213], v175 offset:19456
	ds_read_b128 v[214:217], v175 offset:20480
	ds_read_b128 v[218:221], v175 offset:21504
	ds_read_b128 v[222:225], v175 offset:22528
	ds_read_b128 v[230:233], v175 offset:23552
	global_load_lds_dwordx4 v138, s[80:81]
	s_add_i32 m0, s3, 0x2000
	s_add_u32 s36, s80, 0x80000
	s_addc_u32 s37, s81, 0
	s_add_i32 s3, s76, s25
	global_load_lds_dwordx4 v142, s[80:81]
	s_mov_b32 m0, s3
	s_nop 0
	global_load_lds_dwordx4 v138, s[36:37]
	s_add_i32 m0, s3, 0x2000
	s_nop 0
	global_load_lds_dwordx4 v142, s[36:37]
	s_mov_b32 m0, s30
	s_nop 0
	global_load_lds_dwordx4 v136, vcc
	s_mov_b32 m0, s31
	s_nop 0
	global_load_lds_dwordx4 v140, vcc
	s_waitcnt vmcnt(8)
	s_waitcnt lgkmcnt(0)
	s_barrier
	s_setprio 1
	v_mfma_f32_16x16x32_bf16 v[60:63], v[128:131], v[198:201], v[60:63]
	v_mfma_f32_16x16x32_bf16 v[56:59], v[158:161], v[198:201], v[56:59]
	v_mfma_f32_16x16x32_bf16 v[44:47], v[128:131], v[206:209], v[44:47]
	v_mfma_f32_16x16x32_bf16 v[40:43], v[158:161], v[206:209], v[40:43]
	v_mfma_f32_16x16x32_bf16 v[28:31], v[128:131], v[214:217], v[28:31]
	v_mfma_f32_16x16x32_bf16 v[24:27], v[158:161], v[214:217], v[24:27]
	v_mfma_f32_16x16x32_bf16 v[12:15], v[128:131], v[222:225], v[12:15]
	v_mfma_f32_16x16x32_bf16 v[8:11], v[158:161], v[222:225], v[8:11]
	v_mfma_f32_16x16x32_bf16 v[60:63], v[132:135], v[202:205], v[60:63]
	v_mfma_f32_16x16x32_bf16 v[56:59], v[178:181], v[202:205], v[56:59]
	v_mfma_f32_16x16x32_bf16 v[44:47], v[132:135], v[210:213], v[44:47]
	v_mfma_f32_16x16x32_bf16 v[40:43], v[178:181], v[210:213], v[40:43]
	v_mfma_f32_16x16x32_bf16 v[28:31], v[132:135], v[218:221], v[28:31]
	v_mfma_f32_16x16x32_bf16 v[24:27], v[178:181], v[218:221], v[24:27]
	v_mfma_f32_16x16x32_bf16 v[12:15], v[132:135], v[230:233], v[12:15]
	v_mfma_f32_16x16x32_bf16 v[8:11], v[178:181], v[230:233], v[8:11]
	v_mfma_f32_16x16x32_bf16 v[52:55], v[182:185], v[198:201], v[52:55]
	v_mfma_f32_16x16x32_bf16 v[48:51], v[190:193], v[198:201], v[48:51]
	v_mfma_f32_16x16x32_bf16 v[36:39], v[182:185], v[206:209], v[36:39]
	v_mfma_f32_16x16x32_bf16 v[32:35], v[190:193], v[206:209], v[32:35]
	v_mfma_f32_16x16x32_bf16 v[20:23], v[182:185], v[214:217], v[20:23]
	v_mfma_f32_16x16x32_bf16 v[16:19], v[190:193], v[214:217], v[16:19]
	v_mfma_f32_16x16x32_bf16 v[4:7], v[182:185], v[222:225], v[4:7]
	v_mfma_f32_16x16x32_bf16 v[0:3], v[190:193], v[222:225], v[0:3]
	v_mfma_f32_16x16x32_bf16 v[52:55], v[186:189], v[202:205], v[52:55]
	v_mfma_f32_16x16x32_bf16 v[48:51], v[194:197], v[202:205], v[48:51]
	v_mfma_f32_16x16x32_bf16 v[36:39], v[186:189], v[210:213], v[36:39]
	v_mfma_f32_16x16x32_bf16 v[32:35], v[194:197], v[210:213], v[32:35]
	v_mfma_f32_16x16x32_bf16 v[20:23], v[186:189], v[218:221], v[20:23]
	v_mfma_f32_16x16x32_bf16 v[16:19], v[194:197], v[218:221], v[16:19]
	v_mfma_f32_16x16x32_bf16 v[4:7], v[186:189], v[230:233], v[4:7]
	v_mfma_f32_16x16x32_bf16 v[0:3], v[194:197], v[230:233], v[0:3]
	s_setprio 0
	s_barrier
	s_add_i32 s3, 0, 0x18000
	v_add_u32_e32 v144, s3, v165
	s_add_i32 s27, 0, 0x1c000
	ds_read_b128 v[128:131], v144
	ds_read_b128 v[132:135], v144 offset:1024
	ds_read_b128 v[158:161], v144 offset:2048
	ds_read_b128 v[178:181], v144 offset:3072
	v_add_u32_e32 v144, s27, v165
	ds_read_b128 v[182:185], v144
	ds_read_b128 v[186:189], v144 offset:1024
	ds_read_b128 v[190:193], v144 offset:2048
	ds_read_b128 v[194:197], v144 offset:3072
	s_add_u32 s36, vcc_lo, 0x80000
	s_addc_u32 s37, vcc_hi, 0
	s_mov_b32 m0, s58
	ds_read_b128 v[198:201], v175 offset:32768
	ds_read_b128 v[202:205], v175 offset:33792
	ds_read_b128 v[206:209], v175 offset:34816
	ds_read_b128 v[210:213], v175 offset:35840
	ds_read_b128 v[214:217], v175 offset:36864
	ds_read_b128 v[218:221], v175 offset:37888
	ds_read_b128 v[222:225], v175 offset:38912
	ds_read_b128 v[230:233], v175 offset:39936
	global_load_lds_dwordx4 v136, s[36:37]
	s_mov_b32 m0, s59
	s_nop 0
	global_load_lds_dwordx4 v140, s[36:37]
	s_waitcnt vmcnt(8)
	s_waitcnt lgkmcnt(0)
	s_barrier
	s_setprio 1
	v_mfma_f32_16x16x32_bf16 v[124:127], v[128:131], v[198:201], v[124:127]
	v_mfma_f32_16x16x32_bf16 v[120:123], v[158:161], v[198:201], v[120:123]
	v_mfma_f32_16x16x32_bf16 v[108:111], v[128:131], v[206:209], v[108:111]
	v_mfma_f32_16x16x32_bf16 v[104:107], v[158:161], v[206:209], v[104:107]
	v_mfma_f32_16x16x32_bf16 v[92:95], v[128:131], v[214:217], v[92:95]
	v_mfma_f32_16x16x32_bf16 v[88:91], v[158:161], v[214:217], v[88:91]
	v_mfma_f32_16x16x32_bf16 v[76:79], v[128:131], v[222:225], v[76:79]
	v_mfma_f32_16x16x32_bf16 v[72:75], v[158:161], v[222:225], v[72:75]
	v_mfma_f32_16x16x32_bf16 v[124:127], v[132:135], v[202:205], v[124:127]
	v_mfma_f32_16x16x32_bf16 v[120:123], v[178:181], v[202:205], v[120:123]
	v_mfma_f32_16x16x32_bf16 v[108:111], v[132:135], v[210:213], v[108:111]
	v_mfma_f32_16x16x32_bf16 v[104:107], v[178:181], v[210:213], v[104:107]
	v_mfma_f32_16x16x32_bf16 v[92:95], v[132:135], v[218:221], v[92:95]
	v_mfma_f32_16x16x32_bf16 v[88:91], v[178:181], v[218:221], v[88:91]
	v_mfma_f32_16x16x32_bf16 v[76:79], v[132:135], v[230:233], v[76:79]
	v_mfma_f32_16x16x32_bf16 v[72:75], v[178:181], v[230:233], v[72:75]
	v_mfma_f32_16x16x32_bf16 v[116:119], v[182:185], v[198:201], v[116:119]
	v_mfma_f32_16x16x32_bf16 v[112:115], v[190:193], v[198:201], v[112:115]
	v_mfma_f32_16x16x32_bf16 v[100:103], v[182:185], v[206:209], v[100:103]
	v_mfma_f32_16x16x32_bf16 v[96:99], v[190:193], v[206:209], v[96:99]
	v_mfma_f32_16x16x32_bf16 v[84:87], v[182:185], v[214:217], v[84:87]
	v_mfma_f32_16x16x32_bf16 v[80:83], v[190:193], v[214:217], v[80:83]
	v_mfma_f32_16x16x32_bf16 v[68:71], v[182:185], v[222:225], v[68:71]
	v_mfma_f32_16x16x32_bf16 v[64:67], v[190:193], v[222:225], v[64:67]
	v_mfma_f32_16x16x32_bf16 v[116:119], v[186:189], v[202:205], v[116:119]
	v_mfma_f32_16x16x32_bf16 v[112:115], v[194:197], v[202:205], v[112:115]
	v_mfma_f32_16x16x32_bf16 v[100:103], v[186:189], v[210:213], v[100:103]
	v_mfma_f32_16x16x32_bf16 v[96:99], v[194:197], v[210:213], v[96:99]
	v_mfma_f32_16x16x32_bf16 v[84:87], v[186:189], v[218:221], v[84:87]
	v_mfma_f32_16x16x32_bf16 v[80:83], v[194:197], v[218:221], v[80:83]
	v_mfma_f32_16x16x32_bf16 v[68:71], v[186:189], v[230:233], v[68:71]
	v_mfma_f32_16x16x32_bf16 v[64:67], v[194:197], v[230:233], v[64:67]
	s_setprio 0
	s_barrier
	s_add_i32 s3, s3, s25
	s_add_u32 s36, s80, 0x80
	s_addc_u32 s37, s81, 0
	s_mov_b32 m0, s3
	ds_read_b128 v[198:201], v175 offset:49152
	ds_read_b128 v[202:205], v175 offset:50176
	ds_read_b128 v[206:209], v175 offset:51200
	ds_read_b128 v[210:213], v175 offset:52224
	ds_read_b128 v[214:217], v175 offset:53248
	ds_read_b128 v[218:221], v175 offset:54272
	ds_read_b128 v[222:225], v175 offset:55296
	ds_read_b128 v[230:233], v175 offset:56320
	global_load_lds_dwordx4 v138, s[36:37]
	s_add_i32 m0, s3, 0x2000
	s_add_i32 s3, s27, s25
	global_load_lds_dwordx4 v142, s[36:37]
	s_add_u32 s36, s36, 0x80000
	s_addc_u32 s37, s37, 0
	s_mov_b32 m0, s3
	s_nop 0
	global_load_lds_dwordx4 v138, s[36:37]
	s_add_i32 m0, s3, 0x2000
	s_nop 0
	global_load_lds_dwordx4 v142, s[36:37]
	s_add_u32 vcc_lo, vcc_lo, 0x80
	s_addc_u32 vcc_hi, vcc_hi, 0
	s_mov_b32 m0, s78
	s_nop 0
	global_load_lds_dwordx4 v136, vcc
	s_mov_b32 m0, s56
	s_nop 0
	global_load_lds_dwordx4 v140, vcc
	s_waitcnt vmcnt(8)
	s_waitcnt lgkmcnt(0)
	s_barrier
	s_setprio 1
	v_mfma_f32_16x16x32_bf16 v[60:63], v[128:131], v[198:201], v[60:63]
	v_mfma_f32_16x16x32_bf16 v[56:59], v[158:161], v[198:201], v[56:59]
	v_mfma_f32_16x16x32_bf16 v[44:47], v[128:131], v[206:209], v[44:47]
	v_mfma_f32_16x16x32_bf16 v[40:43], v[158:161], v[206:209], v[40:43]
	v_mfma_f32_16x16x32_bf16 v[28:31], v[128:131], v[214:217], v[28:31]
	v_mfma_f32_16x16x32_bf16 v[24:27], v[158:161], v[214:217], v[24:27]
	v_mfma_f32_16x16x32_bf16 v[12:15], v[128:131], v[222:225], v[12:15]
	v_mfma_f32_16x16x32_bf16 v[8:11], v[158:161], v[222:225], v[8:11]
	v_mfma_f32_16x16x32_bf16 v[60:63], v[132:135], v[202:205], v[60:63]
	v_mfma_f32_16x16x32_bf16 v[56:59], v[178:181], v[202:205], v[56:59]
	v_mfma_f32_16x16x32_bf16 v[44:47], v[132:135], v[210:213], v[44:47]
	v_mfma_f32_16x16x32_bf16 v[40:43], v[178:181], v[210:213], v[40:43]
	v_mfma_f32_16x16x32_bf16 v[28:31], v[132:135], v[218:221], v[28:31]
	v_mfma_f32_16x16x32_bf16 v[24:27], v[178:181], v[218:221], v[24:27]
	v_mfma_f32_16x16x32_bf16 v[12:15], v[132:135], v[230:233], v[12:15]
	v_mfma_f32_16x16x32_bf16 v[8:11], v[178:181], v[230:233], v[8:11]
	v_mfma_f32_16x16x32_bf16 v[52:55], v[182:185], v[198:201], v[52:55]
	v_mfma_f32_16x16x32_bf16 v[48:51], v[190:193], v[198:201], v[48:51]
	v_mfma_f32_16x16x32_bf16 v[36:39], v[182:185], v[206:209], v[36:39]
	v_mfma_f32_16x16x32_bf16 v[32:35], v[190:193], v[206:209], v[32:35]
	v_mfma_f32_16x16x32_bf16 v[20:23], v[182:185], v[214:217], v[20:23]
	v_mfma_f32_16x16x32_bf16 v[16:19], v[190:193], v[214:217], v[16:19]
	v_mfma_f32_16x16x32_bf16 v[4:7], v[182:185], v[222:225], v[4:7]
	v_mfma_f32_16x16x32_bf16 v[0:3], v[190:193], v[222:225], v[0:3]
	v_mfma_f32_16x16x32_bf16 v[52:55], v[186:189], v[202:205], v[52:55]
	v_mfma_f32_16x16x32_bf16 v[48:51], v[194:197], v[202:205], v[48:51]
	v_mfma_f32_16x16x32_bf16 v[36:39], v[186:189], v[210:213], v[36:39]
	v_mfma_f32_16x16x32_bf16 v[32:35], v[194:197], v[210:213], v[32:35]
	v_mfma_f32_16x16x32_bf16 v[20:23], v[186:189], v[218:221], v[20:23]
	v_mfma_f32_16x16x32_bf16 v[16:19], v[194:197], v[218:221], v[16:19]
	v_mfma_f32_16x16x32_bf16 v[4:7], v[186:189], v[230:233], v[4:7]
	v_mfma_f32_16x16x32_bf16 v[0:3], v[194:197], v[230:233], v[0:3]
	s_setprio 0
	s_add_i32 s24, s24, 2
	s_add_u32 s34, s34, 0x100
	s_addc_u32 s35, s35, 0
	s_add_u32 s18, s18, 0x100
	s_addc_u32 s19, s19, 0
	s_cmp_gt_u32 s24, 29
	s_barrier
	s_cbranch_scc0 .LBB0_919
	s_and_b64 vcc, exec, s[86:87]
	s_cbranch_vccz .LBB0_922
	s_barrier

.LBB0_1393:
	ds_read_b128 v[144:147], v153
	ds_read_b128 v[156:159], v153 offset:1024
	ds_read_b128 v[160:163], v153 offset:2048
	ds_read_b128 v[164:167], v153 offset:3072
	ds_read_b128 v[168:171], v154
	ds_read_b128 v[172:175], v154 offset:1024
	ds_read_b128 v[176:179], v154 offset:2048
	ds_read_b128 v[180:183], v154 offset:3072
	s_add_u32 s3, s88, 0xfffc0080
	s_addc_u32 s37, s89, -1
	s_cmp_eq_u32 s36, 12
	s_cselect_b32 s91, s0, s37
	s_cselect_b32 s90, s1, s3
	s_cselect_b32 s81, s17, s35
	s_cselect_b32 s80, s27, s33
	s_add_i32 m0, s19, 0xc000
	ds_read_b128 v[184:187], v155
	ds_read_b128 v[188:191], v155 offset:1024
	ds_read_b128 v[192:195], v155 offset:2048
	ds_read_b128 v[196:199], v155 offset:3072
	ds_read_b128 v[200:203], v155 offset:4096
	ds_read_b128 v[204:207], v155 offset:5120
	ds_read_b128 v[208:211], v155 offset:6144
	ds_read_b128 v[212:215], v155 offset:7168
	global_load_lds_dwordx4 v136, s[88:89]
	s_add_i32 m0, s19, 0xe000
	s_nop 0
	global_load_lds_dwordx4 v138, s[88:89]
	s_waitcnt vmcnt(8)
	s_waitcnt lgkmcnt(0)
	s_barrier
	s_setprio 1
	v_mfma_f32_16x16x32_bf16 v[124:127], v[144:147], v[184:187], v[124:127]
	v_mfma_f32_16x16x32_bf16 v[120:123], v[160:163], v[184:187], v[120:123]
	v_mfma_f32_16x16x32_bf16 v[108:111], v[144:147], v[192:195], v[108:111]
	v_mfma_f32_16x16x32_bf16 v[104:107], v[160:163], v[192:195], v[104:107]
	v_mfma_f32_16x16x32_bf16 v[92:95], v[144:147], v[200:203], v[92:95]
	v_mfma_f32_16x16x32_bf16 v[88:91], v[160:163], v[200:203], v[88:91]
	v_mfma_f32_16x16x32_bf16 v[76:79], v[144:147], v[208:211], v[76:79]
	v_mfma_f32_16x16x32_bf16 v[72:75], v[160:163], v[208:211], v[72:75]
	v_mfma_f32_16x16x32_bf16 v[124:127], v[156:159], v[188:191], v[124:127]
	v_mfma_f32_16x16x32_bf16 v[120:123], v[164:167], v[188:191], v[120:123]
	v_mfma_f32_16x16x32_bf16 v[108:111], v[156:159], v[196:199], v[108:111]
	v_mfma_f32_16x16x32_bf16 v[104:107], v[164:167], v[196:199], v[104:107]
	v_mfma_f32_16x16x32_bf16 v[92:95], v[156:159], v[204:207], v[92:95]
	v_mfma_f32_16x16x32_bf16 v[88:91], v[164:167], v[204:207], v[88:91]
	v_mfma_f32_16x16x32_bf16 v[76:79], v[156:159], v[212:215], v[76:79]
	v_mfma_f32_16x16x32_bf16 v[72:75], v[164:167], v[212:215], v[72:75]
	v_mfma_f32_16x16x32_bf16 v[116:119], v[168:171], v[184:187], v[116:119]
	v_mfma_f32_16x16x32_bf16 v[112:115], v[176:179], v[184:187], v[112:115]
	v_mfma_f32_16x16x32_bf16 v[100:103], v[168:171], v[192:195], v[100:103]
	v_mfma_f32_16x16x32_bf16 v[96:99], v[176:179], v[192:195], v[96:99]
	v_mfma_f32_16x16x32_bf16 v[84:87], v[168:171], v[200:203], v[84:87]
	v_mfma_f32_16x16x32_bf16 v[80:83], v[176:179], v[200:203], v[80:83]
	v_mfma_f32_16x16x32_bf16 v[68:71], v[168:171], v[208:211], v[68:71]
	v_mfma_f32_16x16x32_bf16 v[64:67], v[176:179], v[208:211], v[64:67]
	v_mfma_f32_16x16x32_bf16 v[116:119], v[172:175], v[188:191], v[116:119]
	v_mfma_f32_16x16x32_bf16 v[112:115], v[180:183], v[188:191], v[112:115]
	v_mfma_f32_16x16x32_bf16 v[100:103], v[172:175], v[196:199], v[100:103]
	v_mfma_f32_16x16x32_bf16 v[96:99], v[180:183], v[196:199], v[96:99]
	v_mfma_f32_16x16x32_bf16 v[84:87], v[172:175], v[204:207], v[84:87]
	v_mfma_f32_16x16x32_bf16 v[80:83], v[180:183], v[204:207], v[80:83]
	v_mfma_f32_16x16x32_bf16 v[68:71], v[172:175], v[212:215], v[68:71]
	v_mfma_f32_16x16x32_bf16 v[64:67], v[180:183], v[212:215], v[64:67]
	s_setprio 0
	s_barrier
	s_add_i32 s3, s57, s18
	s_mov_b32 m0, s3
	ds_read_b128 v[184:187], v155 offset:16384
	ds_read_b128 v[188:191], v155 offset:17408
	ds_read_b128 v[192:195], v155 offset:18432
	ds_read_b128 v[196:199], v155 offset:19456
	ds_read_b128 v[200:203], v155 offset:20480
	ds_read_b128 v[204:207], v155 offset:21504
	ds_read_b128 v[208:211], v155 offset:22528
	ds_read_b128 v[212:215], v155 offset:23552
	global_load_lds_dwordx4 v130, s[80:81]
	s_add_i32 m0, s3, 0x2000
	s_add_u32 s42, s80, 0x40000
	s_addc_u32 s43, s81, 0
	s_add_i32 s3, s58, s18
	global_load_lds_dwordx4 v134, s[80:81]
	s_mov_b32 m0, s3
	s_nop 0
	global_load_lds_dwordx4 v130, s[42:43]
	s_add_i32 m0, s3, 0x2000
	s_nop 0
	global_load_lds_dwordx4 v134, s[42:43]
	s_mov_b32 m0, s19
	s_nop 0
	global_load_lds_dwordx4 v128, s[90:91]
	s_mov_b32 m0, s25
	s_nop 0
	global_load_lds_dwordx4 v132, s[90:91]
	s_waitcnt vmcnt(8)
	s_waitcnt lgkmcnt(0)
	s_barrier
	s_setprio 1
	v_mfma_f32_16x16x32_bf16 v[60:63], v[144:147], v[184:187], v[60:63]
	v_mfma_f32_16x16x32_bf16 v[56:59], v[160:163], v[184:187], v[56:59]
	v_mfma_f32_16x16x32_bf16 v[44:47], v[144:147], v[192:195], v[44:47]
	v_mfma_f32_16x16x32_bf16 v[40:43], v[160:163], v[192:195], v[40:43]
	v_mfma_f32_16x16x32_bf16 v[28:31], v[144:147], v[200:203], v[28:31]
	v_mfma_f32_16x16x32_bf16 v[24:27], v[160:163], v[200:203], v[24:27]
	v_mfma_f32_16x16x32_bf16 v[12:15], v[144:147], v[208:211], v[12:15]
	v_mfma_f32_16x16x32_bf16 v[8:11], v[160:163], v[208:211], v[8:11]
	v_mfma_f32_16x16x32_bf16 v[60:63], v[156:159], v[188:191], v[60:63]
	v_mfma_f32_16x16x32_bf16 v[56:59], v[164:167], v[188:191], v[56:59]
	v_mfma_f32_16x16x32_bf16 v[44:47], v[156:159], v[196:199], v[44:47]
	v_mfma_f32_16x16x32_bf16 v[40:43], v[164:167], v[196:199], v[40:43]
	v_mfma_f32_16x16x32_bf16 v[28:31], v[156:159], v[204:207], v[28:31]
	v_mfma_f32_16x16x32_bf16 v[24:27], v[164:167], v[204:207], v[24:27]
	v_mfma_f32_16x16x32_bf16 v[12:15], v[156:159], v[212:215], v[12:15]
	v_mfma_f32_16x16x32_bf16 v[8:11], v[164:167], v[212:215], v[8:11]
	v_mfma_f32_16x16x32_bf16 v[52:55], v[168:171], v[184:187], v[52:55]
	v_mfma_f32_16x16x32_bf16 v[48:51], v[176:179], v[184:187], v[48:51]
	v_mfma_f32_16x16x32_bf16 v[36:39], v[168:171], v[192:195], v[36:39]
	v_mfma_f32_16x16x32_bf16 v[32:35], v[176:179], v[192:195], v[32:35]
	v_mfma_f32_16x16x32_bf16 v[20:23], v[168:171], v[200:203], v[20:23]
	v_mfma_f32_16x16x32_bf16 v[16:19], v[176:179], v[200:203], v[16:19]
	v_mfma_f32_16x16x32_bf16 v[4:7], v[168:171], v[208:211], v[4:7]
	v_mfma_f32_16x16x32_bf16 v[0:3], v[176:179], v[208:211], v[0:3]
	v_mfma_f32_16x16x32_bf16 v[52:55], v[172:175], v[188:191], v[52:55]
	v_mfma_f32_16x16x32_bf16 v[48:51], v[180:183], v[188:191], v[48:51]
	v_mfma_f32_16x16x32_bf16 v[36:39], v[172:175], v[196:199], v[36:39]
	v_mfma_f32_16x16x32_bf16 v[32:35], v[180:183], v[196:199], v[32:35]
	v_mfma_f32_16x16x32_bf16 v[20:23], v[172:175], v[204:207], v[20:23]
	v_mfma_f32_16x16x32_bf16 v[16:19], v[180:183], v[204:207], v[16:19]
	v_mfma_f32_16x16x32_bf16 v[4:7], v[172:175], v[212:215], v[4:7]
	v_mfma_f32_16x16x32_bf16 v[0:3], v[180:183], v[212:215], v[0:3]
	s_setprio 0
	s_barrier
	s_add_i32 s3, 0, 0x18000
	s_add_i32 s37, 0, 0x1c000
	v_add_u32_e32 v164, s3, v151
	v_add_u32_e32 v180, s37, v151
	ds_read_b128 v[144:147], v164
	ds_read_b128 v[156:159], v164 offset:1024
	ds_read_b128 v[160:163], v164 offset:2048
	ds_read_b128 v[164:167], v164 offset:3072
	ds_read_b128 v[168:171], v180
	ds_read_b128 v[172:175], v180 offset:1024
	ds_read_b128 v[176:179], v180 offset:2048
	ds_read_b128 v[180:183], v180 offset:3072
	s_add_u32 s42, s90, 0x40000
	s_addc_u32 s43, s91, 0
	s_mov_b32 m0, s30
	ds_read_b128 v[184:187], v155 offset:32768
	ds_read_b128 v[188:191], v155 offset:33792
	ds_read_b128 v[192:195], v155 offset:34816
	ds_read_b128 v[196:199], v155 offset:35840
	ds_read_b128 v[200:203], v155 offset:36864
	ds_read_b128 v[204:207], v155 offset:37888
	ds_read_b128 v[208:211], v155 offset:38912
	ds_read_b128 v[212:215], v155 offset:39936
	global_load_lds_dwordx4 v128, s[42:43]
	v_lshl_add_u64 v[222:223], s[42:43], 0, v[132:133]
	s_mov_b32 m0, s31
	s_nop 0
	global_load_lds_dwordx4 v[222:223], off
	s_waitcnt vmcnt(8)
	s_waitcnt lgkmcnt(0)
	s_barrier
	s_setprio 1
	v_mfma_f32_16x16x32_bf16 v[124:127], v[144:147], v[184:187], v[124:127]
	v_mfma_f32_16x16x32_bf16 v[120:123], v[160:163], v[184:187], v[120:123]
	v_mfma_f32_16x16x32_bf16 v[108:111], v[144:147], v[192:195], v[108:111]
	v_mfma_f32_16x16x32_bf16 v[104:107], v[160:163], v[192:195], v[104:107]
	v_mfma_f32_16x16x32_bf16 v[92:95], v[144:147], v[200:203], v[92:95]
	v_mfma_f32_16x16x32_bf16 v[88:91], v[160:163], v[200:203], v[88:91]
	v_mfma_f32_16x16x32_bf16 v[76:79], v[144:147], v[208:211], v[76:79]
	v_mfma_f32_16x16x32_bf16 v[72:75], v[160:163], v[208:211], v[72:75]
	v_mfma_f32_16x16x32_bf16 v[124:127], v[156:159], v[188:191], v[124:127]
	v_mfma_f32_16x16x32_bf16 v[120:123], v[164:167], v[188:191], v[120:123]
	v_mfma_f32_16x16x32_bf16 v[108:111], v[156:159], v[196:199], v[108:111]
	v_mfma_f32_16x16x32_bf16 v[104:107], v[164:167], v[196:199], v[104:107]
	v_mfma_f32_16x16x32_bf16 v[92:95], v[156:159], v[204:207], v[92:95]
	v_mfma_f32_16x16x32_bf16 v[88:91], v[164:167], v[204:207], v[88:91]
	v_mfma_f32_16x16x32_bf16 v[76:79], v[156:159], v[212:215], v[76:79]
	v_mfma_f32_16x16x32_bf16 v[72:75], v[164:167], v[212:215], v[72:75]
	v_mfma_f32_16x16x32_bf16 v[116:119], v[168:171], v[184:187], v[116:119]
	v_mfma_f32_16x16x32_bf16 v[112:115], v[176:179], v[184:187], v[112:115]
	v_mfma_f32_16x16x32_bf16 v[100:103], v[168:171], v[192:195], v[100:103]
	v_mfma_f32_16x16x32_bf16 v[96:99], v[176:179], v[192:195], v[96:99]
	v_mfma_f32_16x16x32_bf16 v[84:87], v[168:171], v[200:203], v[84:87]
	v_mfma_f32_16x16x32_bf16 v[80:83], v[176:179], v[200:203], v[80:83]
	v_mfma_f32_16x16x32_bf16 v[68:71], v[168:171], v[208:211], v[68:71]
	v_mfma_f32_16x16x32_bf16 v[64:67], v[176:179], v[208:211], v[64:67]
	v_mfma_f32_16x16x32_bf16 v[116:119], v[172:175], v[188:191], v[116:119]
	v_mfma_f32_16x16x32_bf16 v[112:115], v[180:183], v[188:191], v[112:115]
	v_mfma_f32_16x16x32_bf16 v[100:103], v[172:175], v[196:199], v[100:103]
	v_mfma_f32_16x16x32_bf16 v[96:99], v[180:183], v[196:199], v[96:99]
	v_mfma_f32_16x16x32_bf16 v[84:87], v[172:175], v[204:207], v[84:87]
	v_mfma_f32_16x16x32_bf16 v[80:83], v[180:183], v[204:207], v[80:83]
	v_mfma_f32_16x16x32_bf16 v[68:71], v[172:175], v[212:215], v[68:71]
	v_mfma_f32_16x16x32_bf16 v[64:67], v[180:183], v[212:215], v[64:67]
	s_setprio 0
	s_barrier
	s_add_i32 s3, s3, s18
	s_add_u32 s42, s80, 0x80
	s_addc_u32 s43, s81, 0
	s_mov_b32 m0, s3
	ds_read_b128 v[184:187], v155 offset:49152
	ds_read_b128 v[188:191], v155 offset:50176
	ds_read_b128 v[192:195], v155 offset:51200
	ds_read_b128 v[196:199], v155 offset:52224
	ds_read_b128 v[200:203], v155 offset:53248
	ds_read_b128 v[204:207], v155 offset:54272
	ds_read_b128 v[208:211], v155 offset:55296
	ds_read_b128 v[212:215], v155 offset:56320
	global_load_lds_dwordx4 v130, s[42:43]
	s_add_i32 m0, s3, 0x2000
	s_add_i32 s3, s37, s18
	global_load_lds_dwordx4 v134, s[42:43]
	s_add_u32 s42, s42, 0x40000
	s_addc_u32 s43, s43, 0
	s_mov_b32 m0, s3
	s_nop 0
	global_load_lds_dwordx4 v130, s[42:43]
	s_add_i32 m0, s3, 0x2000
	s_nop 0
	global_load_lds_dwordx4 v134, s[42:43]
	s_add_u32 s90, s90, 0x80
	s_addc_u32 s91, s91, 0
	s_mov_b32 m0, s53
	s_nop 0
	global_load_lds_dwordx4 v128, s[90:91]
	s_mov_b32 m0, s56
	s_nop 0
	global_load_lds_dwordx4 v132, s[90:91]
	s_waitcnt vmcnt(8)
	s_waitcnt lgkmcnt(0)
	s_barrier
	s_setprio 1
	v_mfma_f32_16x16x32_bf16 v[60:63], v[144:147], v[184:187], v[60:63]
	v_mfma_f32_16x16x32_bf16 v[56:59], v[160:163], v[184:187], v[56:59]
	v_mfma_f32_16x16x32_bf16 v[44:47], v[144:147], v[192:195], v[44:47]
	v_mfma_f32_16x16x32_bf16 v[40:43], v[160:163], v[192:195], v[40:43]
	v_mfma_f32_16x16x32_bf16 v[28:31], v[144:147], v[200:203], v[28:31]
	v_mfma_f32_16x16x32_bf16 v[24:27], v[160:163], v[200:203], v[24:27]
	v_mfma_f32_16x16x32_bf16 v[12:15], v[144:147], v[208:211], v[12:15]
	v_mfma_f32_16x16x32_bf16 v[8:11], v[160:163], v[208:211], v[8:11]
	v_mfma_f32_16x16x32_bf16 v[60:63], v[156:159], v[188:191], v[60:63]
	v_mfma_f32_16x16x32_bf16 v[56:59], v[164:167], v[188:191], v[56:59]
	v_mfma_f32_16x16x32_bf16 v[44:47], v[156:159], v[196:199], v[44:47]
	v_mfma_f32_16x16x32_bf16 v[40:43], v[164:167], v[196:199], v[40:43]
	v_mfma_f32_16x16x32_bf16 v[28:31], v[156:159], v[204:207], v[28:31]
	v_mfma_f32_16x16x32_bf16 v[24:27], v[164:167], v[204:207], v[24:27]
	v_mfma_f32_16x16x32_bf16 v[12:15], v[156:159], v[212:215], v[12:15]
	v_mfma_f32_16x16x32_bf16 v[8:11], v[164:167], v[212:215], v[8:11]
	v_mfma_f32_16x16x32_bf16 v[52:55], v[168:171], v[184:187], v[52:55]
	v_mfma_f32_16x16x32_bf16 v[48:51], v[176:179], v[184:187], v[48:51]
	v_mfma_f32_16x16x32_bf16 v[36:39], v[168:171], v[192:195], v[36:39]
	v_mfma_f32_16x16x32_bf16 v[32:35], v[176:179], v[192:195], v[32:35]
	v_mfma_f32_16x16x32_bf16 v[20:23], v[168:171], v[200:203], v[20:23]
	v_mfma_f32_16x16x32_bf16 v[16:19], v[176:179], v[200:203], v[16:19]
	v_mfma_f32_16x16x32_bf16 v[4:7], v[168:171], v[208:211], v[4:7]
	v_mfma_f32_16x16x32_bf16 v[0:3], v[176:179], v[208:211], v[0:3]
	v_mfma_f32_16x16x32_bf16 v[52:55], v[172:175], v[188:191], v[52:55]
	v_mfma_f32_16x16x32_bf16 v[48:51], v[180:183], v[188:191], v[48:51]
	v_mfma_f32_16x16x32_bf16 v[36:39], v[172:175], v[196:199], v[36:39]
	v_mfma_f32_16x16x32_bf16 v[32:35], v[180:183], v[196:199], v[32:35]
	v_mfma_f32_16x16x32_bf16 v[20:23], v[172:175], v[204:207], v[20:23]
	v_mfma_f32_16x16x32_bf16 v[16:19], v[180:183], v[204:207], v[16:19]
	v_mfma_f32_16x16x32_bf16 v[4:7], v[172:175], v[212:215], v[4:7]
	v_mfma_f32_16x16x32_bf16 v[0:3], v[180:183], v[212:215], v[0:3]
	s_setprio 0
	s_add_i32 s36, s36, 2
	s_add_u32 s88, s88, 0x100
	s_addc_u32 s89, s89, 0
	s_add_u32 s33, s33, 0x100
	s_addc_u32 s35, s35, 0
	s_cmp_gt_u32 s36, 13
	s_barrier
	s_cbranch_scc0 .LBB0_1393
	s_and_b64 vcc, exec, s[12:13]
	s_cbranch_vccz .LBB0_1396
	s_barrier

.LBB0_1417:
	ds_read_b128 v[144:147], v157
	ds_read_b128 v[148:151], v157 offset:1024
	ds_read_b128 v[160:163], v157 offset:2048
	ds_read_b128 v[164:167], v157 offset:3072
	ds_read_b128 v[168:171], v158
	ds_read_b128 v[172:175], v158 offset:1024
	ds_read_b128 v[176:179], v158 offset:2048
	ds_read_b128 v[180:183], v158 offset:3072
	s_add_u32 s3, s34, 0xfffe0080
	s_addc_u32 s42, s35, -1
	s_cmp_eq_u32 s37, 4
	s_cselect_b32 s91, s0, s42
	s_cselect_b32 s90, s1, s3
	s_cselect_b32 s81, s24, s36
	s_cselect_b32 s80, s27, s33
	s_add_i32 m0, s19, 0xc000
	ds_read_b128 v[184:187], v159
	ds_read_b128 v[188:191], v159 offset:1024
	ds_read_b128 v[192:195], v159 offset:2048
	ds_read_b128 v[196:199], v159 offset:3072
	ds_read_b128 v[200:203], v159 offset:4096
	ds_read_b128 v[204:207], v159 offset:5120
	ds_read_b128 v[208:211], v159 offset:6144
	ds_read_b128 v[212:215], v159 offset:7168
	global_load_lds_dwordx4 v136, s[34:35]
	s_add_i32 m0, s19, 0xe000
	s_nop 0
	global_load_lds_dwordx4 v138, s[34:35]
	s_waitcnt vmcnt(8)
	s_waitcnt lgkmcnt(0)
	s_barrier
	s_setprio 1
	v_mfma_f32_16x16x32_bf16 v[124:127], v[144:147], v[184:187], v[124:127]
	v_mfma_f32_16x16x32_bf16 v[120:123], v[160:163], v[184:187], v[120:123]
	v_mfma_f32_16x16x32_bf16 v[108:111], v[144:147], v[192:195], v[108:111]
	v_mfma_f32_16x16x32_bf16 v[104:107], v[160:163], v[192:195], v[104:107]
	v_mfma_f32_16x16x32_bf16 v[92:95], v[144:147], v[200:203], v[92:95]
	v_mfma_f32_16x16x32_bf16 v[88:91], v[160:163], v[200:203], v[88:91]
	v_mfma_f32_16x16x32_bf16 v[76:79], v[144:147], v[208:211], v[76:79]
	v_mfma_f32_16x16x32_bf16 v[72:75], v[160:163], v[208:211], v[72:75]
	v_mfma_f32_16x16x32_bf16 v[124:127], v[148:151], v[188:191], v[124:127]
	v_mfma_f32_16x16x32_bf16 v[120:123], v[164:167], v[188:191], v[120:123]
	v_mfma_f32_16x16x32_bf16 v[108:111], v[148:151], v[196:199], v[108:111]
	v_mfma_f32_16x16x32_bf16 v[104:107], v[164:167], v[196:199], v[104:107]
	v_mfma_f32_16x16x32_bf16 v[92:95], v[148:151], v[204:207], v[92:95]
	v_mfma_f32_16x16x32_bf16 v[88:91], v[164:167], v[204:207], v[88:91]
	v_mfma_f32_16x16x32_bf16 v[76:79], v[148:151], v[212:215], v[76:79]
	v_mfma_f32_16x16x32_bf16 v[72:75], v[164:167], v[212:215], v[72:75]
	v_mfma_f32_16x16x32_bf16 v[116:119], v[168:171], v[184:187], v[116:119]
	v_mfma_f32_16x16x32_bf16 v[112:115], v[176:179], v[184:187], v[112:115]
	v_mfma_f32_16x16x32_bf16 v[100:103], v[168:171], v[192:195], v[100:103]
	v_mfma_f32_16x16x32_bf16 v[96:99], v[176:179], v[192:195], v[96:99]
	v_mfma_f32_16x16x32_bf16 v[84:87], v[168:171], v[200:203], v[84:87]
	v_mfma_f32_16x16x32_bf16 v[80:83], v[176:179], v[200:203], v[80:83]
	v_mfma_f32_16x16x32_bf16 v[68:71], v[168:171], v[208:211], v[68:71]
	v_mfma_f32_16x16x32_bf16 v[64:67], v[176:179], v[208:211], v[64:67]
	v_mfma_f32_16x16x32_bf16 v[116:119], v[172:175], v[188:191], v[116:119]
	v_mfma_f32_16x16x32_bf16 v[112:115], v[180:183], v[188:191], v[112:115]
	v_mfma_f32_16x16x32_bf16 v[100:103], v[172:175], v[196:199], v[100:103]
	v_mfma_f32_16x16x32_bf16 v[96:99], v[180:183], v[196:199], v[96:99]
	v_mfma_f32_16x16x32_bf16 v[84:87], v[172:175], v[204:207], v[84:87]
	v_mfma_f32_16x16x32_bf16 v[80:83], v[180:183], v[204:207], v[80:83]
	v_mfma_f32_16x16x32_bf16 v[68:71], v[172:175], v[212:215], v[68:71]
	v_mfma_f32_16x16x32_bf16 v[64:67], v[180:183], v[212:215], v[64:67]
	s_setprio 0
	s_barrier
	s_add_i32 s3, s78, s18
	s_mov_b32 m0, s3
	ds_read_b128 v[184:187], v159 offset:16384
	ds_read_b128 v[188:191], v159 offset:17408
	ds_read_b128 v[192:195], v159 offset:18432
	ds_read_b128 v[196:199], v159 offset:19456
	ds_read_b128 v[200:203], v159 offset:20480
	ds_read_b128 v[204:207], v159 offset:21504
	ds_read_b128 v[208:211], v159 offset:22528
	ds_read_b128 v[212:215], v159 offset:23552
	global_load_lds_dwordx4 v130, s[80:81]
	s_add_i32 m0, s3, 0x2000
	s_add_u32 s42, s80, 0x20000
	s_addc_u32 s43, s81, 0
	s_add_i32 s3, s79, s18
	global_load_lds_dwordx4 v134, s[80:81]
	s_mov_b32 m0, s3
	s_nop 0
	global_load_lds_dwordx4 v130, s[42:43]
	s_add_i32 m0, s3, 0x2000
	s_nop 0
	global_load_lds_dwordx4 v134, s[42:43]
	s_mov_b32 m0, s19
	s_nop 0
	global_load_lds_dwordx4 v128, s[90:91]
	s_mov_b32 m0, s25
	s_nop 0
	global_load_lds_dwordx4 v132, s[90:91]
	s_waitcnt vmcnt(8)
	s_waitcnt lgkmcnt(0)
	s_barrier
	s_setprio 1
	v_mfma_f32_16x16x32_bf16 v[60:63], v[144:147], v[184:187], v[60:63]
	v_mfma_f32_16x16x32_bf16 v[56:59], v[160:163], v[184:187], v[56:59]
	v_mfma_f32_16x16x32_bf16 v[44:47], v[144:147], v[192:195], v[44:47]
	v_mfma_f32_16x16x32_bf16 v[40:43], v[160:163], v[192:195], v[40:43]
	v_mfma_f32_16x16x32_bf16 v[28:31], v[144:147], v[200:203], v[28:31]
	v_mfma_f32_16x16x32_bf16 v[24:27], v[160:163], v[200:203], v[24:27]
	v_mfma_f32_16x16x32_bf16 v[12:15], v[144:147], v[208:211], v[12:15]
	v_mfma_f32_16x16x32_bf16 v[8:11], v[160:163], v[208:211], v[8:11]
	v_mfma_f32_16x16x32_bf16 v[60:63], v[148:151], v[188:191], v[60:63]
	v_mfma_f32_16x16x32_bf16 v[56:59], v[164:167], v[188:191], v[56:59]
	v_mfma_f32_16x16x32_bf16 v[44:47], v[148:151], v[196:199], v[44:47]
	v_mfma_f32_16x16x32_bf16 v[40:43], v[164:167], v[196:199], v[40:43]
	v_mfma_f32_16x16x32_bf16 v[28:31], v[148:151], v[204:207], v[28:31]
	v_mfma_f32_16x16x32_bf16 v[24:27], v[164:167], v[204:207], v[24:27]
	v_mfma_f32_16x16x32_bf16 v[12:15], v[148:151], v[212:215], v[12:15]
	v_mfma_f32_16x16x32_bf16 v[8:11], v[164:167], v[212:215], v[8:11]
	v_mfma_f32_16x16x32_bf16 v[52:55], v[168:171], v[184:187], v[52:55]
	v_mfma_f32_16x16x32_bf16 v[48:51], v[176:179], v[184:187], v[48:51]
	v_mfma_f32_16x16x32_bf16 v[36:39], v[168:171], v[192:195], v[36:39]
	v_mfma_f32_16x16x32_bf16 v[32:35], v[176:179], v[192:195], v[32:35]
	v_mfma_f32_16x16x32_bf16 v[20:23], v[168:171], v[200:203], v[20:23]
	v_mfma_f32_16x16x32_bf16 v[16:19], v[176:179], v[200:203], v[16:19]
	v_mfma_f32_16x16x32_bf16 v[4:7], v[168:171], v[208:211], v[4:7]
	v_mfma_f32_16x16x32_bf16 v[0:3], v[176:179], v[208:211], v[0:3]
	v_mfma_f32_16x16x32_bf16 v[52:55], v[172:175], v[188:191], v[52:55]
	v_mfma_f32_16x16x32_bf16 v[48:51], v[180:183], v[188:191], v[48:51]
	v_mfma_f32_16x16x32_bf16 v[36:39], v[172:175], v[196:199], v[36:39]
	v_mfma_f32_16x16x32_bf16 v[32:35], v[180:183], v[196:199], v[32:35]
	v_mfma_f32_16x16x32_bf16 v[20:23], v[172:175], v[204:207], v[20:23]
	v_mfma_f32_16x16x32_bf16 v[16:19], v[180:183], v[204:207], v[16:19]
	v_mfma_f32_16x16x32_bf16 v[4:7], v[172:175], v[212:215], v[4:7]
	v_mfma_f32_16x16x32_bf16 v[0:3], v[180:183], v[212:215], v[0:3]
	s_setprio 0
	s_barrier
	s_add_i32 s3, 0, 0x18000
	s_add_i32 s44, 0, 0x1c000
	v_add_u32_e32 v164, s3, v155
	v_add_u32_e32 v180, s44, v155
	ds_read_b128 v[144:147], v164
	ds_read_b128 v[148:151], v164 offset:1024
	ds_read_b128 v[160:163], v164 offset:2048
	ds_read_b128 v[164:167], v164 offset:3072
	ds_read_b128 v[168:171], v180
	ds_read_b128 v[172:175], v180 offset:1024
	ds_read_b128 v[176:179], v180 offset:2048
	ds_read_b128 v[180:183], v180 offset:3072
	s_add_u32 s42, s90, 0x20000
	s_addc_u32 s43, s91, 0
	s_mov_b32 m0, s30
	ds_read_b128 v[184:187], v159 offset:32768
	ds_read_b128 v[188:191], v159 offset:33792
	ds_read_b128 v[192:195], v159 offset:34816
	ds_read_b128 v[196:199], v159 offset:35840
	ds_read_b128 v[200:203], v159 offset:36864
	ds_read_b128 v[204:207], v159 offset:37888
	ds_read_b128 v[208:211], v159 offset:38912
	ds_read_b128 v[212:215], v159 offset:39936
	global_load_lds_dwordx4 v128, s[42:43]
	v_lshl_add_u64 v[222:223], s[42:43], 0, v[132:133]
	s_mov_b32 m0, s31
	s_nop 0
	global_load_lds_dwordx4 v[222:223], off
	s_waitcnt vmcnt(8)
	s_waitcnt lgkmcnt(0)
	s_barrier
	s_setprio 1
	v_mfma_f32_16x16x32_bf16 v[124:127], v[144:147], v[184:187], v[124:127]
	v_mfma_f32_16x16x32_bf16 v[120:123], v[160:163], v[184:187], v[120:123]
	v_mfma_f32_16x16x32_bf16 v[108:111], v[144:147], v[192:195], v[108:111]
	v_mfma_f32_16x16x32_bf16 v[104:107], v[160:163], v[192:195], v[104:107]
	v_mfma_f32_16x16x32_bf16 v[92:95], v[144:147], v[200:203], v[92:95]
	v_mfma_f32_16x16x32_bf16 v[88:91], v[160:163], v[200:203], v[88:91]
	v_mfma_f32_16x16x32_bf16 v[76:79], v[144:147], v[208:211], v[76:79]
	v_mfma_f32_16x16x32_bf16 v[72:75], v[160:163], v[208:211], v[72:75]
	v_mfma_f32_16x16x32_bf16 v[124:127], v[148:151], v[188:191], v[124:127]
	v_mfma_f32_16x16x32_bf16 v[120:123], v[164:167], v[188:191], v[120:123]
	v_mfma_f32_16x16x32_bf16 v[108:111], v[148:151], v[196:199], v[108:111]
	v_mfma_f32_16x16x32_bf16 v[104:107], v[164:167], v[196:199], v[104:107]
	v_mfma_f32_16x16x32_bf16 v[92:95], v[148:151], v[204:207], v[92:95]
	v_mfma_f32_16x16x32_bf16 v[88:91], v[164:167], v[204:207], v[88:91]
	v_mfma_f32_16x16x32_bf16 v[76:79], v[148:151], v[212:215], v[76:79]
	v_mfma_f32_16x16x32_bf16 v[72:75], v[164:167], v[212:215], v[72:75]
	v_mfma_f32_16x16x32_bf16 v[116:119], v[168:171], v[184:187], v[116:119]
	v_mfma_f32_16x16x32_bf16 v[112:115], v[176:179], v[184:187], v[112:115]
	v_mfma_f32_16x16x32_bf16 v[100:103], v[168:171], v[192:195], v[100:103]
	v_mfma_f32_16x16x32_bf16 v[96:99], v[176:179], v[192:195], v[96:99]
	v_mfma_f32_16x16x32_bf16 v[84:87], v[168:171], v[200:203], v[84:87]
	v_mfma_f32_16x16x32_bf16 v[80:83], v[176:179], v[200:203], v[80:83]
	v_mfma_f32_16x16x32_bf16 v[68:71], v[168:171], v[208:211], v[68:71]
	v_mfma_f32_16x16x32_bf16 v[64:67], v[176:179], v[208:211], v[64:67]
	v_mfma_f32_16x16x32_bf16 v[116:119], v[172:175], v[188:191], v[116:119]
	v_mfma_f32_16x16x32_bf16 v[112:115], v[180:183], v[188:191], v[112:115]
	v_mfma_f32_16x16x32_bf16 v[100:103], v[172:175], v[196:199], v[100:103]
	v_mfma_f32_16x16x32_bf16 v[96:99], v[180:183], v[196:199], v[96:99]
	v_mfma_f32_16x16x32_bf16 v[84:87], v[172:175], v[204:207], v[84:87]
	v_mfma_f32_16x16x32_bf16 v[80:83], v[180:183], v[204:207], v[80:83]
	v_mfma_f32_16x16x32_bf16 v[68:71], v[172:175], v[212:215], v[68:71]
	v_mfma_f32_16x16x32_bf16 v[64:67], v[180:183], v[212:215], v[64:67]
	s_setprio 0
	s_barrier
	s_add_i32 s3, s3, s18
	s_add_u32 s42, s80, 0x80
	s_addc_u32 s43, s81, 0
	s_mov_b32 m0, s3
	ds_read_b128 v[184:187], v159 offset:49152
	ds_read_b128 v[188:191], v159 offset:50176
	ds_read_b128 v[192:195], v159 offset:51200
	ds_read_b128 v[196:199], v159 offset:52224
	ds_read_b128 v[200:203], v159 offset:53248
	ds_read_b128 v[204:207], v159 offset:54272
	ds_read_b128 v[208:211], v159 offset:55296
	ds_read_b128 v[212:215], v159 offset:56320
	global_load_lds_dwordx4 v130, s[42:43]
	s_add_i32 m0, s3, 0x2000
	s_add_i32 s3, s44, s18
	global_load_lds_dwordx4 v134, s[42:43]
	s_add_u32 s42, s42, 0x20000
	s_addc_u32 s43, s43, 0
	s_mov_b32 m0, s3
	s_nop 0
	global_load_lds_dwordx4 v130, s[42:43]
	s_add_i32 m0, s3, 0x2000
	s_nop 0
	global_load_lds_dwordx4 v134, s[42:43]
	s_add_u32 s90, s90, 0x80
	s_addc_u32 s91, s91, 0
	s_mov_b32 m0, s58
	s_nop 0
	global_load_lds_dwordx4 v128, s[90:91]
	s_mov_b32 m0, s59
	s_nop 0
	global_load_lds_dwordx4 v132, s[90:91]
	s_waitcnt vmcnt(8)
	s_waitcnt lgkmcnt(0)
	s_barrier
	s_setprio 1
	v_mfma_f32_16x16x32_bf16 v[60:63], v[144:147], v[184:187], v[60:63]
	v_mfma_f32_16x16x32_bf16 v[56:59], v[160:163], v[184:187], v[56:59]
	v_mfma_f32_16x16x32_bf16 v[44:47], v[144:147], v[192:195], v[44:47]
	v_mfma_f32_16x16x32_bf16 v[40:43], v[160:163], v[192:195], v[40:43]
	v_mfma_f32_16x16x32_bf16 v[28:31], v[144:147], v[200:203], v[28:31]
	v_mfma_f32_16x16x32_bf16 v[24:27], v[160:163], v[200:203], v[24:27]
	v_mfma_f32_16x16x32_bf16 v[12:15], v[144:147], v[208:211], v[12:15]
	v_mfma_f32_16x16x32_bf16 v[8:11], v[160:163], v[208:211], v[8:11]
	v_mfma_f32_16x16x32_bf16 v[60:63], v[148:151], v[188:191], v[60:63]
	v_mfma_f32_16x16x32_bf16 v[56:59], v[164:167], v[188:191], v[56:59]
	v_mfma_f32_16x16x32_bf16 v[44:47], v[148:151], v[196:199], v[44:47]
	v_mfma_f32_16x16x32_bf16 v[40:43], v[164:167], v[196:199], v[40:43]
	v_mfma_f32_16x16x32_bf16 v[28:31], v[148:151], v[204:207], v[28:31]
	v_mfma_f32_16x16x32_bf16 v[24:27], v[164:167], v[204:207], v[24:27]
	v_mfma_f32_16x16x32_bf16 v[12:15], v[148:151], v[212:215], v[12:15]
	v_mfma_f32_16x16x32_bf16 v[8:11], v[164:167], v[212:215], v[8:11]
	v_mfma_f32_16x16x32_bf16 v[52:55], v[168:171], v[184:187], v[52:55]
	v_mfma_f32_16x16x32_bf16 v[48:51], v[176:179], v[184:187], v[48:51]
	v_mfma_f32_16x16x32_bf16 v[36:39], v[168:171], v[192:195], v[36:39]
	v_mfma_f32_16x16x32_bf16 v[32:35], v[176:179], v[192:195], v[32:35]
	v_mfma_f32_16x16x32_bf16 v[20:23], v[168:171], v[200:203], v[20:23]
	v_mfma_f32_16x16x32_bf16 v[16:19], v[176:179], v[200:203], v[16:19]
	v_mfma_f32_16x16x32_bf16 v[4:7], v[168:171], v[208:211], v[4:7]
	v_mfma_f32_16x16x32_bf16 v[0:3], v[176:179], v[208:211], v[0:3]
	v_mfma_f32_16x16x32_bf16 v[52:55], v[172:175], v[188:191], v[52:55]
	v_mfma_f32_16x16x32_bf16 v[48:51], v[180:183], v[188:191], v[48:51]
	v_mfma_f32_16x16x32_bf16 v[36:39], v[172:175], v[196:199], v[36:39]
	v_mfma_f32_16x16x32_bf16 v[32:35], v[180:183], v[196:199], v[32:35]
	v_mfma_f32_16x16x32_bf16 v[20:23], v[172:175], v[204:207], v[20:23]
	v_mfma_f32_16x16x32_bf16 v[16:19], v[180:183], v[204:207], v[16:19]
	v_mfma_f32_16x16x32_bf16 v[4:7], v[172:175], v[212:215], v[4:7]
	v_mfma_f32_16x16x32_bf16 v[0:3], v[180:183], v[212:215], v[0:3]
	s_setprio 0
	s_add_i32 s37, s37, 2
	s_add_u32 s34, s34, 0x100
	s_addc_u32 s35, s35, 0
	s_add_u32 s33, s33, 0x100
	s_addc_u32 s36, s36, 0
	s_cmp_gt_u32 s37, 5
	s_barrier
	s_cbranch_scc0 .LBB0_1417
	s_and_b64 vcc, exec, s[14:15]
	s_cbranch_vccz .LBB0_1420
	s_barrier

.LBB0_1493:
	ds_read_b128 v[140:143], v149
	ds_read_b128 v[152:155], v149 offset:1024
	ds_read_b128 v[156:159], v149 offset:2048
	ds_read_b128 v[160:163], v149 offset:3072
	ds_read_b128 v[164:167], v150
	ds_read_b128 v[168:171], v150 offset:1024
	ds_read_b128 v[172:175], v150 offset:2048
	ds_read_b128 v[176:179], v150 offset:3072
	s_add_u32 s3, s86, 0xfff80080
	s_addc_u32 s33, s87, -1
	s_cmp_eq_u32 s27, 28
	s_cselect_b32 s89, s0, s33
	s_cselect_b32 s88, s1, s3
	s_cselect_b32 s81, s15, s24
	s_cselect_b32 s80, s17, s19
	s_add_i32 m0, s30, 0xc000
	ds_read_b128 v[180:183], v151
	ds_read_b128 v[184:187], v151 offset:1024
	ds_read_b128 v[188:191], v151 offset:2048
	ds_read_b128 v[192:195], v151 offset:3072
	ds_read_b128 v[196:199], v151 offset:4096
	ds_read_b128 v[200:203], v151 offset:5120
	ds_read_b128 v[204:207], v151 offset:6144
	ds_read_b128 v[208:211], v151 offset:7168
	global_load_lds_dwordx4 v132, s[86:87]
	s_add_i32 m0, s30, 0xe000
	s_nop 0
	global_load_lds_dwordx4 v134, s[86:87]
	s_waitcnt vmcnt(8)
	s_waitcnt lgkmcnt(0)
	s_barrier
	s_setprio 1
	v_mfma_f32_16x16x32_bf16 v[124:127], v[140:143], v[180:183], v[124:127]
	v_mfma_f32_16x16x32_bf16 v[120:123], v[156:159], v[180:183], v[120:123]
	v_mfma_f32_16x16x32_bf16 v[108:111], v[140:143], v[188:191], v[108:111]
	v_mfma_f32_16x16x32_bf16 v[104:107], v[156:159], v[188:191], v[104:107]
	v_mfma_f32_16x16x32_bf16 v[92:95], v[140:143], v[196:199], v[92:95]
	v_mfma_f32_16x16x32_bf16 v[88:91], v[156:159], v[196:199], v[88:91]
	v_mfma_f32_16x16x32_bf16 v[76:79], v[140:143], v[204:207], v[76:79]
	v_mfma_f32_16x16x32_bf16 v[72:75], v[156:159], v[204:207], v[72:75]
	v_mfma_f32_16x16x32_bf16 v[124:127], v[152:155], v[184:187], v[124:127]
	v_mfma_f32_16x16x32_bf16 v[120:123], v[160:163], v[184:187], v[120:123]
	v_mfma_f32_16x16x32_bf16 v[108:111], v[152:155], v[192:195], v[108:111]
	v_mfma_f32_16x16x32_bf16 v[104:107], v[160:163], v[192:195], v[104:107]
	v_mfma_f32_16x16x32_bf16 v[92:95], v[152:155], v[200:203], v[92:95]
	v_mfma_f32_16x16x32_bf16 v[88:91], v[160:163], v[200:203], v[88:91]
	v_mfma_f32_16x16x32_bf16 v[76:79], v[152:155], v[208:211], v[76:79]
	v_mfma_f32_16x16x32_bf16 v[72:75], v[160:163], v[208:211], v[72:75]
	v_mfma_f32_16x16x32_bf16 v[116:119], v[164:167], v[180:183], v[116:119]
	v_mfma_f32_16x16x32_bf16 v[112:115], v[172:175], v[180:183], v[112:115]
	v_mfma_f32_16x16x32_bf16 v[100:103], v[164:167], v[188:191], v[100:103]
	v_mfma_f32_16x16x32_bf16 v[96:99], v[172:175], v[188:191], v[96:99]
	v_mfma_f32_16x16x32_bf16 v[84:87], v[164:167], v[196:199], v[84:87]
	v_mfma_f32_16x16x32_bf16 v[80:83], v[172:175], v[196:199], v[80:83]
	v_mfma_f32_16x16x32_bf16 v[68:71], v[164:167], v[204:207], v[68:71]
	v_mfma_f32_16x16x32_bf16 v[64:67], v[172:175], v[204:207], v[64:67]
	v_mfma_f32_16x16x32_bf16 v[116:119], v[168:171], v[184:187], v[116:119]
	v_mfma_f32_16x16x32_bf16 v[112:115], v[176:179], v[184:187], v[112:115]
	v_mfma_f32_16x16x32_bf16 v[100:103], v[168:171], v[192:195], v[100:103]
	v_mfma_f32_16x16x32_bf16 v[96:99], v[176:179], v[192:195], v[96:99]
	v_mfma_f32_16x16x32_bf16 v[84:87], v[168:171], v[200:203], v[84:87]
	v_mfma_f32_16x16x32_bf16 v[80:83], v[176:179], v[200:203], v[80:83]
	v_mfma_f32_16x16x32_bf16 v[68:71], v[168:171], v[208:211], v[68:71]
	v_mfma_f32_16x16x32_bf16 v[64:67], v[176:179], v[208:211], v[64:67]
	s_setprio 0
	s_barrier
	s_add_i32 s3, s59, s25
	s_mov_b32 m0, s3
	ds_read_b128 v[180:183], v151 offset:16384
	ds_read_b128 v[184:187], v151 offset:17408
	ds_read_b128 v[188:191], v151 offset:18432
	ds_read_b128 v[192:195], v151 offset:19456
	ds_read_b128 v[196:199], v151 offset:20480
	ds_read_b128 v[200:203], v151 offset:21504
	ds_read_b128 v[204:207], v151 offset:22528
	ds_read_b128 v[208:211], v151 offset:23552
	global_load_lds_dwordx4 v128, s[80:81]
	s_add_i32 m0, s3, 0x2000
	s_add_u32 s36, s80, 0x80000
	s_addc_u32 s37, s81, 0
	s_add_i32 s3, s68, s25
	global_load_lds_dwordx4 v130, s[80:81]
	s_mov_b32 m0, s3
	s_nop 0
	global_load_lds_dwordx4 v128, s[36:37]
	s_add_i32 m0, s3, 0x2000
	s_nop 0
	global_load_lds_dwordx4 v130, s[36:37]
	s_mov_b32 m0, s30
	s_nop 0
	global_load_lds_dwordx4 v128, s[88:89]
	s_mov_b32 m0, s31
	s_nop 0
	global_load_lds_dwordx4 v130, s[88:89]
	s_waitcnt vmcnt(8)
	s_waitcnt lgkmcnt(0)
	s_barrier
	s_setprio 1
	v_mfma_f32_16x16x32_bf16 v[60:63], v[140:143], v[180:183], v[60:63]
	v_mfma_f32_16x16x32_bf16 v[56:59], v[156:159], v[180:183], v[56:59]
	v_mfma_f32_16x16x32_bf16 v[44:47], v[140:143], v[188:191], v[44:47]
	v_mfma_f32_16x16x32_bf16 v[40:43], v[156:159], v[188:191], v[40:43]
	v_mfma_f32_16x16x32_bf16 v[28:31], v[140:143], v[196:199], v[28:31]
	v_mfma_f32_16x16x32_bf16 v[24:27], v[156:159], v[196:199], v[24:27]
	v_mfma_f32_16x16x32_bf16 v[12:15], v[140:143], v[204:207], v[12:15]
	v_mfma_f32_16x16x32_bf16 v[8:11], v[156:159], v[204:207], v[8:11]
	v_mfma_f32_16x16x32_bf16 v[60:63], v[152:155], v[184:187], v[60:63]
	v_mfma_f32_16x16x32_bf16 v[56:59], v[160:163], v[184:187], v[56:59]
	v_mfma_f32_16x16x32_bf16 v[44:47], v[152:155], v[192:195], v[44:47]
	v_mfma_f32_16x16x32_bf16 v[40:43], v[160:163], v[192:195], v[40:43]
	v_mfma_f32_16x16x32_bf16 v[28:31], v[152:155], v[200:203], v[28:31]
	v_mfma_f32_16x16x32_bf16 v[24:27], v[160:163], v[200:203], v[24:27]
	v_mfma_f32_16x16x32_bf16 v[12:15], v[152:155], v[208:211], v[12:15]
	v_mfma_f32_16x16x32_bf16 v[8:11], v[160:163], v[208:211], v[8:11]
	v_mfma_f32_16x16x32_bf16 v[52:55], v[164:167], v[180:183], v[52:55]
	v_mfma_f32_16x16x32_bf16 v[48:51], v[172:175], v[180:183], v[48:51]
	v_mfma_f32_16x16x32_bf16 v[36:39], v[164:167], v[188:191], v[36:39]
	v_mfma_f32_16x16x32_bf16 v[32:35], v[172:175], v[188:191], v[32:35]
	v_mfma_f32_16x16x32_bf16 v[20:23], v[164:167], v[196:199], v[20:23]
	v_mfma_f32_16x16x32_bf16 v[16:19], v[172:175], v[196:199], v[16:19]
	v_mfma_f32_16x16x32_bf16 v[4:7], v[164:167], v[204:207], v[4:7]
	v_mfma_f32_16x16x32_bf16 v[0:3], v[172:175], v[204:207], v[0:3]
	v_mfma_f32_16x16x32_bf16 v[52:55], v[168:171], v[184:187], v[52:55]
	v_mfma_f32_16x16x32_bf16 v[48:51], v[176:179], v[184:187], v[48:51]
	v_mfma_f32_16x16x32_bf16 v[36:39], v[168:171], v[192:195], v[36:39]
	v_mfma_f32_16x16x32_bf16 v[32:35], v[176:179], v[192:195], v[32:35]
	v_mfma_f32_16x16x32_bf16 v[20:23], v[168:171], v[200:203], v[20:23]
	v_mfma_f32_16x16x32_bf16 v[16:19], v[176:179], v[200:203], v[16:19]
	v_mfma_f32_16x16x32_bf16 v[4:7], v[168:171], v[208:211], v[4:7]
	v_mfma_f32_16x16x32_bf16 v[0:3], v[176:179], v[208:211], v[0:3]
	s_setprio 0
	s_barrier
	s_add_i32 s3, 0, 0x18000
	s_add_i32 s33, 0, 0x1c000
	v_add_u32_e32 v160, s3, v147
	v_add_u32_e32 v176, s33, v147
	ds_read_b128 v[140:143], v160
	ds_read_b128 v[152:155], v160 offset:1024
	ds_read_b128 v[156:159], v160 offset:2048
	ds_read_b128 v[160:163], v160 offset:3072
	ds_read_b128 v[164:167], v176
	ds_read_b128 v[168:171], v176 offset:1024
	ds_read_b128 v[172:175], v176 offset:2048
	ds_read_b128 v[176:179], v176 offset:3072
	s_add_u32 s36, s88, 0x80000
	s_addc_u32 s37, s89, 0
	s_mov_b32 m0, s52
	ds_read_b128 v[180:183], v151 offset:32768
	ds_read_b128 v[184:187], v151 offset:33792
	ds_read_b128 v[188:191], v151 offset:34816
	ds_read_b128 v[192:195], v151 offset:35840
	ds_read_b128 v[196:199], v151 offset:36864
	ds_read_b128 v[200:203], v151 offset:37888
	ds_read_b128 v[204:207], v151 offset:38912
	ds_read_b128 v[208:211], v151 offset:39936
	global_load_lds_dwordx4 v128, s[36:37]
	v_lshl_add_u64 v[218:219], s[36:37], 0, v[130:131]
	s_mov_b32 m0, s53
	s_nop 0
	global_load_lds_dwordx4 v[218:219], off
	s_waitcnt vmcnt(8)
	s_waitcnt lgkmcnt(0)
	s_barrier
	s_setprio 1
	v_mfma_f32_16x16x32_bf16 v[124:127], v[140:143], v[180:183], v[124:127]
	v_mfma_f32_16x16x32_bf16 v[120:123], v[156:159], v[180:183], v[120:123]
	v_mfma_f32_16x16x32_bf16 v[108:111], v[140:143], v[188:191], v[108:111]
	v_mfma_f32_16x16x32_bf16 v[104:107], v[156:159], v[188:191], v[104:107]
	v_mfma_f32_16x16x32_bf16 v[92:95], v[140:143], v[196:199], v[92:95]
	v_mfma_f32_16x16x32_bf16 v[88:91], v[156:159], v[196:199], v[88:91]
	v_mfma_f32_16x16x32_bf16 v[76:79], v[140:143], v[204:207], v[76:79]
	v_mfma_f32_16x16x32_bf16 v[72:75], v[156:159], v[204:207], v[72:75]
	v_mfma_f32_16x16x32_bf16 v[124:127], v[152:155], v[184:187], v[124:127]
	v_mfma_f32_16x16x32_bf16 v[120:123], v[160:163], v[184:187], v[120:123]
	v_mfma_f32_16x16x32_bf16 v[108:111], v[152:155], v[192:195], v[108:111]
	v_mfma_f32_16x16x32_bf16 v[104:107], v[160:163], v[192:195], v[104:107]
	v_mfma_f32_16x16x32_bf16 v[92:95], v[152:155], v[200:203], v[92:95]
	v_mfma_f32_16x16x32_bf16 v[88:91], v[160:163], v[200:203], v[88:91]
	v_mfma_f32_16x16x32_bf16 v[76:79], v[152:155], v[208:211], v[76:79]
	v_mfma_f32_16x16x32_bf16 v[72:75], v[160:163], v[208:211], v[72:75]
	v_mfma_f32_16x16x32_bf16 v[116:119], v[164:167], v[180:183], v[116:119]
	v_mfma_f32_16x16x32_bf16 v[112:115], v[172:175], v[180:183], v[112:115]
	v_mfma_f32_16x16x32_bf16 v[100:103], v[164:167], v[188:191], v[100:103]
	v_mfma_f32_16x16x32_bf16 v[96:99], v[172:175], v[188:191], v[96:99]
	v_mfma_f32_16x16x32_bf16 v[84:87], v[164:167], v[196:199], v[84:87]
	v_mfma_f32_16x16x32_bf16 v[80:83], v[172:175], v[196:199], v[80:83]
	v_mfma_f32_16x16x32_bf16 v[68:71], v[164:167], v[204:207], v[68:71]
	v_mfma_f32_16x16x32_bf16 v[64:67], v[172:175], v[204:207], v[64:67]
	v_mfma_f32_16x16x32_bf16 v[116:119], v[168:171], v[184:187], v[116:119]
	v_mfma_f32_16x16x32_bf16 v[112:115], v[176:179], v[184:187], v[112:115]
	v_mfma_f32_16x16x32_bf16 v[100:103], v[168:171], v[192:195], v[100:103]
	v_mfma_f32_16x16x32_bf16 v[96:99], v[176:179], v[192:195], v[96:99]
	v_mfma_f32_16x16x32_bf16 v[84:87], v[168:171], v[200:203], v[84:87]
	v_mfma_f32_16x16x32_bf16 v[80:83], v[176:179], v[200:203], v[80:83]
	v_mfma_f32_16x16x32_bf16 v[68:71], v[168:171], v[208:211], v[68:71]
	v_mfma_f32_16x16x32_bf16 v[64:67], v[176:179], v[208:211], v[64:67]
	s_setprio 0
	s_barrier
	s_add_i32 s3, s3, s25
	s_add_u32 s36, s80, 0x80
	s_addc_u32 s37, s81, 0
	s_mov_b32 m0, s3
	ds_read_b128 v[180:183], v151 offset:49152
	ds_read_b128 v[184:187], v151 offset:50176
	ds_read_b128 v[188:191], v151 offset:51200
	ds_read_b128 v[192:195], v151 offset:52224
	ds_read_b128 v[196:199], v151 offset:53248
	ds_read_b128 v[200:203], v151 offset:54272
	ds_read_b128 v[204:207], v151 offset:55296
	ds_read_b128 v[208:211], v151 offset:56320
	global_load_lds_dwordx4 v128, s[36:37]
	s_add_i32 m0, s3, 0x2000
	s_add_i32 s3, s33, s25
	global_load_lds_dwordx4 v130, s[36:37]
	s_add_u32 s36, s36, 0x80000
	s_addc_u32 s37, s37, 0
	s_mov_b32 m0, s3
	s_nop 0
	global_load_lds_dwordx4 v128, s[36:37]
	s_add_i32 m0, s3, 0x2000
	s_nop 0
	global_load_lds_dwordx4 v130, s[36:37]
	s_add_u32 s88, s88, 0x80
	s_addc_u32 s89, s89, 0
	s_mov_b32 m0, s57
	s_nop 0
	global_load_lds_dwordx4 v128, s[88:89]
	s_mov_b32 m0, s58
	s_nop 0
	global_load_lds_dwordx4 v130, s[88:89]
	s_waitcnt vmcnt(8)
	s_waitcnt lgkmcnt(0)
	s_barrier
	s_setprio 1
	v_mfma_f32_16x16x32_bf16 v[60:63], v[140:143], v[180:183], v[60:63]
	v_mfma_f32_16x16x32_bf16 v[56:59], v[156:159], v[180:183], v[56:59]
	v_mfma_f32_16x16x32_bf16 v[44:47], v[140:143], v[188:191], v[44:47]
	v_mfma_f32_16x16x32_bf16 v[40:43], v[156:159], v[188:191], v[40:43]
	v_mfma_f32_16x16x32_bf16 v[28:31], v[140:143], v[196:199], v[28:31]
	v_mfma_f32_16x16x32_bf16 v[24:27], v[156:159], v[196:199], v[24:27]
	v_mfma_f32_16x16x32_bf16 v[12:15], v[140:143], v[204:207], v[12:15]
	v_mfma_f32_16x16x32_bf16 v[8:11], v[156:159], v[204:207], v[8:11]
	v_mfma_f32_16x16x32_bf16 v[60:63], v[152:155], v[184:187], v[60:63]
	v_mfma_f32_16x16x32_bf16 v[56:59], v[160:163], v[184:187], v[56:59]
	v_mfma_f32_16x16x32_bf16 v[44:47], v[152:155], v[192:195], v[44:47]
	v_mfma_f32_16x16x32_bf16 v[40:43], v[160:163], v[192:195], v[40:43]
	v_mfma_f32_16x16x32_bf16 v[28:31], v[152:155], v[200:203], v[28:31]
	v_mfma_f32_16x16x32_bf16 v[24:27], v[160:163], v[200:203], v[24:27]
	v_mfma_f32_16x16x32_bf16 v[12:15], v[152:155], v[208:211], v[12:15]
	v_mfma_f32_16x16x32_bf16 v[8:11], v[160:163], v[208:211], v[8:11]
	v_mfma_f32_16x16x32_bf16 v[52:55], v[164:167], v[180:183], v[52:55]
	v_mfma_f32_16x16x32_bf16 v[48:51], v[172:175], v[180:183], v[48:51]
	v_mfma_f32_16x16x32_bf16 v[36:39], v[164:167], v[188:191], v[36:39]
	v_mfma_f32_16x16x32_bf16 v[32:35], v[172:175], v[188:191], v[32:35]
	v_mfma_f32_16x16x32_bf16 v[20:23], v[164:167], v[196:199], v[20:23]
	v_mfma_f32_16x16x32_bf16 v[16:19], v[172:175], v[196:199], v[16:19]
	v_mfma_f32_16x16x32_bf16 v[4:7], v[164:167], v[204:207], v[4:7]
	v_mfma_f32_16x16x32_bf16 v[0:3], v[172:175], v[204:207], v[0:3]
	v_mfma_f32_16x16x32_bf16 v[52:55], v[168:171], v[184:187], v[52:55]
	v_mfma_f32_16x16x32_bf16 v[48:51], v[176:179], v[184:187], v[48:51]
	v_mfma_f32_16x16x32_bf16 v[36:39], v[168:171], v[192:195], v[36:39]
	v_mfma_f32_16x16x32_bf16 v[32:35], v[176:179], v[192:195], v[32:35]
	v_mfma_f32_16x16x32_bf16 v[20:23], v[168:171], v[200:203], v[20:23]
	v_mfma_f32_16x16x32_bf16 v[16:19], v[176:179], v[200:203], v[16:19]
	v_mfma_f32_16x16x32_bf16 v[4:7], v[168:171], v[208:211], v[4:7]
	v_mfma_f32_16x16x32_bf16 v[0:3], v[176:179], v[208:211], v[0:3]
	s_setprio 0
	s_add_i32 s27, s27, 2
	s_add_u32 s86, s86, 0x100
	s_addc_u32 s87, s87, 0
	s_add_u32 s19, s19, 0x100
	s_addc_u32 s24, s24, 0
	s_cmp_gt_u32 s27, 29
	s_barrier
	s_cbranch_scc0 .LBB0_1493
	s_and_b64 vcc, exec, s[12:13]
	s_cbranch_vccz .LBB0_1496
	s_barrier

.LBB0_1624:
	ds_read_b128 v[154:157], v150
	ds_read_b128 v[158:161], v150 offset:1024
	ds_read_b128 v[162:165], v150 offset:2048
	ds_read_b128 v[166:169], v150 offset:3072
	ds_read_b128 v[170:173], v151
	ds_read_b128 v[174:177], v151 offset:1024
	ds_read_b128 v[178:181], v151 offset:2048
	ds_read_b128 v[182:185], v151 offset:3072
	s_add_u32 s3, s88, 0xfff80080
	s_addc_u32 s42, s89, -1
	s_cmp_eq_u32 s37, 28
	s_cselect_b32 s93, s0, s42
	s_cselect_b32 s92, s1, s3
	s_cselect_b32 s91, s27, s36
	s_cselect_b32 s90, s33, s35
	s_add_i32 m0, s9, 0xc000
	ds_read_b128 v[186:189], v152
	ds_read_b128 v[190:193], v152 offset:1024
	ds_read_b128 v[194:197], v152 offset:2048
	ds_read_b128 v[198:201], v152 offset:3072
	ds_read_b128 v[202:205], v152 offset:4096
	ds_read_b128 v[206:209], v152 offset:5120
	ds_read_b128 v[210:213], v152 offset:6144
	ds_read_b128 v[214:217], v152 offset:7168
	global_load_lds_dwordx4 v138, s[88:89]
	s_add_i32 m0, s9, 0xe000
	s_nop 0
	global_load_lds_dwordx4 v140, s[88:89]
	s_waitcnt vmcnt(8)
	s_waitcnt lgkmcnt(0)
	s_barrier
	s_setprio 1
	v_mfma_f32_16x16x32_bf16 v[124:127], v[154:157], v[186:189], v[124:127]
	v_mfma_f32_16x16x32_bf16 v[120:123], v[162:165], v[186:189], v[120:123]
	v_mfma_f32_16x16x32_bf16 v[108:111], v[154:157], v[194:197], v[108:111]
	v_mfma_f32_16x16x32_bf16 v[104:107], v[162:165], v[194:197], v[104:107]
	v_mfma_f32_16x16x32_bf16 v[92:95], v[154:157], v[202:205], v[92:95]
	v_mfma_f32_16x16x32_bf16 v[88:91], v[162:165], v[202:205], v[88:91]
	v_mfma_f32_16x16x32_bf16 v[76:79], v[154:157], v[210:213], v[76:79]
	v_mfma_f32_16x16x32_bf16 v[72:75], v[162:165], v[210:213], v[72:75]
	v_mfma_f32_16x16x32_bf16 v[124:127], v[158:161], v[190:193], v[124:127]
	v_mfma_f32_16x16x32_bf16 v[120:123], v[166:169], v[190:193], v[120:123]
	v_mfma_f32_16x16x32_bf16 v[108:111], v[158:161], v[198:201], v[108:111]
	v_mfma_f32_16x16x32_bf16 v[104:107], v[166:169], v[198:201], v[104:107]
	v_mfma_f32_16x16x32_bf16 v[92:95], v[158:161], v[206:209], v[92:95]
	v_mfma_f32_16x16x32_bf16 v[88:91], v[166:169], v[206:209], v[88:91]
	v_mfma_f32_16x16x32_bf16 v[76:79], v[158:161], v[214:217], v[76:79]
	v_mfma_f32_16x16x32_bf16 v[72:75], v[166:169], v[214:217], v[72:75]
	v_mfma_f32_16x16x32_bf16 v[116:119], v[170:173], v[186:189], v[116:119]
	v_mfma_f32_16x16x32_bf16 v[112:115], v[178:181], v[186:189], v[112:115]
	v_mfma_f32_16x16x32_bf16 v[100:103], v[170:173], v[194:197], v[100:103]
	v_mfma_f32_16x16x32_bf16 v[96:99], v[178:181], v[194:197], v[96:99]
	v_mfma_f32_16x16x32_bf16 v[84:87], v[170:173], v[202:205], v[84:87]
	v_mfma_f32_16x16x32_bf16 v[80:83], v[178:181], v[202:205], v[80:83]
	v_mfma_f32_16x16x32_bf16 v[68:71], v[170:173], v[210:213], v[68:71]
	v_mfma_f32_16x16x32_bf16 v[64:67], v[178:181], v[210:213], v[64:67]
	v_mfma_f32_16x16x32_bf16 v[116:119], v[174:177], v[190:193], v[116:119]
	v_mfma_f32_16x16x32_bf16 v[112:115], v[182:185], v[190:193], v[112:115]
	v_mfma_f32_16x16x32_bf16 v[100:103], v[174:177], v[198:201], v[100:103]
	v_mfma_f32_16x16x32_bf16 v[96:99], v[182:185], v[198:201], v[96:99]
	v_mfma_f32_16x16x32_bf16 v[84:87], v[174:177], v[206:209], v[84:87]
	v_mfma_f32_16x16x32_bf16 v[80:83], v[182:185], v[206:209], v[80:83]
	v_mfma_f32_16x16x32_bf16 v[68:71], v[174:177], v[214:217], v[68:71]
	v_mfma_f32_16x16x32_bf16 v[64:67], v[182:185], v[214:217], v[64:67]
	s_setprio 0
	s_barrier
	s_add_i32 s3, s48, s8
	s_mov_b32 m0, s3
	ds_read_b128 v[186:189], v152 offset:16384
	ds_read_b128 v[190:193], v152 offset:17408
	ds_read_b128 v[194:197], v152 offset:18432
	ds_read_b128 v[198:201], v152 offset:19456
	ds_read_b128 v[202:205], v152 offset:20480
	ds_read_b128 v[206:209], v152 offset:21504
	ds_read_b128 v[210:213], v152 offset:22528
	ds_read_b128 v[214:217], v152 offset:23552
	global_load_lds_dwordx4 v130, s[90:91]
	s_add_i32 m0, s3, 0x2000
	s_add_u32 s42, s90, 0x80000
	s_addc_u32 s43, s91, 0
	s_add_i32 s3, s49, s8
	global_load_lds_dwordx4 v134, s[90:91]
	s_mov_b32 m0, s3
	s_nop 0
	global_load_lds_dwordx4 v130, s[42:43]
	s_add_i32 m0, s3, 0x2000
	s_nop 0
	global_load_lds_dwordx4 v134, s[42:43]
	s_mov_b32 m0, s9
	s_nop 0
	global_load_lds_dwordx4 v128, s[92:93]
	s_mov_b32 m0, s18
	s_nop 0
	global_load_lds_dwordx4 v132, s[92:93]
	s_waitcnt vmcnt(8)
	s_waitcnt lgkmcnt(0)
	s_barrier
	s_setprio 1
	v_mfma_f32_16x16x32_bf16 v[60:63], v[154:157], v[186:189], v[60:63]
	v_mfma_f32_16x16x32_bf16 v[56:59], v[162:165], v[186:189], v[56:59]
	v_mfma_f32_16x16x32_bf16 v[44:47], v[154:157], v[194:197], v[44:47]
	v_mfma_f32_16x16x32_bf16 v[40:43], v[162:165], v[194:197], v[40:43]
	v_mfma_f32_16x16x32_bf16 v[28:31], v[154:157], v[202:205], v[28:31]
	v_mfma_f32_16x16x32_bf16 v[24:27], v[162:165], v[202:205], v[24:27]
	v_mfma_f32_16x16x32_bf16 v[12:15], v[154:157], v[210:213], v[12:15]
	v_mfma_f32_16x16x32_bf16 v[8:11], v[162:165], v[210:213], v[8:11]
	v_mfma_f32_16x16x32_bf16 v[60:63], v[158:161], v[190:193], v[60:63]
	v_mfma_f32_16x16x32_bf16 v[56:59], v[166:169], v[190:193], v[56:59]
	v_mfma_f32_16x16x32_bf16 v[44:47], v[158:161], v[198:201], v[44:47]
	v_mfma_f32_16x16x32_bf16 v[40:43], v[166:169], v[198:201], v[40:43]
	v_mfma_f32_16x16x32_bf16 v[28:31], v[158:161], v[206:209], v[28:31]
	v_mfma_f32_16x16x32_bf16 v[24:27], v[166:169], v[206:209], v[24:27]
	v_mfma_f32_16x16x32_bf16 v[12:15], v[158:161], v[214:217], v[12:15]
	v_mfma_f32_16x16x32_bf16 v[8:11], v[166:169], v[214:217], v[8:11]
	v_mfma_f32_16x16x32_bf16 v[52:55], v[170:173], v[186:189], v[52:55]
	v_mfma_f32_16x16x32_bf16 v[48:51], v[178:181], v[186:189], v[48:51]
	v_mfma_f32_16x16x32_bf16 v[36:39], v[170:173], v[194:197], v[36:39]
	v_mfma_f32_16x16x32_bf16 v[32:35], v[178:181], v[194:197], v[32:35]
	v_mfma_f32_16x16x32_bf16 v[20:23], v[170:173], v[202:205], v[20:23]
	v_mfma_f32_16x16x32_bf16 v[16:19], v[178:181], v[202:205], v[16:19]
	v_mfma_f32_16x16x32_bf16 v[4:7], v[170:173], v[210:213], v[4:7]
	v_mfma_f32_16x16x32_bf16 v[0:3], v[178:181], v[210:213], v[0:3]
	v_mfma_f32_16x16x32_bf16 v[52:55], v[174:177], v[190:193], v[52:55]
	v_mfma_f32_16x16x32_bf16 v[48:51], v[182:185], v[190:193], v[48:51]
	v_mfma_f32_16x16x32_bf16 v[36:39], v[174:177], v[198:201], v[36:39]
	v_mfma_f32_16x16x32_bf16 v[32:35], v[182:185], v[198:201], v[32:35]
	v_mfma_f32_16x16x32_bf16 v[20:23], v[174:177], v[206:209], v[20:23]
	v_mfma_f32_16x16x32_bf16 v[16:19], v[182:185], v[206:209], v[16:19]
	v_mfma_f32_16x16x32_bf16 v[4:7], v[174:177], v[214:217], v[4:7]
	v_mfma_f32_16x16x32_bf16 v[0:3], v[182:185], v[214:217], v[0:3]
	s_setprio 0
	s_barrier
	s_add_i32 s3, 0, 0x18000
	v_add_u32_e32 v153, s3, v149
	s_add_i32 s44, 0, 0x1c000
	ds_read_b128 v[154:157], v153
	ds_read_b128 v[158:161], v153 offset:1024
	ds_read_b128 v[162:165], v153 offset:2048
	ds_read_b128 v[166:169], v153 offset:3072
	v_add_u32_e32 v153, s44, v149
	ds_read_b128 v[170:173], v153
	ds_read_b128 v[174:177], v153 offset:1024
	ds_read_b128 v[178:181], v153 offset:2048
	ds_read_b128 v[182:185], v153 offset:3072
	s_add_u32 s42, s92, 0x80000
	s_addc_u32 s43, s93, 0
	s_mov_b32 m0, s19
	ds_read_b128 v[186:189], v152 offset:32768
	ds_read_b128 v[190:193], v152 offset:33792
	ds_read_b128 v[194:197], v152 offset:34816
	ds_read_b128 v[198:201], v152 offset:35840
	ds_read_b128 v[202:205], v152 offset:36864
	ds_read_b128 v[206:209], v152 offset:37888
	ds_read_b128 v[210:213], v152 offset:38912
	ds_read_b128 v[214:217], v152 offset:39936
	global_load_lds_dwordx4 v128, s[42:43]
	v_lshl_add_u64 v[224:225], s[42:43], 0, v[132:133]
	s_mov_b32 m0, s25
	s_nop 0
	global_load_lds_dwordx4 v[224:225], off
	s_waitcnt vmcnt(8)
	s_waitcnt lgkmcnt(0)
	s_barrier
	s_setprio 1
	v_mfma_f32_16x16x32_bf16 v[124:127], v[154:157], v[186:189], v[124:127]
	v_mfma_f32_16x16x32_bf16 v[120:123], v[162:165], v[186:189], v[120:123]
	v_mfma_f32_16x16x32_bf16 v[108:111], v[154:157], v[194:197], v[108:111]
	v_mfma_f32_16x16x32_bf16 v[104:107], v[162:165], v[194:197], v[104:107]
	v_mfma_f32_16x16x32_bf16 v[92:95], v[154:157], v[202:205], v[92:95]
	v_mfma_f32_16x16x32_bf16 v[88:91], v[162:165], v[202:205], v[88:91]
	v_mfma_f32_16x16x32_bf16 v[76:79], v[154:157], v[210:213], v[76:79]
	v_mfma_f32_16x16x32_bf16 v[72:75], v[162:165], v[210:213], v[72:75]
	v_mfma_f32_16x16x32_bf16 v[124:127], v[158:161], v[190:193], v[124:127]
	v_mfma_f32_16x16x32_bf16 v[120:123], v[166:169], v[190:193], v[120:123]
	v_mfma_f32_16x16x32_bf16 v[108:111], v[158:161], v[198:201], v[108:111]
	v_mfma_f32_16x16x32_bf16 v[104:107], v[166:169], v[198:201], v[104:107]
	v_mfma_f32_16x16x32_bf16 v[92:95], v[158:161], v[206:209], v[92:95]
	v_mfma_f32_16x16x32_bf16 v[88:91], v[166:169], v[206:209], v[88:91]
	v_mfma_f32_16x16x32_bf16 v[76:79], v[158:161], v[214:217], v[76:79]
	v_mfma_f32_16x16x32_bf16 v[72:75], v[166:169], v[214:217], v[72:75]
	v_mfma_f32_16x16x32_bf16 v[116:119], v[170:173], v[186:189], v[116:119]
	v_mfma_f32_16x16x32_bf16 v[112:115], v[178:181], v[186:189], v[112:115]
	v_mfma_f32_16x16x32_bf16 v[100:103], v[170:173], v[194:197], v[100:103]
	v_mfma_f32_16x16x32_bf16 v[96:99], v[178:181], v[194:197], v[96:99]
	v_mfma_f32_16x16x32_bf16 v[84:87], v[170:173], v[202:205], v[84:87]
	v_mfma_f32_16x16x32_bf16 v[80:83], v[178:181], v[202:205], v[80:83]
	v_mfma_f32_16x16x32_bf16 v[68:71], v[170:173], v[210:213], v[68:71]
	v_mfma_f32_16x16x32_bf16 v[64:67], v[178:181], v[210:213], v[64:67]
	v_mfma_f32_16x16x32_bf16 v[116:119], v[174:177], v[190:193], v[116:119]
	v_mfma_f32_16x16x32_bf16 v[112:115], v[182:185], v[190:193], v[112:115]
	v_mfma_f32_16x16x32_bf16 v[100:103], v[174:177], v[198:201], v[100:103]
	v_mfma_f32_16x16x32_bf16 v[96:99], v[182:185], v[198:201], v[96:99]
	v_mfma_f32_16x16x32_bf16 v[84:87], v[174:177], v[206:209], v[84:87]
	v_mfma_f32_16x16x32_bf16 v[80:83], v[182:185], v[206:209], v[80:83]
	v_mfma_f32_16x16x32_bf16 v[68:71], v[174:177], v[214:217], v[68:71]
	v_mfma_f32_16x16x32_bf16 v[64:67], v[182:185], v[214:217], v[64:67]
	s_setprio 0
	s_barrier
	s_add_i32 s3, s3, s8
	s_add_u32 s42, s90, 0x80
	s_addc_u32 s43, s91, 0
	s_mov_b32 m0, s3
	ds_read_b128 v[186:189], v152 offset:49152
	ds_read_b128 v[190:193], v152 offset:50176
	ds_read_b128 v[194:197], v152 offset:51200
	ds_read_b128 v[198:201], v152 offset:52224
	ds_read_b128 v[202:205], v152 offset:53248
	ds_read_b128 v[206:209], v152 offset:54272
	ds_read_b128 v[210:213], v152 offset:55296
	ds_read_b128 v[214:217], v152 offset:56320
	global_load_lds_dwordx4 v130, s[42:43]
	s_add_i32 m0, s3, 0x2000
	s_add_i32 s3, s44, s8
	global_load_lds_dwordx4 v134, s[42:43]
	s_add_u32 s42, s42, 0x80000
	s_addc_u32 s43, s43, 0
	s_mov_b32 m0, s3
	s_nop 0
	global_load_lds_dwordx4 v130, s[42:43]
	s_add_i32 m0, s3, 0x2000
	s_nop 0
	global_load_lds_dwordx4 v134, s[42:43]
	s_add_u32 s92, s92, 0x80
	s_addc_u32 s93, s93, 0
	s_mov_b32 m0, s30
	s_nop 0
	global_load_lds_dwordx4 v128, s[92:93]
	s_mov_b32 m0, s31
	s_nop 0
	global_load_lds_dwordx4 v132, s[92:93]
	s_waitcnt vmcnt(8)
	s_waitcnt lgkmcnt(0)
	s_barrier
	s_setprio 1
	v_mfma_f32_16x16x32_bf16 v[60:63], v[154:157], v[186:189], v[60:63]
	v_mfma_f32_16x16x32_bf16 v[56:59], v[162:165], v[186:189], v[56:59]
	v_mfma_f32_16x16x32_bf16 v[44:47], v[154:157], v[194:197], v[44:47]
	v_mfma_f32_16x16x32_bf16 v[40:43], v[162:165], v[194:197], v[40:43]
	v_mfma_f32_16x16x32_bf16 v[28:31], v[154:157], v[202:205], v[28:31]
	v_mfma_f32_16x16x32_bf16 v[24:27], v[162:165], v[202:205], v[24:27]
	v_mfma_f32_16x16x32_bf16 v[12:15], v[154:157], v[210:213], v[12:15]
	v_mfma_f32_16x16x32_bf16 v[8:11], v[162:165], v[210:213], v[8:11]
	v_mfma_f32_16x16x32_bf16 v[60:63], v[158:161], v[190:193], v[60:63]
	v_mfma_f32_16x16x32_bf16 v[56:59], v[166:169], v[190:193], v[56:59]
	v_mfma_f32_16x16x32_bf16 v[44:47], v[158:161], v[198:201], v[44:47]
	v_mfma_f32_16x16x32_bf16 v[40:43], v[166:169], v[198:201], v[40:43]
	v_mfma_f32_16x16x32_bf16 v[28:31], v[158:161], v[206:209], v[28:31]
	v_mfma_f32_16x16x32_bf16 v[24:27], v[166:169], v[206:209], v[24:27]
	v_mfma_f32_16x16x32_bf16 v[12:15], v[158:161], v[214:217], v[12:15]
	v_mfma_f32_16x16x32_bf16 v[8:11], v[166:169], v[214:217], v[8:11]
	v_mfma_f32_16x16x32_bf16 v[52:55], v[170:173], v[186:189], v[52:55]
	v_mfma_f32_16x16x32_bf16 v[48:51], v[178:181], v[186:189], v[48:51]
	v_mfma_f32_16x16x32_bf16 v[36:39], v[170:173], v[194:197], v[36:39]
	v_mfma_f32_16x16x32_bf16 v[32:35], v[178:181], v[194:197], v[32:35]
	v_mfma_f32_16x16x32_bf16 v[20:23], v[170:173], v[202:205], v[20:23]
	v_mfma_f32_16x16x32_bf16 v[16:19], v[178:181], v[202:205], v[16:19]
	v_mfma_f32_16x16x32_bf16 v[4:7], v[170:173], v[210:213], v[4:7]
	v_mfma_f32_16x16x32_bf16 v[0:3], v[178:181], v[210:213], v[0:3]
	v_mfma_f32_16x16x32_bf16 v[52:55], v[174:177], v[190:193], v[52:55]
	v_mfma_f32_16x16x32_bf16 v[48:51], v[182:185], v[190:193], v[48:51]
	v_mfma_f32_16x16x32_bf16 v[36:39], v[174:177], v[198:201], v[36:39]
	v_mfma_f32_16x16x32_bf16 v[32:35], v[182:185], v[198:201], v[32:35]
	v_mfma_f32_16x16x32_bf16 v[20:23], v[174:177], v[206:209], v[20:23]
	v_mfma_f32_16x16x32_bf16 v[16:19], v[182:185], v[206:209], v[16:19]
	v_mfma_f32_16x16x32_bf16 v[4:7], v[174:177], v[214:217], v[4:7]
	v_mfma_f32_16x16x32_bf16 v[0:3], v[182:185], v[214:217], v[0:3]
	s_setprio 0
	s_add_i32 s37, s37, 2
	s_add_u32 s88, s88, 0x100
	s_addc_u32 s89, s89, 0
	s_add_u32 s35, s35, 0x100
	s_addc_u32 s36, s36, 0
	s_cmp_gt_u32 s37, 29
	s_barrier
	s_cbranch_scc0 .LBB0_1624
	s_and_b64 vcc, exec, s[16:17]
	s_cbranch_vccz .LBB0_1627
	s_barrier

.LBB0_1700:
	ds_read_b128 v[140:143], v149
	ds_read_b128 v[152:155], v149 offset:1024
	ds_read_b128 v[156:159], v149 offset:2048
	ds_read_b128 v[160:163], v149 offset:3072
	ds_read_b128 v[164:167], v150
	ds_read_b128 v[168:171], v150 offset:1024
	ds_read_b128 v[172:175], v150 offset:2048
	ds_read_b128 v[176:179], v150 offset:3072
	s_add_u32 s3, s86, 0xffe00080
	s_addc_u32 s37, s87, -1
	s_cmpk_eq_i32 s36, 0x7c
	s_cselect_b32 s91, s0, s37
	s_cselect_b32 s90, s1, s3
	s_cselect_b32 s89, s17, s35
	s_cselect_b32 s88, s27, s33
	s_add_i32 m0, s18, 0xc000
	ds_read_b128 v[180:183], v151
	ds_read_b128 v[184:187], v151 offset:1024
	ds_read_b128 v[188:191], v151 offset:2048
	ds_read_b128 v[192:195], v151 offset:3072
	ds_read_b128 v[196:199], v151 offset:4096
	ds_read_b128 v[200:203], v151 offset:5120
	ds_read_b128 v[204:207], v151 offset:6144
	ds_read_b128 v[208:211], v151 offset:7168
	global_load_lds_dwordx4 v132, s[86:87]
	s_add_i32 m0, s18, 0xe000
	s_nop 0
	global_load_lds_dwordx4 v134, s[86:87]
	s_waitcnt vmcnt(8)
	s_waitcnt lgkmcnt(0)
	s_barrier
	s_setprio 1
	v_mfma_f32_16x16x32_bf16 v[124:127], v[140:143], v[180:183], v[124:127]
	v_mfma_f32_16x16x32_bf16 v[120:123], v[156:159], v[180:183], v[120:123]
	v_mfma_f32_16x16x32_bf16 v[112:115], v[140:143], v[188:191], v[112:115]
	v_mfma_f32_16x16x32_bf16 v[104:107], v[156:159], v[188:191], v[104:107]
	v_mfma_f32_16x16x32_bf16 v[96:99], v[140:143], v[196:199], v[96:99]
	v_mfma_f32_16x16x32_bf16 v[88:91], v[156:159], v[196:199], v[88:91]
	v_mfma_f32_16x16x32_bf16 v[80:83], v[140:143], v[204:207], v[80:83]
	v_mfma_f32_16x16x32_bf16 v[72:75], v[156:159], v[204:207], v[72:75]
	v_mfma_f32_16x16x32_bf16 v[124:127], v[152:155], v[184:187], v[124:127]
	v_mfma_f32_16x16x32_bf16 v[120:123], v[160:163], v[184:187], v[120:123]
	v_mfma_f32_16x16x32_bf16 v[112:115], v[152:155], v[192:195], v[112:115]
	v_mfma_f32_16x16x32_bf16 v[104:107], v[160:163], v[192:195], v[104:107]
	v_mfma_f32_16x16x32_bf16 v[96:99], v[152:155], v[200:203], v[96:99]
	v_mfma_f32_16x16x32_bf16 v[88:91], v[160:163], v[200:203], v[88:91]
	v_mfma_f32_16x16x32_bf16 v[80:83], v[152:155], v[208:211], v[80:83]
	v_mfma_f32_16x16x32_bf16 v[72:75], v[160:163], v[208:211], v[72:75]
	v_mfma_f32_16x16x32_bf16 v[116:119], v[164:167], v[180:183], v[116:119]
	v_mfma_f32_16x16x32_bf16 v[108:111], v[172:175], v[180:183], v[108:111]
	v_mfma_f32_16x16x32_bf16 v[100:103], v[164:167], v[188:191], v[100:103]
	v_mfma_f32_16x16x32_bf16 v[92:95], v[172:175], v[188:191], v[92:95]
	v_mfma_f32_16x16x32_bf16 v[84:87], v[164:167], v[196:199], v[84:87]
	v_mfma_f32_16x16x32_bf16 v[76:79], v[172:175], v[196:199], v[76:79]
	v_mfma_f32_16x16x32_bf16 v[68:71], v[164:167], v[204:207], v[68:71]
	v_mfma_f32_16x16x32_bf16 v[64:67], v[172:175], v[204:207], v[64:67]
	v_mfma_f32_16x16x32_bf16 v[116:119], v[168:171], v[184:187], v[116:119]
	v_mfma_f32_16x16x32_bf16 v[108:111], v[176:179], v[184:187], v[108:111]
	v_mfma_f32_16x16x32_bf16 v[100:103], v[168:171], v[192:195], v[100:103]
	v_mfma_f32_16x16x32_bf16 v[92:95], v[176:179], v[192:195], v[92:95]
	v_mfma_f32_16x16x32_bf16 v[84:87], v[168:171], v[200:203], v[84:87]
	v_mfma_f32_16x16x32_bf16 v[76:79], v[176:179], v[200:203], v[76:79]
	v_mfma_f32_16x16x32_bf16 v[68:71], v[168:171], v[208:211], v[68:71]
	v_mfma_f32_16x16x32_bf16 v[64:67], v[176:179], v[208:211], v[64:67]
	s_setprio 0
	s_barrier
	s_add_i32 s3, s49, s9
	s_mov_b32 m0, s3
	ds_read_b128 v[180:183], v151 offset:16384
	ds_read_b128 v[184:187], v151 offset:17408
	ds_read_b128 v[188:191], v151 offset:18432
	ds_read_b128 v[192:195], v151 offset:19456
	ds_read_b128 v[196:199], v151 offset:20480
	ds_read_b128 v[200:203], v151 offset:21504
	ds_read_b128 v[204:207], v151 offset:22528
	ds_read_b128 v[208:211], v151 offset:23552
	global_load_lds_dwordx4 v128, s[88:89]
	s_add_i32 m0, s3, 0x2000
	s_add_u32 s42, s88, 0x200000
	s_addc_u32 s43, s89, 0
	s_add_i32 s3, s52, s9
	global_load_lds_dwordx4 v130, s[88:89]
	s_mov_b32 m0, s3
	s_nop 0
	global_load_lds_dwordx4 v128, s[42:43]
	s_add_i32 m0, s3, 0x2000
	s_nop 0
	global_load_lds_dwordx4 v130, s[42:43]
	s_mov_b32 m0, s18
	s_nop 0
	global_load_lds_dwordx4 v128, s[90:91]
	s_mov_b32 m0, s19
	s_nop 0
	global_load_lds_dwordx4 v130, s[90:91]
	s_waitcnt vmcnt(8)
	s_waitcnt lgkmcnt(0)
	s_barrier
	s_setprio 1
	v_mfma_f32_16x16x32_bf16 v[60:63], v[140:143], v[180:183], v[60:63]
	v_mfma_f32_16x16x32_bf16 v[56:59], v[156:159], v[180:183], v[56:59]
	v_mfma_f32_16x16x32_bf16 v[48:51], v[140:143], v[188:191], v[48:51]
	v_mfma_f32_16x16x32_bf16 v[40:43], v[156:159], v[188:191], v[40:43]
	v_mfma_f32_16x16x32_bf16 v[32:35], v[140:143], v[196:199], v[32:35]
	v_mfma_f32_16x16x32_bf16 v[24:27], v[156:159], v[196:199], v[24:27]
	v_mfma_f32_16x16x32_bf16 v[16:19], v[140:143], v[204:207], v[16:19]
	v_mfma_f32_16x16x32_bf16 v[8:11], v[156:159], v[204:207], v[8:11]
	v_mfma_f32_16x16x32_bf16 v[60:63], v[152:155], v[184:187], v[60:63]
	v_mfma_f32_16x16x32_bf16 v[56:59], v[160:163], v[184:187], v[56:59]
	v_mfma_f32_16x16x32_bf16 v[48:51], v[152:155], v[192:195], v[48:51]
	v_mfma_f32_16x16x32_bf16 v[40:43], v[160:163], v[192:195], v[40:43]
	v_mfma_f32_16x16x32_bf16 v[32:35], v[152:155], v[200:203], v[32:35]
	v_mfma_f32_16x16x32_bf16 v[24:27], v[160:163], v[200:203], v[24:27]
	v_mfma_f32_16x16x32_bf16 v[16:19], v[152:155], v[208:211], v[16:19]
	v_mfma_f32_16x16x32_bf16 v[8:11], v[160:163], v[208:211], v[8:11]
	v_mfma_f32_16x16x32_bf16 v[52:55], v[164:167], v[180:183], v[52:55]
	v_mfma_f32_16x16x32_bf16 v[44:47], v[172:175], v[180:183], v[44:47]
	v_mfma_f32_16x16x32_bf16 v[36:39], v[164:167], v[188:191], v[36:39]
	v_mfma_f32_16x16x32_bf16 v[28:31], v[172:175], v[188:191], v[28:31]
	v_mfma_f32_16x16x32_bf16 v[20:23], v[164:167], v[196:199], v[20:23]
	v_mfma_f32_16x16x32_bf16 v[12:15], v[172:175], v[196:199], v[12:15]
	v_mfma_f32_16x16x32_bf16 v[4:7], v[164:167], v[204:207], v[4:7]
	v_mfma_f32_16x16x32_bf16 v[0:3], v[172:175], v[204:207], v[0:3]
	v_mfma_f32_16x16x32_bf16 v[52:55], v[168:171], v[184:187], v[52:55]
	v_mfma_f32_16x16x32_bf16 v[44:47], v[176:179], v[184:187], v[44:47]
	v_mfma_f32_16x16x32_bf16 v[36:39], v[168:171], v[192:195], v[36:39]
	v_mfma_f32_16x16x32_bf16 v[28:31], v[176:179], v[192:195], v[28:31]
	v_mfma_f32_16x16x32_bf16 v[20:23], v[168:171], v[200:203], v[20:23]
	v_mfma_f32_16x16x32_bf16 v[12:15], v[176:179], v[200:203], v[12:15]
	v_mfma_f32_16x16x32_bf16 v[4:7], v[168:171], v[208:211], v[4:7]
	v_mfma_f32_16x16x32_bf16 v[0:3], v[176:179], v[208:211], v[0:3]
	s_setprio 0
	s_barrier
	s_add_i32 s3, 0, 0x18000
	s_add_i32 s37, 0, 0x1c000
	v_add_u32_e32 v160, s3, v147
	v_add_u32_e32 v176, s37, v147
	ds_read_b128 v[140:143], v160
	ds_read_b128 v[152:155], v160 offset:1024
	ds_read_b128 v[156:159], v160 offset:2048
	ds_read_b128 v[160:163], v160 offset:3072
	ds_read_b128 v[164:167], v176
	ds_read_b128 v[168:171], v176 offset:1024
	ds_read_b128 v[172:175], v176 offset:2048
	ds_read_b128 v[176:179], v176 offset:3072
	s_add_u32 s42, s90, 0x200000
	s_addc_u32 s43, s91, 0
	s_mov_b32 m0, s25
	ds_read_b128 v[180:183], v151 offset:32768
	ds_read_b128 v[184:187], v151 offset:33792
	ds_read_b128 v[188:191], v151 offset:34816
	ds_read_b128 v[192:195], v151 offset:35840
	ds_read_b128 v[196:199], v151 offset:36864
	ds_read_b128 v[200:203], v151 offset:37888
	ds_read_b128 v[204:207], v151 offset:38912
	ds_read_b128 v[208:211], v151 offset:39936
	global_load_lds_dwordx4 v128, s[42:43]
	v_lshl_add_u64 v[218:219], s[42:43], 0, v[130:131]
	s_mov_b32 m0, s30
	s_nop 0
	global_load_lds_dwordx4 v[218:219], off
	s_waitcnt vmcnt(8)
	s_waitcnt lgkmcnt(0)
	s_barrier
	s_setprio 1
	v_mfma_f32_16x16x32_bf16 v[124:127], v[140:143], v[180:183], v[124:127]
	v_mfma_f32_16x16x32_bf16 v[120:123], v[156:159], v[180:183], v[120:123]
	v_mfma_f32_16x16x32_bf16 v[112:115], v[140:143], v[188:191], v[112:115]
	v_mfma_f32_16x16x32_bf16 v[104:107], v[156:159], v[188:191], v[104:107]
	v_mfma_f32_16x16x32_bf16 v[96:99], v[140:143], v[196:199], v[96:99]
	v_mfma_f32_16x16x32_bf16 v[88:91], v[156:159], v[196:199], v[88:91]
	v_mfma_f32_16x16x32_bf16 v[80:83], v[140:143], v[204:207], v[80:83]
	v_mfma_f32_16x16x32_bf16 v[72:75], v[156:159], v[204:207], v[72:75]
	v_mfma_f32_16x16x32_bf16 v[124:127], v[152:155], v[184:187], v[124:127]
	v_mfma_f32_16x16x32_bf16 v[120:123], v[160:163], v[184:187], v[120:123]
	v_mfma_f32_16x16x32_bf16 v[112:115], v[152:155], v[192:195], v[112:115]
	v_mfma_f32_16x16x32_bf16 v[104:107], v[160:163], v[192:195], v[104:107]
	v_mfma_f32_16x16x32_bf16 v[96:99], v[152:155], v[200:203], v[96:99]
	v_mfma_f32_16x16x32_bf16 v[88:91], v[160:163], v[200:203], v[88:91]
	v_mfma_f32_16x16x32_bf16 v[80:83], v[152:155], v[208:211], v[80:83]
	v_mfma_f32_16x16x32_bf16 v[72:75], v[160:163], v[208:211], v[72:75]
	v_mfma_f32_16x16x32_bf16 v[116:119], v[164:167], v[180:183], v[116:119]
	v_mfma_f32_16x16x32_bf16 v[108:111], v[172:175], v[180:183], v[108:111]
	v_mfma_f32_16x16x32_bf16 v[100:103], v[164:167], v[188:191], v[100:103]
	v_mfma_f32_16x16x32_bf16 v[92:95], v[172:175], v[188:191], v[92:95]
	v_mfma_f32_16x16x32_bf16 v[84:87], v[164:167], v[196:199], v[84:87]
	v_mfma_f32_16x16x32_bf16 v[76:79], v[172:175], v[196:199], v[76:79]
	v_mfma_f32_16x16x32_bf16 v[68:71], v[164:167], v[204:207], v[68:71]
	v_mfma_f32_16x16x32_bf16 v[64:67], v[172:175], v[204:207], v[64:67]
	v_mfma_f32_16x16x32_bf16 v[116:119], v[168:171], v[184:187], v[116:119]
	v_mfma_f32_16x16x32_bf16 v[108:111], v[176:179], v[184:187], v[108:111]
	v_mfma_f32_16x16x32_bf16 v[100:103], v[168:171], v[192:195], v[100:103]
	v_mfma_f32_16x16x32_bf16 v[92:95], v[176:179], v[192:195], v[92:95]
	v_mfma_f32_16x16x32_bf16 v[84:87], v[168:171], v[200:203], v[84:87]
	v_mfma_f32_16x16x32_bf16 v[76:79], v[176:179], v[200:203], v[76:79]
	v_mfma_f32_16x16x32_bf16 v[68:71], v[168:171], v[208:211], v[68:71]
	v_mfma_f32_16x16x32_bf16 v[64:67], v[176:179], v[208:211], v[64:67]
	s_setprio 0
	s_barrier
	s_add_i32 s3, s3, s9
	s_add_u32 s42, s88, 0x80
	s_addc_u32 s43, s89, 0
	s_mov_b32 m0, s3
	ds_read_b128 v[180:183], v151 offset:49152
	ds_read_b128 v[184:187], v151 offset:50176
	ds_read_b128 v[188:191], v151 offset:51200
	ds_read_b128 v[192:195], v151 offset:52224
	ds_read_b128 v[196:199], v151 offset:53248
	ds_read_b128 v[200:203], v151 offset:54272
	ds_read_b128 v[204:207], v151 offset:55296
	ds_read_b128 v[208:211], v151 offset:56320
	global_load_lds_dwordx4 v128, s[42:43]
	s_add_i32 m0, s3, 0x2000
	s_add_i32 s3, s37, s9
	global_load_lds_dwordx4 v130, s[42:43]
	s_add_u32 s42, s42, 0x200000
	s_addc_u32 s43, s43, 0
	s_mov_b32 m0, s3
	s_nop 0
	global_load_lds_dwordx4 v128, s[42:43]
	s_add_i32 m0, s3, 0x2000
	s_nop 0
	global_load_lds_dwordx4 v130, s[42:43]
	s_add_u32 s90, s90, 0x80
	s_addc_u32 s91, s91, 0
	s_mov_b32 m0, s8
	s_nop 0
	global_load_lds_dwordx4 v128, s[90:91]
	s_mov_b32 m0, s48
	s_nop 0
	global_load_lds_dwordx4 v130, s[90:91]
	s_waitcnt vmcnt(8)
	s_waitcnt lgkmcnt(0)
	s_barrier
	s_setprio 1
	v_mfma_f32_16x16x32_bf16 v[60:63], v[140:143], v[180:183], v[60:63]
	v_mfma_f32_16x16x32_bf16 v[56:59], v[156:159], v[180:183], v[56:59]
	v_mfma_f32_16x16x32_bf16 v[48:51], v[140:143], v[188:191], v[48:51]
	v_mfma_f32_16x16x32_bf16 v[40:43], v[156:159], v[188:191], v[40:43]
	v_mfma_f32_16x16x32_bf16 v[32:35], v[140:143], v[196:199], v[32:35]
	v_mfma_f32_16x16x32_bf16 v[24:27], v[156:159], v[196:199], v[24:27]
	v_mfma_f32_16x16x32_bf16 v[16:19], v[140:143], v[204:207], v[16:19]
	v_mfma_f32_16x16x32_bf16 v[8:11], v[156:159], v[204:207], v[8:11]
	v_mfma_f32_16x16x32_bf16 v[60:63], v[152:155], v[184:187], v[60:63]
	v_mfma_f32_16x16x32_bf16 v[56:59], v[160:163], v[184:187], v[56:59]
	v_mfma_f32_16x16x32_bf16 v[48:51], v[152:155], v[192:195], v[48:51]
	v_mfma_f32_16x16x32_bf16 v[40:43], v[160:163], v[192:195], v[40:43]
	v_mfma_f32_16x16x32_bf16 v[32:35], v[152:155], v[200:203], v[32:35]
	v_mfma_f32_16x16x32_bf16 v[24:27], v[160:163], v[200:203], v[24:27]
	v_mfma_f32_16x16x32_bf16 v[16:19], v[152:155], v[208:211], v[16:19]
	v_mfma_f32_16x16x32_bf16 v[8:11], v[160:163], v[208:211], v[8:11]
	v_mfma_f32_16x16x32_bf16 v[52:55], v[164:167], v[180:183], v[52:55]
	v_mfma_f32_16x16x32_bf16 v[44:47], v[172:175], v[180:183], v[44:47]
	v_mfma_f32_16x16x32_bf16 v[36:39], v[164:167], v[188:191], v[36:39]
	v_mfma_f32_16x16x32_bf16 v[28:31], v[172:175], v[188:191], v[28:31]
	v_mfma_f32_16x16x32_bf16 v[20:23], v[164:167], v[196:199], v[20:23]
	v_mfma_f32_16x16x32_bf16 v[12:15], v[172:175], v[196:199], v[12:15]
	v_mfma_f32_16x16x32_bf16 v[4:7], v[164:167], v[204:207], v[4:7]
	v_mfma_f32_16x16x32_bf16 v[0:3], v[172:175], v[204:207], v[0:3]
	v_mfma_f32_16x16x32_bf16 v[52:55], v[168:171], v[184:187], v[52:55]
	v_mfma_f32_16x16x32_bf16 v[44:47], v[176:179], v[184:187], v[44:47]
	v_mfma_f32_16x16x32_bf16 v[36:39], v[168:171], v[192:195], v[36:39]
	v_mfma_f32_16x16x32_bf16 v[28:31], v[176:179], v[192:195], v[28:31]
	v_mfma_f32_16x16x32_bf16 v[20:23], v[168:171], v[200:203], v[20:23]
	v_mfma_f32_16x16x32_bf16 v[12:15], v[176:179], v[200:203], v[12:15]
	v_mfma_f32_16x16x32_bf16 v[4:7], v[168:171], v[208:211], v[4:7]
	v_mfma_f32_16x16x32_bf16 v[0:3], v[176:179], v[208:211], v[0:3]
	s_setprio 0
	s_add_i32 s36, s36, 2
	s_add_u32 s86, s86, 0x100
	s_addc_u32 s87, s87, 0
	s_add_u32 s33, s33, 0x100
	s_addc_u32 s35, s35, 0
	s_cmpk_gt_u32 s36, 0x7d
	s_barrier
	s_cbranch_scc0 .LBB0_1700
	s_and_b64 vcc, exec, s[14:15]
	s_cbranch_vccz .LBB0_1703
	s_barrier

.LBB0_1773:
	ds_read_b128 v[128:131], v173
	ds_read_b128 v[132:135], v173 offset:1024
	ds_read_b128 v[158:161], v173 offset:2048
	ds_read_b128 v[178:181], v173 offset:3072
	ds_read_b128 v[182:185], v174
	ds_read_b128 v[186:189], v174 offset:1024
	ds_read_b128 v[190:193], v174 offset:2048
	ds_read_b128 v[194:197], v174 offset:3072
	s_add_u32 s3, s34, 0xfff80080
	s_addc_u32 s19, s35, -1
	s_cmp_eq_u32 s18, 28
	s_cselect_b32 vcc_hi, s0, s19
	s_cselect_b32 vcc_lo, s1, s3
	s_cselect_b32 s97, s8, s17
	s_cselect_b32 s96, s9, s15
	s_add_i32 m0, s48, 0xc000
	ds_read_b128 v[198:201], v175
	ds_read_b128 v[202:205], v175 offset:1024
	ds_read_b128 v[206:209], v175 offset:2048
	ds_read_b128 v[210:213], v175 offset:3072
	ds_read_b128 v[214:217], v175 offset:4096
	ds_read_b128 v[218:221], v175 offset:5120
	ds_read_b128 v[222:225], v175 offset:6144
	ds_read_b128 v[230:233], v175 offset:7168
	global_load_lds_dwordx4 v148, s[34:35]
	s_add_i32 m0, s48, 0xe000
	s_nop 0
	global_load_lds_dwordx4 v150, s[34:35]
	s_waitcnt vmcnt(8)
	s_waitcnt lgkmcnt(0)
	s_barrier
	s_setprio 1
	v_mfma_f32_16x16x32_bf16 v[124:127], v[128:131], v[198:201], v[124:127]
	v_mfma_f32_16x16x32_bf16 v[120:123], v[158:161], v[198:201], v[120:123]
	v_mfma_f32_16x16x32_bf16 v[108:111], v[128:131], v[206:209], v[108:111]
	v_mfma_f32_16x16x32_bf16 v[104:107], v[158:161], v[206:209], v[104:107]
	v_mfma_f32_16x16x32_bf16 v[92:95], v[128:131], v[214:217], v[92:95]
	v_mfma_f32_16x16x32_bf16 v[88:91], v[158:161], v[214:217], v[88:91]
	v_mfma_f32_16x16x32_bf16 v[76:79], v[128:131], v[222:225], v[76:79]
	v_mfma_f32_16x16x32_bf16 v[72:75], v[158:161], v[222:225], v[72:75]
	v_mfma_f32_16x16x32_bf16 v[124:127], v[132:135], v[202:205], v[124:127]
	v_mfma_f32_16x16x32_bf16 v[120:123], v[178:181], v[202:205], v[120:123]
	v_mfma_f32_16x16x32_bf16 v[108:111], v[132:135], v[210:213], v[108:111]
	v_mfma_f32_16x16x32_bf16 v[104:107], v[178:181], v[210:213], v[104:107]
	v_mfma_f32_16x16x32_bf16 v[92:95], v[132:135], v[218:221], v[92:95]
	v_mfma_f32_16x16x32_bf16 v[88:91], v[178:181], v[218:221], v[88:91]
	v_mfma_f32_16x16x32_bf16 v[76:79], v[132:135], v[230:233], v[76:79]
	v_mfma_f32_16x16x32_bf16 v[72:75], v[178:181], v[230:233], v[72:75]
	v_mfma_f32_16x16x32_bf16 v[116:119], v[182:185], v[198:201], v[116:119]
	v_mfma_f32_16x16x32_bf16 v[112:115], v[190:193], v[198:201], v[112:115]
	v_mfma_f32_16x16x32_bf16 v[100:103], v[182:185], v[206:209], v[100:103]
	v_mfma_f32_16x16x32_bf16 v[96:99], v[190:193], v[206:209], v[96:99]
	v_mfma_f32_16x16x32_bf16 v[84:87], v[182:185], v[214:217], v[84:87]
	v_mfma_f32_16x16x32_bf16 v[80:83], v[190:193], v[214:217], v[80:83]
	v_mfma_f32_16x16x32_bf16 v[68:71], v[182:185], v[222:225], v[68:71]
	v_mfma_f32_16x16x32_bf16 v[64:67], v[190:193], v[222:225], v[64:67]
	v_mfma_f32_16x16x32_bf16 v[116:119], v[186:189], v[202:205], v[116:119]
	v_mfma_f32_16x16x32_bf16 v[112:115], v[194:197], v[202:205], v[112:115]
	v_mfma_f32_16x16x32_bf16 v[100:103], v[186:189], v[210:213], v[100:103]
	v_mfma_f32_16x16x32_bf16 v[96:99], v[194:197], v[210:213], v[96:99]
	v_mfma_f32_16x16x32_bf16 v[84:87], v[186:189], v[218:221], v[84:87]
	v_mfma_f32_16x16x32_bf16 v[80:83], v[194:197], v[218:221], v[80:83]
	v_mfma_f32_16x16x32_bf16 v[68:71], v[186:189], v[230:233], v[68:71]
	v_mfma_f32_16x16x32_bf16 v[64:67], v[194:197], v[230:233], v[64:67]
	s_setprio 0
	s_barrier
	s_add_i32 s3, s76, s25
	s_mov_b32 m0, s3
	ds_read_b128 v[198:201], v175 offset:16384
	ds_read_b128 v[202:205], v175 offset:17408
	ds_read_b128 v[206:209], v175 offset:18432
	ds_read_b128 v[210:213], v175 offset:19456
	ds_read_b128 v[214:217], v175 offset:20480
	ds_read_b128 v[218:221], v175 offset:21504
	ds_read_b128 v[222:225], v175 offset:22528
	ds_read_b128 v[230:233], v175 offset:23552
	global_load_lds_dwordx4 v138, s[96:97]
	s_add_i32 m0, s3, 0x2000
	s_add_u32 s36, s96, 0x80000
	s_addc_u32 s37, s97, 0
	s_add_i32 s3, s77, s25
	global_load_lds_dwordx4 v142, s[96:97]
	s_mov_b32 m0, s3
	s_nop 0
	global_load_lds_dwordx4 v138, s[36:37]
	s_add_i32 m0, s3, 0x2000
	s_nop 0
	global_load_lds_dwordx4 v142, s[36:37]
	s_mov_b32 m0, s48
	s_nop 0
	global_load_lds_dwordx4 v136, vcc
	s_mov_b32 m0, s49
	s_nop 0
	global_load_lds_dwordx4 v140, vcc
	s_waitcnt vmcnt(8)
	s_waitcnt lgkmcnt(0)
	s_barrier
	s_setprio 1
	v_mfma_f32_16x16x32_bf16 v[60:63], v[128:131], v[198:201], v[60:63]
	v_mfma_f32_16x16x32_bf16 v[56:59], v[158:161], v[198:201], v[56:59]
	v_mfma_f32_16x16x32_bf16 v[44:47], v[128:131], v[206:209], v[44:47]
	v_mfma_f32_16x16x32_bf16 v[40:43], v[158:161], v[206:209], v[40:43]
	v_mfma_f32_16x16x32_bf16 v[28:31], v[128:131], v[214:217], v[28:31]
	v_mfma_f32_16x16x32_bf16 v[24:27], v[158:161], v[214:217], v[24:27]
	v_mfma_f32_16x16x32_bf16 v[12:15], v[128:131], v[222:225], v[12:15]
	v_mfma_f32_16x16x32_bf16 v[8:11], v[158:161], v[222:225], v[8:11]
	v_mfma_f32_16x16x32_bf16 v[60:63], v[132:135], v[202:205], v[60:63]
	v_mfma_f32_16x16x32_bf16 v[56:59], v[178:181], v[202:205], v[56:59]
	v_mfma_f32_16x16x32_bf16 v[44:47], v[132:135], v[210:213], v[44:47]
	v_mfma_f32_16x16x32_bf16 v[40:43], v[178:181], v[210:213], v[40:43]
	v_mfma_f32_16x16x32_bf16 v[28:31], v[132:135], v[218:221], v[28:31]
	v_mfma_f32_16x16x32_bf16 v[24:27], v[178:181], v[218:221], v[24:27]
	v_mfma_f32_16x16x32_bf16 v[12:15], v[132:135], v[230:233], v[12:15]
	v_mfma_f32_16x16x32_bf16 v[8:11], v[178:181], v[230:233], v[8:11]
	v_mfma_f32_16x16x32_bf16 v[52:55], v[182:185], v[198:201], v[52:55]
	v_mfma_f32_16x16x32_bf16 v[48:51], v[190:193], v[198:201], v[48:51]
	v_mfma_f32_16x16x32_bf16 v[36:39], v[182:185], v[206:209], v[36:39]
	v_mfma_f32_16x16x32_bf16 v[32:35], v[190:193], v[206:209], v[32:35]
	v_mfma_f32_16x16x32_bf16 v[20:23], v[182:185], v[214:217], v[20:23]
	v_mfma_f32_16x16x32_bf16 v[16:19], v[190:193], v[214:217], v[16:19]
	v_mfma_f32_16x16x32_bf16 v[4:7], v[182:185], v[222:225], v[4:7]
	v_mfma_f32_16x16x32_bf16 v[0:3], v[190:193], v[222:225], v[0:3]
	v_mfma_f32_16x16x32_bf16 v[52:55], v[186:189], v[202:205], v[52:55]
	v_mfma_f32_16x16x32_bf16 v[48:51], v[194:197], v[202:205], v[48:51]
	v_mfma_f32_16x16x32_bf16 v[36:39], v[186:189], v[210:213], v[36:39]
	v_mfma_f32_16x16x32_bf16 v[32:35], v[194:197], v[210:213], v[32:35]
	v_mfma_f32_16x16x32_bf16 v[20:23], v[186:189], v[218:221], v[20:23]
	v_mfma_f32_16x16x32_bf16 v[16:19], v[194:197], v[218:221], v[16:19]
	v_mfma_f32_16x16x32_bf16 v[4:7], v[186:189], v[230:233], v[4:7]
	v_mfma_f32_16x16x32_bf16 v[0:3], v[194:197], v[230:233], v[0:3]
	s_setprio 0
	s_barrier
	s_add_i32 s3, 0, 0x18000
	v_add_u32_e32 v144, s3, v165
	s_add_i32 s19, 0, 0x1c000
	ds_read_b128 v[128:131], v144
	ds_read_b128 v[132:135], v144 offset:1024
	ds_read_b128 v[158:161], v144 offset:2048
	ds_read_b128 v[178:181], v144 offset:3072
	v_add_u32_e32 v144, s19, v165
	ds_read_b128 v[182:185], v144
	ds_read_b128 v[186:189], v144 offset:1024
	ds_read_b128 v[190:193], v144 offset:2048
	ds_read_b128 v[194:197], v144 offset:3072
	s_add_u32 s36, vcc_lo, 0x80000
	s_addc_u32 s37, vcc_hi, 0
	s_mov_b32 m0, s52
	ds_read_b128 v[198:201], v175 offset:32768
	ds_read_b128 v[202:205], v175 offset:33792
	ds_read_b128 v[206:209], v175 offset:34816
	ds_read_b128 v[210:213], v175 offset:35840
	ds_read_b128 v[214:217], v175 offset:36864
	ds_read_b128 v[218:221], v175 offset:37888
	ds_read_b128 v[222:225], v175 offset:38912
	ds_read_b128 v[230:233], v175 offset:39936
	global_load_lds_dwordx4 v136, s[36:37]
	s_mov_b32 m0, s53
	s_nop 0
	global_load_lds_dwordx4 v140, s[36:37]
	s_waitcnt vmcnt(8)
	s_waitcnt lgkmcnt(0)
	s_barrier
	s_setprio 1
	v_mfma_f32_16x16x32_bf16 v[124:127], v[128:131], v[198:201], v[124:127]
	v_mfma_f32_16x16x32_bf16 v[120:123], v[158:161], v[198:201], v[120:123]
	v_mfma_f32_16x16x32_bf16 v[108:111], v[128:131], v[206:209], v[108:111]
	v_mfma_f32_16x16x32_bf16 v[104:107], v[158:161], v[206:209], v[104:107]
	v_mfma_f32_16x16x32_bf16 v[92:95], v[128:131], v[214:217], v[92:95]
	v_mfma_f32_16x16x32_bf16 v[88:91], v[158:161], v[214:217], v[88:91]
	v_mfma_f32_16x16x32_bf16 v[76:79], v[128:131], v[222:225], v[76:79]
	v_mfma_f32_16x16x32_bf16 v[72:75], v[158:161], v[222:225], v[72:75]
	v_mfma_f32_16x16x32_bf16 v[124:127], v[132:135], v[202:205], v[124:127]
	v_mfma_f32_16x16x32_bf16 v[120:123], v[178:181], v[202:205], v[120:123]
	v_mfma_f32_16x16x32_bf16 v[108:111], v[132:135], v[210:213], v[108:111]
	v_mfma_f32_16x16x32_bf16 v[104:107], v[178:181], v[210:213], v[104:107]
	v_mfma_f32_16x16x32_bf16 v[92:95], v[132:135], v[218:221], v[92:95]
	v_mfma_f32_16x16x32_bf16 v[88:91], v[178:181], v[218:221], v[88:91]
	v_mfma_f32_16x16x32_bf16 v[76:79], v[132:135], v[230:233], v[76:79]
	v_mfma_f32_16x16x32_bf16 v[72:75], v[178:181], v[230:233], v[72:75]
	v_mfma_f32_16x16x32_bf16 v[116:119], v[182:185], v[198:201], v[116:119]
	v_mfma_f32_16x16x32_bf16 v[112:115], v[190:193], v[198:201], v[112:115]
	v_mfma_f32_16x16x32_bf16 v[100:103], v[182:185], v[206:209], v[100:103]
	v_mfma_f32_16x16x32_bf16 v[96:99], v[190:193], v[206:209], v[96:99]
	v_mfma_f32_16x16x32_bf16 v[84:87], v[182:185], v[214:217], v[84:87]
	v_mfma_f32_16x16x32_bf16 v[80:83], v[190:193], v[214:217], v[80:83]
	v_mfma_f32_16x16x32_bf16 v[68:71], v[182:185], v[222:225], v[68:71]
	v_mfma_f32_16x16x32_bf16 v[64:67], v[190:193], v[222:225], v[64:67]
	v_mfma_f32_16x16x32_bf16 v[116:119], v[186:189], v[202:205], v[116:119]
	v_mfma_f32_16x16x32_bf16 v[112:115], v[194:197], v[202:205], v[112:115]
	v_mfma_f32_16x16x32_bf16 v[100:103], v[186:189], v[210:213], v[100:103]
	v_mfma_f32_16x16x32_bf16 v[96:99], v[194:197], v[210:213], v[96:99]
	v_mfma_f32_16x16x32_bf16 v[84:87], v[186:189], v[218:221], v[84:87]
	v_mfma_f32_16x16x32_bf16 v[80:83], v[194:197], v[218:221], v[80:83]
	v_mfma_f32_16x16x32_bf16 v[68:71], v[186:189], v[230:233], v[68:71]
	v_mfma_f32_16x16x32_bf16 v[64:67], v[194:197], v[230:233], v[64:67]
	s_setprio 0
	s_barrier
	s_add_i32 s3, s3, s25
	s_add_u32 s36, s96, 0x80
	s_addc_u32 s37, s97, 0
	s_mov_b32 m0, s3
	ds_read_b128 v[198:201], v175 offset:49152
	ds_read_b128 v[202:205], v175 offset:50176
	ds_read_b128 v[206:209], v175 offset:51200
	ds_read_b128 v[210:213], v175 offset:52224
	ds_read_b128 v[214:217], v175 offset:53248
	ds_read_b128 v[218:221], v175 offset:54272
	ds_read_b128 v[222:225], v175 offset:55296
	ds_read_b128 v[230:233], v175 offset:56320
	global_load_lds_dwordx4 v138, s[36:37]
	s_add_i32 m0, s3, 0x2000
	s_add_i32 s3, s19, s25
	global_load_lds_dwordx4 v142, s[36:37]
	s_add_u32 s36, s36, 0x80000
	s_addc_u32 s37, s37, 0
	s_mov_b32 m0, s3
	s_nop 0
	global_load_lds_dwordx4 v138, s[36:37]
	s_add_i32 m0, s3, 0x2000
	s_nop 0
	global_load_lds_dwordx4 v142, s[36:37]
	s_add_u32 vcc_lo, vcc_lo, 0x80
	s_addc_u32 vcc_hi, vcc_hi, 0
	s_mov_b32 m0, s56
	s_nop 0
	global_load_lds_dwordx4 v136, vcc
	s_mov_b32 m0, s57
	s_nop 0
	global_load_lds_dwordx4 v140, vcc
	s_waitcnt vmcnt(8)
	s_waitcnt lgkmcnt(0)
	s_barrier
	s_setprio 1
	v_mfma_f32_16x16x32_bf16 v[60:63], v[128:131], v[198:201], v[60:63]
	v_mfma_f32_16x16x32_bf16 v[56:59], v[158:161], v[198:201], v[56:59]
	v_mfma_f32_16x16x32_bf16 v[44:47], v[128:131], v[206:209], v[44:47]
	v_mfma_f32_16x16x32_bf16 v[40:43], v[158:161], v[206:209], v[40:43]
	v_mfma_f32_16x16x32_bf16 v[28:31], v[128:131], v[214:217], v[28:31]
	v_mfma_f32_16x16x32_bf16 v[24:27], v[158:161], v[214:217], v[24:27]
	v_mfma_f32_16x16x32_bf16 v[12:15], v[128:131], v[222:225], v[12:15]
	v_mfma_f32_16x16x32_bf16 v[8:11], v[158:161], v[222:225], v[8:11]
	v_mfma_f32_16x16x32_bf16 v[60:63], v[132:135], v[202:205], v[60:63]
	v_mfma_f32_16x16x32_bf16 v[56:59], v[178:181], v[202:205], v[56:59]
	v_mfma_f32_16x16x32_bf16 v[44:47], v[132:135], v[210:213], v[44:47]
	v_mfma_f32_16x16x32_bf16 v[40:43], v[178:181], v[210:213], v[40:43]
	v_mfma_f32_16x16x32_bf16 v[28:31], v[132:135], v[218:221], v[28:31]
	v_mfma_f32_16x16x32_bf16 v[24:27], v[178:181], v[218:221], v[24:27]
	v_mfma_f32_16x16x32_bf16 v[12:15], v[132:135], v[230:233], v[12:15]
	v_mfma_f32_16x16x32_bf16 v[8:11], v[178:181], v[230:233], v[8:11]
	v_mfma_f32_16x16x32_bf16 v[52:55], v[182:185], v[198:201], v[52:55]
	v_mfma_f32_16x16x32_bf16 v[48:51], v[190:193], v[198:201], v[48:51]
	v_mfma_f32_16x16x32_bf16 v[36:39], v[182:185], v[206:209], v[36:39]
	v_mfma_f32_16x16x32_bf16 v[32:35], v[190:193], v[206:209], v[32:35]
	v_mfma_f32_16x16x32_bf16 v[20:23], v[182:185], v[214:217], v[20:23]
	v_mfma_f32_16x16x32_bf16 v[16:19], v[190:193], v[214:217], v[16:19]
	v_mfma_f32_16x16x32_bf16 v[4:7], v[182:185], v[222:225], v[4:7]
	v_mfma_f32_16x16x32_bf16 v[0:3], v[190:193], v[222:225], v[0:3]
	v_mfma_f32_16x16x32_bf16 v[52:55], v[186:189], v[202:205], v[52:55]
	v_mfma_f32_16x16x32_bf16 v[48:51], v[194:197], v[202:205], v[48:51]
	v_mfma_f32_16x16x32_bf16 v[36:39], v[186:189], v[210:213], v[36:39]
	v_mfma_f32_16x16x32_bf16 v[32:35], v[194:197], v[210:213], v[32:35]
	v_mfma_f32_16x16x32_bf16 v[20:23], v[186:189], v[218:221], v[20:23]
	v_mfma_f32_16x16x32_bf16 v[16:19], v[194:197], v[218:221], v[16:19]
	v_mfma_f32_16x16x32_bf16 v[4:7], v[186:189], v[230:233], v[4:7]
	v_mfma_f32_16x16x32_bf16 v[0:3], v[194:197], v[230:233], v[0:3]
	s_setprio 0
	s_add_i32 s18, s18, 2
	s_add_u32 s34, s34, 0x100
	s_addc_u32 s35, s35, 0
	s_add_u32 s15, s15, 0x100
	s_addc_u32 s17, s17, 0
	s_cmp_gt_u32 s18, 29
	s_barrier
	s_cbranch_scc0 .LBB0_1773
	s_and_b64 vcc, exec, s[84:85]
	s_cbranch_vccz .LBB0_1776
	s_barrier

.LBB0_2248:
	ds_read_b128 v[144:147], v153
	ds_read_b128 v[156:159], v153 offset:1024
	ds_read_b128 v[160:163], v153 offset:2048
	ds_read_b128 v[164:167], v153 offset:3072
	ds_read_b128 v[168:171], v154
	ds_read_b128 v[172:175], v154 offset:1024
	ds_read_b128 v[176:179], v154 offset:2048
	ds_read_b128 v[180:183], v154 offset:3072
	s_add_u32 s3, s52, 0xfffc0080
	s_addc_u32 s45, s53, -1
	s_cmp_eq_u32 s44, 12
	s_cselect_b32 s59, s0, s45
	s_cselect_b32 s58, s1, s3
	s_cselect_b32 s57, s17, s35
	s_cselect_b32 s56, s27, s33
	s_add_i32 m0, s9, 0xc000
	ds_read_b128 v[184:187], v155
	ds_read_b128 v[188:191], v155 offset:1024
	ds_read_b128 v[192:195], v155 offset:2048
	ds_read_b128 v[196:199], v155 offset:3072
	ds_read_b128 v[200:203], v155 offset:4096
	ds_read_b128 v[204:207], v155 offset:5120
	ds_read_b128 v[208:211], v155 offset:6144
	ds_read_b128 v[212:215], v155 offset:7168
	global_load_lds_dwordx4 v136, s[52:53]
	s_add_i32 m0, s9, 0xe000
	s_nop 0
	global_load_lds_dwordx4 v138, s[52:53]
	s_waitcnt vmcnt(8)
	s_waitcnt lgkmcnt(0)
	s_barrier
	s_setprio 1
	v_mfma_f32_16x16x32_bf16 v[124:127], v[144:147], v[184:187], v[124:127]
	v_mfma_f32_16x16x32_bf16 v[120:123], v[160:163], v[184:187], v[120:123]
	v_mfma_f32_16x16x32_bf16 v[108:111], v[144:147], v[192:195], v[108:111]
	v_mfma_f32_16x16x32_bf16 v[104:107], v[160:163], v[192:195], v[104:107]
	v_mfma_f32_16x16x32_bf16 v[92:95], v[144:147], v[200:203], v[92:95]
	v_mfma_f32_16x16x32_bf16 v[88:91], v[160:163], v[200:203], v[88:91]
	v_mfma_f32_16x16x32_bf16 v[76:79], v[144:147], v[208:211], v[76:79]
	v_mfma_f32_16x16x32_bf16 v[72:75], v[160:163], v[208:211], v[72:75]
	v_mfma_f32_16x16x32_bf16 v[124:127], v[156:159], v[188:191], v[124:127]
	v_mfma_f32_16x16x32_bf16 v[120:123], v[164:167], v[188:191], v[120:123]
	v_mfma_f32_16x16x32_bf16 v[108:111], v[156:159], v[196:199], v[108:111]
	v_mfma_f32_16x16x32_bf16 v[104:107], v[164:167], v[196:199], v[104:107]
	v_mfma_f32_16x16x32_bf16 v[92:95], v[156:159], v[204:207], v[92:95]
	v_mfma_f32_16x16x32_bf16 v[88:91], v[164:167], v[204:207], v[88:91]
	v_mfma_f32_16x16x32_bf16 v[76:79], v[156:159], v[212:215], v[76:79]
	v_mfma_f32_16x16x32_bf16 v[72:75], v[164:167], v[212:215], v[72:75]
	v_mfma_f32_16x16x32_bf16 v[116:119], v[168:171], v[184:187], v[116:119]
	v_mfma_f32_16x16x32_bf16 v[112:115], v[176:179], v[184:187], v[112:115]
	v_mfma_f32_16x16x32_bf16 v[100:103], v[168:171], v[192:195], v[100:103]
	v_mfma_f32_16x16x32_bf16 v[96:99], v[176:179], v[192:195], v[96:99]
	v_mfma_f32_16x16x32_bf16 v[84:87], v[168:171], v[200:203], v[84:87]
	v_mfma_f32_16x16x32_bf16 v[80:83], v[176:179], v[200:203], v[80:83]
	v_mfma_f32_16x16x32_bf16 v[68:71], v[168:171], v[208:211], v[68:71]
	v_mfma_f32_16x16x32_bf16 v[64:67], v[176:179], v[208:211], v[64:67]
	v_mfma_f32_16x16x32_bf16 v[116:119], v[172:175], v[188:191], v[116:119]
	v_mfma_f32_16x16x32_bf16 v[112:115], v[180:183], v[188:191], v[112:115]
	v_mfma_f32_16x16x32_bf16 v[100:103], v[172:175], v[196:199], v[100:103]
	v_mfma_f32_16x16x32_bf16 v[96:99], v[180:183], v[196:199], v[96:99]
	v_mfma_f32_16x16x32_bf16 v[84:87], v[172:175], v[204:207], v[84:87]
	v_mfma_f32_16x16x32_bf16 v[80:83], v[180:183], v[204:207], v[80:83]
	v_mfma_f32_16x16x32_bf16 v[68:71], v[172:175], v[212:215], v[68:71]
	v_mfma_f32_16x16x32_bf16 v[64:67], v[180:183], v[212:215], v[64:67]
	s_setprio 0
	s_barrier
	s_add_i32 s3, s62, s8
	s_mov_b32 m0, s3
	ds_read_b128 v[184:187], v155 offset:16384
	ds_read_b128 v[188:191], v155 offset:17408
	ds_read_b128 v[192:195], v155 offset:18432
	ds_read_b128 v[196:199], v155 offset:19456
	ds_read_b128 v[200:203], v155 offset:20480
	ds_read_b128 v[204:207], v155 offset:21504
	ds_read_b128 v[208:211], v155 offset:22528
	ds_read_b128 v[212:215], v155 offset:23552
	global_load_lds_dwordx4 v130, s[56:57]
	s_add_i32 m0, s3, 0x2000
	s_add_u32 s50, s56, 0x40000
	s_addc_u32 s51, s57, 0
	s_add_i32 s3, s63, s8
	global_load_lds_dwordx4 v134, s[56:57]
	s_mov_b32 m0, s3
	s_nop 0
	global_load_lds_dwordx4 v130, s[50:51]
	s_add_i32 m0, s3, 0x2000
	s_nop 0
	global_load_lds_dwordx4 v134, s[50:51]
	s_mov_b32 m0, s9
	s_nop 0
	global_load_lds_dwordx4 v128, s[58:59]
	s_mov_b32 m0, s18
	s_nop 0
	global_load_lds_dwordx4 v132, s[58:59]
	s_waitcnt vmcnt(8)
	s_waitcnt lgkmcnt(0)
	s_barrier
	s_setprio 1
	v_mfma_f32_16x16x32_bf16 v[60:63], v[144:147], v[184:187], v[60:63]
	v_mfma_f32_16x16x32_bf16 v[56:59], v[160:163], v[184:187], v[56:59]
	v_mfma_f32_16x16x32_bf16 v[44:47], v[144:147], v[192:195], v[44:47]
	v_mfma_f32_16x16x32_bf16 v[40:43], v[160:163], v[192:195], v[40:43]
	v_mfma_f32_16x16x32_bf16 v[28:31], v[144:147], v[200:203], v[28:31]
	v_mfma_f32_16x16x32_bf16 v[24:27], v[160:163], v[200:203], v[24:27]
	v_mfma_f32_16x16x32_bf16 v[12:15], v[144:147], v[208:211], v[12:15]
	v_mfma_f32_16x16x32_bf16 v[8:11], v[160:163], v[208:211], v[8:11]
	v_mfma_f32_16x16x32_bf16 v[60:63], v[156:159], v[188:191], v[60:63]
	v_mfma_f32_16x16x32_bf16 v[56:59], v[164:167], v[188:191], v[56:59]
	v_mfma_f32_16x16x32_bf16 v[44:47], v[156:159], v[196:199], v[44:47]
	v_mfma_f32_16x16x32_bf16 v[40:43], v[164:167], v[196:199], v[40:43]
	v_mfma_f32_16x16x32_bf16 v[28:31], v[156:159], v[204:207], v[28:31]
	v_mfma_f32_16x16x32_bf16 v[24:27], v[164:167], v[204:207], v[24:27]
	v_mfma_f32_16x16x32_bf16 v[12:15], v[156:159], v[212:215], v[12:15]
	v_mfma_f32_16x16x32_bf16 v[8:11], v[164:167], v[212:215], v[8:11]
	v_mfma_f32_16x16x32_bf16 v[52:55], v[168:171], v[184:187], v[52:55]
	v_mfma_f32_16x16x32_bf16 v[48:51], v[176:179], v[184:187], v[48:51]
	v_mfma_f32_16x16x32_bf16 v[36:39], v[168:171], v[192:195], v[36:39]
	v_mfma_f32_16x16x32_bf16 v[32:35], v[176:179], v[192:195], v[32:35]
	v_mfma_f32_16x16x32_bf16 v[20:23], v[168:171], v[200:203], v[20:23]
	v_mfma_f32_16x16x32_bf16 v[16:19], v[176:179], v[200:203], v[16:19]
	v_mfma_f32_16x16x32_bf16 v[4:7], v[168:171], v[208:211], v[4:7]
	v_mfma_f32_16x16x32_bf16 v[0:3], v[176:179], v[208:211], v[0:3]
	v_mfma_f32_16x16x32_bf16 v[52:55], v[172:175], v[188:191], v[52:55]
	v_mfma_f32_16x16x32_bf16 v[48:51], v[180:183], v[188:191], v[48:51]
	v_mfma_f32_16x16x32_bf16 v[36:39], v[172:175], v[196:199], v[36:39]
	v_mfma_f32_16x16x32_bf16 v[32:35], v[180:183], v[196:199], v[32:35]
	v_mfma_f32_16x16x32_bf16 v[20:23], v[172:175], v[204:207], v[20:23]
	v_mfma_f32_16x16x32_bf16 v[16:19], v[180:183], v[204:207], v[16:19]
	v_mfma_f32_16x16x32_bf16 v[4:7], v[172:175], v[212:215], v[4:7]
	v_mfma_f32_16x16x32_bf16 v[0:3], v[180:183], v[212:215], v[0:3]
	s_setprio 0
	s_barrier
	s_add_i32 s3, 0, 0x18000
	s_add_i32 s45, 0, 0x1c000
	v_add_u32_e32 v164, s3, v151
	v_add_u32_e32 v180, s45, v151
	ds_read_b128 v[144:147], v164
	ds_read_b128 v[156:159], v164 offset:1024
	ds_read_b128 v[160:163], v164 offset:2048
	ds_read_b128 v[164:167], v164 offset:3072
	ds_read_b128 v[168:171], v180
	ds_read_b128 v[172:175], v180 offset:1024
	ds_read_b128 v[176:179], v180 offset:2048
	ds_read_b128 v[180:183], v180 offset:3072
	s_add_u32 s50, s58, 0x40000
	s_addc_u32 s51, s59, 0
	s_mov_b32 m0, s19
	ds_read_b128 v[184:187], v155 offset:32768
	ds_read_b128 v[188:191], v155 offset:33792
	ds_read_b128 v[192:195], v155 offset:34816
	ds_read_b128 v[196:199], v155 offset:35840
	ds_read_b128 v[200:203], v155 offset:36864
	ds_read_b128 v[204:207], v155 offset:37888
	ds_read_b128 v[208:211], v155 offset:38912
	ds_read_b128 v[212:215], v155 offset:39936
	global_load_lds_dwordx4 v128, s[50:51]
	s_mov_b32 m0, s25
	s_nop 0
	global_load_lds_dwordx4 v132, s[50:51]
	s_waitcnt vmcnt(8)
	s_waitcnt lgkmcnt(0)
	s_barrier
	s_setprio 1
	v_mfma_f32_16x16x32_bf16 v[124:127], v[144:147], v[184:187], v[124:127]
	v_mfma_f32_16x16x32_bf16 v[120:123], v[160:163], v[184:187], v[120:123]
	v_mfma_f32_16x16x32_bf16 v[108:111], v[144:147], v[192:195], v[108:111]
	v_mfma_f32_16x16x32_bf16 v[104:107], v[160:163], v[192:195], v[104:107]
	v_mfma_f32_16x16x32_bf16 v[92:95], v[144:147], v[200:203], v[92:95]
	v_mfma_f32_16x16x32_bf16 v[88:91], v[160:163], v[200:203], v[88:91]
	v_mfma_f32_16x16x32_bf16 v[76:79], v[144:147], v[208:211], v[76:79]
	v_mfma_f32_16x16x32_bf16 v[72:75], v[160:163], v[208:211], v[72:75]
	v_mfma_f32_16x16x32_bf16 v[124:127], v[156:159], v[188:191], v[124:127]
	v_mfma_f32_16x16x32_bf16 v[120:123], v[164:167], v[188:191], v[120:123]
	v_mfma_f32_16x16x32_bf16 v[108:111], v[156:159], v[196:199], v[108:111]
	v_mfma_f32_16x16x32_bf16 v[104:107], v[164:167], v[196:199], v[104:107]
	v_mfma_f32_16x16x32_bf16 v[92:95], v[156:159], v[204:207], v[92:95]
	v_mfma_f32_16x16x32_bf16 v[88:91], v[164:167], v[204:207], v[88:91]
	v_mfma_f32_16x16x32_bf16 v[76:79], v[156:159], v[212:215], v[76:79]
	v_mfma_f32_16x16x32_bf16 v[72:75], v[164:167], v[212:215], v[72:75]
	v_mfma_f32_16x16x32_bf16 v[116:119], v[168:171], v[184:187], v[116:119]
	v_mfma_f32_16x16x32_bf16 v[112:115], v[176:179], v[184:187], v[112:115]
	v_mfma_f32_16x16x32_bf16 v[100:103], v[168:171], v[192:195], v[100:103]
	v_mfma_f32_16x16x32_bf16 v[96:99], v[176:179], v[192:195], v[96:99]
	v_mfma_f32_16x16x32_bf16 v[84:87], v[168:171], v[200:203], v[84:87]
	v_mfma_f32_16x16x32_bf16 v[80:83], v[176:179], v[200:203], v[80:83]
	v_mfma_f32_16x16x32_bf16 v[68:71], v[168:171], v[208:211], v[68:71]
	v_mfma_f32_16x16x32_bf16 v[64:67], v[176:179], v[208:211], v[64:67]
	v_mfma_f32_16x16x32_bf16 v[116:119], v[172:175], v[188:191], v[116:119]
	v_mfma_f32_16x16x32_bf16 v[112:115], v[180:183], v[188:191], v[112:115]
	v_mfma_f32_16x16x32_bf16 v[100:103], v[172:175], v[196:199], v[100:103]
	v_mfma_f32_16x16x32_bf16 v[96:99], v[180:183], v[196:199], v[96:99]
	v_mfma_f32_16x16x32_bf16 v[84:87], v[172:175], v[204:207], v[84:87]
	v_mfma_f32_16x16x32_bf16 v[80:83], v[180:183], v[204:207], v[80:83]
	v_mfma_f32_16x16x32_bf16 v[68:71], v[172:175], v[212:215], v[68:71]
	v_mfma_f32_16x16x32_bf16 v[64:67], v[180:183], v[212:215], v[64:67]
	s_setprio 0
	s_barrier
	s_add_i32 s3, s3, s8
	s_add_u32 s50, s56, 0x80
	s_addc_u32 s51, s57, 0
	s_mov_b32 m0, s3
	ds_read_b128 v[184:187], v155 offset:49152
	ds_read_b128 v[188:191], v155 offset:50176
	ds_read_b128 v[192:195], v155 offset:51200
	ds_read_b128 v[196:199], v155 offset:52224
	ds_read_b128 v[200:203], v155 offset:53248
	ds_read_b128 v[204:207], v155 offset:54272
	ds_read_b128 v[208:211], v155 offset:55296
	ds_read_b128 v[212:215], v155 offset:56320
	global_load_lds_dwordx4 v130, s[50:51]
	s_add_i32 m0, s3, 0x2000
	s_add_i32 s3, s45, s8
	global_load_lds_dwordx4 v134, s[50:51]
	s_add_u32 s50, s50, 0x40000
	s_addc_u32 s51, s51, 0
	s_mov_b32 m0, s3
	s_nop 0
	global_load_lds_dwordx4 v130, s[50:51]
	s_add_i32 m0, s3, 0x2000
	s_nop 0
	global_load_lds_dwordx4 v134, s[50:51]
	s_add_u32 s58, s58, 0x80
	s_addc_u32 s59, s59, 0
	s_mov_b32 m0, s60
	s_nop 0
	global_load_lds_dwordx4 v128, s[58:59]
	s_mov_b32 m0, s61
	s_nop 0
	global_load_lds_dwordx4 v132, s[58:59]
	s_waitcnt vmcnt(8)
	s_waitcnt lgkmcnt(0)
	s_barrier
	s_setprio 1
	v_mfma_f32_16x16x32_bf16 v[60:63], v[144:147], v[184:187], v[60:63]
	v_mfma_f32_16x16x32_bf16 v[56:59], v[160:163], v[184:187], v[56:59]
	v_mfma_f32_16x16x32_bf16 v[44:47], v[144:147], v[192:195], v[44:47]
	v_mfma_f32_16x16x32_bf16 v[40:43], v[160:163], v[192:195], v[40:43]
	v_mfma_f32_16x16x32_bf16 v[28:31], v[144:147], v[200:203], v[28:31]
	v_mfma_f32_16x16x32_bf16 v[24:27], v[160:163], v[200:203], v[24:27]
	v_mfma_f32_16x16x32_bf16 v[12:15], v[144:147], v[208:211], v[12:15]
	v_mfma_f32_16x16x32_bf16 v[8:11], v[160:163], v[208:211], v[8:11]
	v_mfma_f32_16x16x32_bf16 v[60:63], v[156:159], v[188:191], v[60:63]
	v_mfma_f32_16x16x32_bf16 v[56:59], v[164:167], v[188:191], v[56:59]
	v_mfma_f32_16x16x32_bf16 v[44:47], v[156:159], v[196:199], v[44:47]
	v_mfma_f32_16x16x32_bf16 v[40:43], v[164:167], v[196:199], v[40:43]
	v_mfma_f32_16x16x32_bf16 v[28:31], v[156:159], v[204:207], v[28:31]
	v_mfma_f32_16x16x32_bf16 v[24:27], v[164:167], v[204:207], v[24:27]
	v_mfma_f32_16x16x32_bf16 v[12:15], v[156:159], v[212:215], v[12:15]
	v_mfma_f32_16x16x32_bf16 v[8:11], v[164:167], v[212:215], v[8:11]
	v_mfma_f32_16x16x32_bf16 v[52:55], v[168:171], v[184:187], v[52:55]
	v_mfma_f32_16x16x32_bf16 v[48:51], v[176:179], v[184:187], v[48:51]
	v_mfma_f32_16x16x32_bf16 v[36:39], v[168:171], v[192:195], v[36:39]
	v_mfma_f32_16x16x32_bf16 v[32:35], v[176:179], v[192:195], v[32:35]
	v_mfma_f32_16x16x32_bf16 v[20:23], v[168:171], v[200:203], v[20:23]
	v_mfma_f32_16x16x32_bf16 v[16:19], v[176:179], v[200:203], v[16:19]
	v_mfma_f32_16x16x32_bf16 v[4:7], v[168:171], v[208:211], v[4:7]
	v_mfma_f32_16x16x32_bf16 v[0:3], v[176:179], v[208:211], v[0:3]
	v_mfma_f32_16x16x32_bf16 v[52:55], v[172:175], v[188:191], v[52:55]
	v_mfma_f32_16x16x32_bf16 v[48:51], v[180:183], v[188:191], v[48:51]
	v_mfma_f32_16x16x32_bf16 v[36:39], v[172:175], v[196:199], v[36:39]
	v_mfma_f32_16x16x32_bf16 v[32:35], v[180:183], v[196:199], v[32:35]
	v_mfma_f32_16x16x32_bf16 v[20:23], v[172:175], v[204:207], v[20:23]
	v_mfma_f32_16x16x32_bf16 v[16:19], v[180:183], v[204:207], v[16:19]
	v_mfma_f32_16x16x32_bf16 v[4:7], v[172:175], v[212:215], v[4:7]
	v_mfma_f32_16x16x32_bf16 v[0:3], v[180:183], v[212:215], v[0:3]
	s_setprio 0
	s_add_i32 s44, s44, 2
	s_add_u32 s52, s52, 0x100
	s_addc_u32 s53, s53, 0
	s_add_u32 s33, s33, 0x100
	s_addc_u32 s35, s35, 0
	s_cmp_gt_u32 s44, 13
	s_barrier
	s_cbranch_scc0 .LBB0_2248
	s_and_b64 vcc, exec, s[12:13]
	s_cbranch_vccz .LBB0_2251
	s_barrier

.LBB0_2272:
	ds_read_b128 v[144:147], v155
	ds_read_b128 v[148:151], v155 offset:1024
	ds_read_b128 v[158:161], v155 offset:2048
	ds_read_b128 v[162:165], v155 offset:3072
	ds_read_b128 v[166:169], v156
	ds_read_b128 v[170:173], v156 offset:1024
	ds_read_b128 v[174:177], v156 offset:2048
	ds_read_b128 v[178:181], v156 offset:3072
	s_add_u32 s3, s52, 0xfffe0080
	s_addc_u32 s51, s53, -1
	s_cmp_eq_u32 s50, 4
	s_cselect_b32 s59, s0, s51
	s_cselect_b32 s58, s1, s3
	s_cselect_b32 s57, s17, s45
	s_cselect_b32 s56, s35, s44
	s_add_i32 m0, s9, 0xc000
	ds_read_b128 v[182:185], v157
	ds_read_b128 v[186:189], v157 offset:1024
	ds_read_b128 v[190:193], v157 offset:2048
	ds_read_b128 v[194:197], v157 offset:3072
	ds_read_b128 v[198:201], v157 offset:4096
	ds_read_b128 v[202:205], v157 offset:5120
	ds_read_b128 v[206:209], v157 offset:6144
	ds_read_b128 v[210:213], v157 offset:7168
	global_load_lds_dwordx4 v136, s[52:53]
	s_add_i32 m0, s9, 0xe000
	s_nop 0
	global_load_lds_dwordx4 v138, s[52:53]
	s_waitcnt vmcnt(8)
	s_waitcnt lgkmcnt(0)
	s_barrier
	s_setprio 1
	v_mfma_f32_16x16x32_bf16 v[124:127], v[144:147], v[182:185], v[124:127]
	v_mfma_f32_16x16x32_bf16 v[120:123], v[158:161], v[182:185], v[120:123]
	v_mfma_f32_16x16x32_bf16 v[108:111], v[144:147], v[190:193], v[108:111]
	v_mfma_f32_16x16x32_bf16 v[104:107], v[158:161], v[190:193], v[104:107]
	v_mfma_f32_16x16x32_bf16 v[92:95], v[144:147], v[198:201], v[92:95]
	v_mfma_f32_16x16x32_bf16 v[88:91], v[158:161], v[198:201], v[88:91]
	v_mfma_f32_16x16x32_bf16 v[76:79], v[144:147], v[206:209], v[76:79]
	v_mfma_f32_16x16x32_bf16 v[72:75], v[158:161], v[206:209], v[72:75]
	v_mfma_f32_16x16x32_bf16 v[124:127], v[148:151], v[186:189], v[124:127]
	v_mfma_f32_16x16x32_bf16 v[120:123], v[162:165], v[186:189], v[120:123]
	v_mfma_f32_16x16x32_bf16 v[108:111], v[148:151], v[194:197], v[108:111]
	v_mfma_f32_16x16x32_bf16 v[104:107], v[162:165], v[194:197], v[104:107]
	v_mfma_f32_16x16x32_bf16 v[92:95], v[148:151], v[202:205], v[92:95]
	v_mfma_f32_16x16x32_bf16 v[88:91], v[162:165], v[202:205], v[88:91]
	v_mfma_f32_16x16x32_bf16 v[76:79], v[148:151], v[210:213], v[76:79]
	v_mfma_f32_16x16x32_bf16 v[72:75], v[162:165], v[210:213], v[72:75]
	v_mfma_f32_16x16x32_bf16 v[116:119], v[166:169], v[182:185], v[116:119]
	v_mfma_f32_16x16x32_bf16 v[112:115], v[174:177], v[182:185], v[112:115]
	v_mfma_f32_16x16x32_bf16 v[100:103], v[166:169], v[190:193], v[100:103]
	v_mfma_f32_16x16x32_bf16 v[96:99], v[174:177], v[190:193], v[96:99]
	v_mfma_f32_16x16x32_bf16 v[84:87], v[166:169], v[198:201], v[84:87]
	v_mfma_f32_16x16x32_bf16 v[80:83], v[174:177], v[198:201], v[80:83]
	v_mfma_f32_16x16x32_bf16 v[68:71], v[166:169], v[206:209], v[68:71]
	v_mfma_f32_16x16x32_bf16 v[64:67], v[174:177], v[206:209], v[64:67]
	v_mfma_f32_16x16x32_bf16 v[116:119], v[170:173], v[186:189], v[116:119]
	v_mfma_f32_16x16x32_bf16 v[112:115], v[178:181], v[186:189], v[112:115]
	v_mfma_f32_16x16x32_bf16 v[100:103], v[170:173], v[194:197], v[100:103]
	v_mfma_f32_16x16x32_bf16 v[96:99], v[178:181], v[194:197], v[96:99]
	v_mfma_f32_16x16x32_bf16 v[84:87], v[170:173], v[202:205], v[84:87]
	v_mfma_f32_16x16x32_bf16 v[80:83], v[178:181], v[202:205], v[80:83]
	v_mfma_f32_16x16x32_bf16 v[68:71], v[170:173], v[210:213], v[68:71]
	v_mfma_f32_16x16x32_bf16 v[64:67], v[178:181], v[210:213], v[64:67]
	s_setprio 0
	s_barrier
	s_add_i32 s3, s61, s8
	s_mov_b32 m0, s3
	ds_read_b128 v[182:185], v157 offset:16384
	ds_read_b128 v[186:189], v157 offset:17408
	ds_read_b128 v[190:193], v157 offset:18432
	ds_read_b128 v[194:197], v157 offset:19456
	ds_read_b128 v[198:201], v157 offset:20480
	ds_read_b128 v[202:205], v157 offset:21504
	ds_read_b128 v[206:209], v157 offset:22528
	ds_read_b128 v[210:213], v157 offset:23552
	global_load_lds_dwordx4 v130, s[56:57]
	s_add_i32 m0, s3, 0x2000
	s_add_u32 s64, s56, 0x20000
	s_addc_u32 s65, s57, 0
	s_add_i32 s3, s62, s8
	global_load_lds_dwordx4 v134, s[56:57]
	s_mov_b32 m0, s3
	s_nop 0
	global_load_lds_dwordx4 v130, s[64:65]
	s_add_i32 m0, s3, 0x2000
	s_nop 0
	global_load_lds_dwordx4 v134, s[64:65]
	s_mov_b32 m0, s9
	s_nop 0
	global_load_lds_dwordx4 v128, s[58:59]
	s_mov_b32 m0, s18
	s_nop 0
	global_load_lds_dwordx4 v132, s[58:59]
	s_waitcnt vmcnt(8)
	s_waitcnt lgkmcnt(0)
	s_barrier
	s_setprio 1
	v_mfma_f32_16x16x32_bf16 v[60:63], v[144:147], v[182:185], v[60:63]
	v_mfma_f32_16x16x32_bf16 v[56:59], v[158:161], v[182:185], v[56:59]
	v_mfma_f32_16x16x32_bf16 v[44:47], v[144:147], v[190:193], v[44:47]
	v_mfma_f32_16x16x32_bf16 v[40:43], v[158:161], v[190:193], v[40:43]
	v_mfma_f32_16x16x32_bf16 v[28:31], v[144:147], v[198:201], v[28:31]
	v_mfma_f32_16x16x32_bf16 v[24:27], v[158:161], v[198:201], v[24:27]
	v_mfma_f32_16x16x32_bf16 v[12:15], v[144:147], v[206:209], v[12:15]
	v_mfma_f32_16x16x32_bf16 v[8:11], v[158:161], v[206:209], v[8:11]
	v_mfma_f32_16x16x32_bf16 v[60:63], v[148:151], v[186:189], v[60:63]
	v_mfma_f32_16x16x32_bf16 v[56:59], v[162:165], v[186:189], v[56:59]
	v_mfma_f32_16x16x32_bf16 v[44:47], v[148:151], v[194:197], v[44:47]
	v_mfma_f32_16x16x32_bf16 v[40:43], v[162:165], v[194:197], v[40:43]
	v_mfma_f32_16x16x32_bf16 v[28:31], v[148:151], v[202:205], v[28:31]
	v_mfma_f32_16x16x32_bf16 v[24:27], v[162:165], v[202:205], v[24:27]
	v_mfma_f32_16x16x32_bf16 v[12:15], v[148:151], v[210:213], v[12:15]
	v_mfma_f32_16x16x32_bf16 v[8:11], v[162:165], v[210:213], v[8:11]
	v_mfma_f32_16x16x32_bf16 v[52:55], v[166:169], v[182:185], v[52:55]
	v_mfma_f32_16x16x32_bf16 v[48:51], v[174:177], v[182:185], v[48:51]
	v_mfma_f32_16x16x32_bf16 v[36:39], v[166:169], v[190:193], v[36:39]
	v_mfma_f32_16x16x32_bf16 v[32:35], v[174:177], v[190:193], v[32:35]
	v_mfma_f32_16x16x32_bf16 v[20:23], v[166:169], v[198:201], v[20:23]
	v_mfma_f32_16x16x32_bf16 v[16:19], v[174:177], v[198:201], v[16:19]
	v_mfma_f32_16x16x32_bf16 v[4:7], v[166:169], v[206:209], v[4:7]
	v_mfma_f32_16x16x32_bf16 v[0:3], v[174:177], v[206:209], v[0:3]
	v_mfma_f32_16x16x32_bf16 v[52:55], v[170:173], v[186:189], v[52:55]
	v_mfma_f32_16x16x32_bf16 v[48:51], v[178:181], v[186:189], v[48:51]
	v_mfma_f32_16x16x32_bf16 v[36:39], v[170:173], v[194:197], v[36:39]
	v_mfma_f32_16x16x32_bf16 v[32:35], v[178:181], v[194:197], v[32:35]
	v_mfma_f32_16x16x32_bf16 v[20:23], v[170:173], v[202:205], v[20:23]
	v_mfma_f32_16x16x32_bf16 v[16:19], v[178:181], v[202:205], v[16:19]
	v_mfma_f32_16x16x32_bf16 v[4:7], v[170:173], v[210:213], v[4:7]
	v_mfma_f32_16x16x32_bf16 v[0:3], v[178:181], v[210:213], v[0:3]
	s_setprio 0
	s_barrier
	s_add_i32 s3, 0, 0x18000
	s_add_i32 s51, 0, 0x1c000
	v_add_u32_e32 v162, s3, v153
	v_add_u32_e32 v178, s51, v153
	ds_read_b128 v[144:147], v162
	ds_read_b128 v[148:151], v162 offset:1024
	ds_read_b128 v[158:161], v162 offset:2048
	ds_read_b128 v[162:165], v162 offset:3072
	ds_read_b128 v[166:169], v178
	ds_read_b128 v[170:173], v178 offset:1024
	ds_read_b128 v[174:177], v178 offset:2048
	ds_read_b128 v[178:181], v178 offset:3072
	s_add_u32 s58, s58, 0x20000
	s_addc_u32 s59, s59, 0
	s_mov_b32 m0, s19
	ds_read_b128 v[182:185], v157 offset:32768
	ds_read_b128 v[186:189], v157 offset:33792
	ds_read_b128 v[190:193], v157 offset:34816
	ds_read_b128 v[194:197], v157 offset:35840
	ds_read_b128 v[198:201], v157 offset:36864
	ds_read_b128 v[202:205], v157 offset:37888
	ds_read_b128 v[206:209], v157 offset:38912
	ds_read_b128 v[210:213], v157 offset:39936
	global_load_lds_dwordx4 v128, s[58:59]
	s_mov_b32 m0, s25
	s_nop 0
	global_load_lds_dwordx4 v132, s[58:59]
	s_waitcnt vmcnt(8)
	s_waitcnt lgkmcnt(0)
	s_barrier
	s_setprio 1
	v_mfma_f32_16x16x32_bf16 v[124:127], v[144:147], v[182:185], v[124:127]
	v_mfma_f32_16x16x32_bf16 v[120:123], v[158:161], v[182:185], v[120:123]
	v_mfma_f32_16x16x32_bf16 v[108:111], v[144:147], v[190:193], v[108:111]
	v_mfma_f32_16x16x32_bf16 v[104:107], v[158:161], v[190:193], v[104:107]
	v_mfma_f32_16x16x32_bf16 v[92:95], v[144:147], v[198:201], v[92:95]
	v_mfma_f32_16x16x32_bf16 v[88:91], v[158:161], v[198:201], v[88:91]
	v_mfma_f32_16x16x32_bf16 v[76:79], v[144:147], v[206:209], v[76:79]
	v_mfma_f32_16x16x32_bf16 v[72:75], v[158:161], v[206:209], v[72:75]
	v_mfma_f32_16x16x32_bf16 v[124:127], v[148:151], v[186:189], v[124:127]
	v_mfma_f32_16x16x32_bf16 v[120:123], v[162:165], v[186:189], v[120:123]
	v_mfma_f32_16x16x32_bf16 v[108:111], v[148:151], v[194:197], v[108:111]
	v_mfma_f32_16x16x32_bf16 v[104:107], v[162:165], v[194:197], v[104:107]
	v_mfma_f32_16x16x32_bf16 v[92:95], v[148:151], v[202:205], v[92:95]
	v_mfma_f32_16x16x32_bf16 v[88:91], v[162:165], v[202:205], v[88:91]
	v_mfma_f32_16x16x32_bf16 v[76:79], v[148:151], v[210:213], v[76:79]
	v_mfma_f32_16x16x32_bf16 v[72:75], v[162:165], v[210:213], v[72:75]
	v_mfma_f32_16x16x32_bf16 v[116:119], v[166:169], v[182:185], v[116:119]
	v_mfma_f32_16x16x32_bf16 v[112:115], v[174:177], v[182:185], v[112:115]
	v_mfma_f32_16x16x32_bf16 v[100:103], v[166:169], v[190:193], v[100:103]
	v_mfma_f32_16x16x32_bf16 v[96:99], v[174:177], v[190:193], v[96:99]
	v_mfma_f32_16x16x32_bf16 v[84:87], v[166:169], v[198:201], v[84:87]
	v_mfma_f32_16x16x32_bf16 v[80:83], v[174:177], v[198:201], v[80:83]
	v_mfma_f32_16x16x32_bf16 v[68:71], v[166:169], v[206:209], v[68:71]
	v_mfma_f32_16x16x32_bf16 v[64:67], v[174:177], v[206:209], v[64:67]
	v_mfma_f32_16x16x32_bf16 v[116:119], v[170:173], v[186:189], v[116:119]
	v_mfma_f32_16x16x32_bf16 v[112:115], v[178:181], v[186:189], v[112:115]
	v_mfma_f32_16x16x32_bf16 v[100:103], v[170:173], v[194:197], v[100:103]
	v_mfma_f32_16x16x32_bf16 v[96:99], v[178:181], v[194:197], v[96:99]
	v_mfma_f32_16x16x32_bf16 v[84:87], v[170:173], v[202:205], v[84:87]
	v_mfma_f32_16x16x32_bf16 v[80:83], v[178:181], v[202:205], v[80:83]
	v_mfma_f32_16x16x32_bf16 v[68:71], v[170:173], v[210:213], v[68:71]
	v_mfma_f32_16x16x32_bf16 v[64:67], v[178:181], v[210:213], v[64:67]
	s_setprio 0
	s_barrier
	s_add_i32 s3, s3, s8
	s_add_u32 s56, s56, 0x80
	s_addc_u32 s57, s57, 0
	s_mov_b32 m0, s3
	ds_read_b128 v[182:185], v157 offset:49152
	ds_read_b128 v[186:189], v157 offset:50176
	ds_read_b128 v[190:193], v157 offset:51200
	ds_read_b128 v[194:197], v157 offset:52224
	ds_read_b128 v[198:201], v157 offset:53248
	ds_read_b128 v[202:205], v157 offset:54272
	ds_read_b128 v[206:209], v157 offset:55296
	ds_read_b128 v[210:213], v157 offset:56320
	global_load_lds_dwordx4 v130, s[56:57]
	s_add_i32 m0, s3, 0x2000
	s_add_i32 s3, s51, s8
	global_load_lds_dwordx4 v134, s[56:57]
	s_add_u32 s56, s56, 0x20000
	s_addc_u32 s57, s57, 0
	s_mov_b32 m0, s3
	s_nop 0
	global_load_lds_dwordx4 v130, s[56:57]
	s_add_i32 m0, s3, 0x2000
	s_nop 0
	global_load_lds_dwordx4 v134, s[56:57]
	s_add_u32 s58, s58, 0xfffe0080
	s_addc_u32 s59, s59, -1
	s_mov_b32 m0, s49
	s_nop 0
	global_load_lds_dwordx4 v128, s[58:59]
	s_mov_b32 m0, s60
	s_nop 0
	global_load_lds_dwordx4 v132, s[58:59]
	s_waitcnt vmcnt(8)
	s_waitcnt lgkmcnt(0)
	s_barrier
	s_setprio 1
	v_mfma_f32_16x16x32_bf16 v[60:63], v[144:147], v[182:185], v[60:63]
	v_mfma_f32_16x16x32_bf16 v[56:59], v[158:161], v[182:185], v[56:59]
	v_mfma_f32_16x16x32_bf16 v[44:47], v[144:147], v[190:193], v[44:47]
	v_mfma_f32_16x16x32_bf16 v[40:43], v[158:161], v[190:193], v[40:43]
	v_mfma_f32_16x16x32_bf16 v[28:31], v[144:147], v[198:201], v[28:31]
	v_mfma_f32_16x16x32_bf16 v[24:27], v[158:161], v[198:201], v[24:27]
	v_mfma_f32_16x16x32_bf16 v[12:15], v[144:147], v[206:209], v[12:15]
	v_mfma_f32_16x16x32_bf16 v[8:11], v[158:161], v[206:209], v[8:11]
	v_mfma_f32_16x16x32_bf16 v[60:63], v[148:151], v[186:189], v[60:63]
	v_mfma_f32_16x16x32_bf16 v[56:59], v[162:165], v[186:189], v[56:59]
	v_mfma_f32_16x16x32_bf16 v[44:47], v[148:151], v[194:197], v[44:47]
	v_mfma_f32_16x16x32_bf16 v[40:43], v[162:165], v[194:197], v[40:43]
	v_mfma_f32_16x16x32_bf16 v[28:31], v[148:151], v[202:205], v[28:31]
	v_mfma_f32_16x16x32_bf16 v[24:27], v[162:165], v[202:205], v[24:27]
	v_mfma_f32_16x16x32_bf16 v[12:15], v[148:151], v[210:213], v[12:15]
	v_mfma_f32_16x16x32_bf16 v[8:11], v[162:165], v[210:213], v[8:11]
	v_mfma_f32_16x16x32_bf16 v[52:55], v[166:169], v[182:185], v[52:55]
	v_mfma_f32_16x16x32_bf16 v[48:51], v[174:177], v[182:185], v[48:51]
	v_mfma_f32_16x16x32_bf16 v[36:39], v[166:169], v[190:193], v[36:39]
	v_mfma_f32_16x16x32_bf16 v[32:35], v[174:177], v[190:193], v[32:35]
	v_mfma_f32_16x16x32_bf16 v[20:23], v[166:169], v[198:201], v[20:23]
	v_mfma_f32_16x16x32_bf16 v[16:19], v[174:177], v[198:201], v[16:19]
	v_mfma_f32_16x16x32_bf16 v[4:7], v[166:169], v[206:209], v[4:7]
	v_mfma_f32_16x16x32_bf16 v[0:3], v[174:177], v[206:209], v[0:3]
	v_mfma_f32_16x16x32_bf16 v[52:55], v[170:173], v[186:189], v[52:55]
	v_mfma_f32_16x16x32_bf16 v[48:51], v[178:181], v[186:189], v[48:51]
	v_mfma_f32_16x16x32_bf16 v[36:39], v[170:173], v[194:197], v[36:39]
	v_mfma_f32_16x16x32_bf16 v[32:35], v[178:181], v[194:197], v[32:35]
	v_mfma_f32_16x16x32_bf16 v[20:23], v[170:173], v[202:205], v[20:23]
	v_mfma_f32_16x16x32_bf16 v[16:19], v[178:181], v[202:205], v[16:19]
	v_mfma_f32_16x16x32_bf16 v[4:7], v[170:173], v[210:213], v[4:7]
	v_mfma_f32_16x16x32_bf16 v[0:3], v[178:181], v[210:213], v[0:3]
	s_setprio 0
	s_add_i32 s50, s50, 2
	s_add_u32 s52, s52, 0x100
	s_addc_u32 s53, s53, 0
	s_add_u32 s44, s44, 0x100
	s_addc_u32 s45, s45, 0
	s_cmp_gt_u32 s50, 5
	s_barrier
	s_cbranch_scc0 .LBB0_2272
	s_and_b64 vcc, exec, s[12:13]
	s_cbranch_vccz .LBB0_2275
	s_barrier

.LBB0_2348:
	ds_read_b128 v[140:143], v149
	ds_read_b128 v[152:155], v149 offset:1024
	ds_read_b128 v[156:159], v149 offset:2048
	ds_read_b128 v[160:163], v149 offset:3072
	ds_read_b128 v[164:167], v150
	ds_read_b128 v[168:171], v150 offset:1024
	ds_read_b128 v[172:175], v150 offset:2048
	ds_read_b128 v[176:179], v150 offset:3072
	s_add_u32 s3, s66, 0xfff80080
	s_addc_u32 s59, s67, -1
	s_cmp_eq_u32 s57, 28
	s_cselect_b32 s75, s0, s59
	s_cselect_b32 s74, s1, s3
	s_cselect_b32 s73, s44, s51
	s_cselect_b32 s72, s45, s50
	s_add_i32 m0, s9, 0xc000
	ds_read_b128 v[180:183], v151
	ds_read_b128 v[184:187], v151 offset:1024
	ds_read_b128 v[188:191], v151 offset:2048
	ds_read_b128 v[192:195], v151 offset:3072
	ds_read_b128 v[196:199], v151 offset:4096
	ds_read_b128 v[200:203], v151 offset:5120
	ds_read_b128 v[204:207], v151 offset:6144
	ds_read_b128 v[208:211], v151 offset:7168
	global_load_lds_dwordx4 v132, s[66:67]
	s_add_i32 m0, s9, 0xe000
	s_nop 0
	global_load_lds_dwordx4 v134, s[66:67]
	s_waitcnt vmcnt(8)
	s_waitcnt lgkmcnt(0)
	s_barrier
	s_setprio 1
	v_mfma_f32_16x16x32_bf16 v[124:127], v[140:143], v[180:183], v[124:127]
	v_mfma_f32_16x16x32_bf16 v[120:123], v[156:159], v[180:183], v[120:123]
	v_mfma_f32_16x16x32_bf16 v[108:111], v[140:143], v[188:191], v[108:111]
	v_mfma_f32_16x16x32_bf16 v[104:107], v[156:159], v[188:191], v[104:107]
	v_mfma_f32_16x16x32_bf16 v[92:95], v[140:143], v[196:199], v[92:95]
	v_mfma_f32_16x16x32_bf16 v[88:91], v[156:159], v[196:199], v[88:91]
	v_mfma_f32_16x16x32_bf16 v[76:79], v[140:143], v[204:207], v[76:79]
	v_mfma_f32_16x16x32_bf16 v[72:75], v[156:159], v[204:207], v[72:75]
	v_mfma_f32_16x16x32_bf16 v[124:127], v[152:155], v[184:187], v[124:127]
	v_mfma_f32_16x16x32_bf16 v[120:123], v[160:163], v[184:187], v[120:123]
	v_mfma_f32_16x16x32_bf16 v[108:111], v[152:155], v[192:195], v[108:111]
	v_mfma_f32_16x16x32_bf16 v[104:107], v[160:163], v[192:195], v[104:107]
	v_mfma_f32_16x16x32_bf16 v[92:95], v[152:155], v[200:203], v[92:95]
	v_mfma_f32_16x16x32_bf16 v[88:91], v[160:163], v[200:203], v[88:91]
	v_mfma_f32_16x16x32_bf16 v[76:79], v[152:155], v[208:211], v[76:79]
	v_mfma_f32_16x16x32_bf16 v[72:75], v[160:163], v[208:211], v[72:75]
	v_mfma_f32_16x16x32_bf16 v[116:119], v[164:167], v[180:183], v[116:119]
	v_mfma_f32_16x16x32_bf16 v[112:115], v[172:175], v[180:183], v[112:115]
	v_mfma_f32_16x16x32_bf16 v[100:103], v[164:167], v[188:191], v[100:103]
	v_mfma_f32_16x16x32_bf16 v[96:99], v[172:175], v[188:191], v[96:99]
	v_mfma_f32_16x16x32_bf16 v[84:87], v[164:167], v[196:199], v[84:87]
	v_mfma_f32_16x16x32_bf16 v[80:83], v[172:175], v[196:199], v[80:83]
	v_mfma_f32_16x16x32_bf16 v[68:71], v[164:167], v[204:207], v[68:71]
	v_mfma_f32_16x16x32_bf16 v[64:67], v[172:175], v[204:207], v[64:67]
	v_mfma_f32_16x16x32_bf16 v[116:119], v[168:171], v[184:187], v[116:119]
	v_mfma_f32_16x16x32_bf16 v[112:115], v[176:179], v[184:187], v[112:115]
	v_mfma_f32_16x16x32_bf16 v[100:103], v[168:171], v[192:195], v[100:103]
	v_mfma_f32_16x16x32_bf16 v[96:99], v[176:179], v[192:195], v[96:99]
	v_mfma_f32_16x16x32_bf16 v[84:87], v[168:171], v[200:203], v[84:87]
	v_mfma_f32_16x16x32_bf16 v[80:83], v[176:179], v[200:203], v[80:83]
	v_mfma_f32_16x16x32_bf16 v[68:71], v[168:171], v[208:211], v[68:71]
	v_mfma_f32_16x16x32_bf16 v[64:67], v[176:179], v[208:211], v[64:67]
	s_setprio 0
	s_barrier
	s_add_i32 s3, s68, s8
	s_mov_b32 m0, s3
	ds_read_b128 v[180:183], v151 offset:16384
	ds_read_b128 v[184:187], v151 offset:17408
	ds_read_b128 v[188:191], v151 offset:18432
	ds_read_b128 v[192:195], v151 offset:19456
	ds_read_b128 v[196:199], v151 offset:20480
	ds_read_b128 v[200:203], v151 offset:21504
	ds_read_b128 v[204:207], v151 offset:22528
	ds_read_b128 v[208:211], v151 offset:23552
	global_load_lds_dwordx4 v128, s[72:73]
	s_add_i32 m0, s3, 0x2000
	s_add_u32 s70, s72, 0x80000
	s_addc_u32 s71, s73, 0
	s_add_i32 s3, s69, s8
	global_load_lds_dwordx4 v130, s[72:73]
	s_mov_b32 m0, s3
	s_nop 0
	global_load_lds_dwordx4 v128, s[70:71]
	s_add_i32 m0, s3, 0x2000
	s_nop 0
	global_load_lds_dwordx4 v130, s[70:71]
	s_mov_b32 m0, s9
	s_nop 0
	global_load_lds_dwordx4 v128, s[74:75]
	s_mov_b32 m0, s18
	s_nop 0
	global_load_lds_dwordx4 v130, s[74:75]
	s_waitcnt vmcnt(8)
	s_waitcnt lgkmcnt(0)
	s_barrier
	s_setprio 1
	v_mfma_f32_16x16x32_bf16 v[60:63], v[140:143], v[180:183], v[60:63]
	v_mfma_f32_16x16x32_bf16 v[56:59], v[156:159], v[180:183], v[56:59]
	v_mfma_f32_16x16x32_bf16 v[44:47], v[140:143], v[188:191], v[44:47]
	v_mfma_f32_16x16x32_bf16 v[40:43], v[156:159], v[188:191], v[40:43]
	v_mfma_f32_16x16x32_bf16 v[28:31], v[140:143], v[196:199], v[28:31]
	v_mfma_f32_16x16x32_bf16 v[24:27], v[156:159], v[196:199], v[24:27]
	v_mfma_f32_16x16x32_bf16 v[12:15], v[140:143], v[204:207], v[12:15]
	v_mfma_f32_16x16x32_bf16 v[8:11], v[156:159], v[204:207], v[8:11]
	v_mfma_f32_16x16x32_bf16 v[60:63], v[152:155], v[184:187], v[60:63]
	v_mfma_f32_16x16x32_bf16 v[56:59], v[160:163], v[184:187], v[56:59]
	v_mfma_f32_16x16x32_bf16 v[44:47], v[152:155], v[192:195], v[44:47]
	v_mfma_f32_16x16x32_bf16 v[40:43], v[160:163], v[192:195], v[40:43]
	v_mfma_f32_16x16x32_bf16 v[28:31], v[152:155], v[200:203], v[28:31]
	v_mfma_f32_16x16x32_bf16 v[24:27], v[160:163], v[200:203], v[24:27]
	v_mfma_f32_16x16x32_bf16 v[12:15], v[152:155], v[208:211], v[12:15]
	v_mfma_f32_16x16x32_bf16 v[8:11], v[160:163], v[208:211], v[8:11]
	v_mfma_f32_16x16x32_bf16 v[52:55], v[164:167], v[180:183], v[52:55]
	v_mfma_f32_16x16x32_bf16 v[48:51], v[172:175], v[180:183], v[48:51]
	v_mfma_f32_16x16x32_bf16 v[36:39], v[164:167], v[188:191], v[36:39]
	v_mfma_f32_16x16x32_bf16 v[32:35], v[172:175], v[188:191], v[32:35]
	v_mfma_f32_16x16x32_bf16 v[20:23], v[164:167], v[196:199], v[20:23]
	v_mfma_f32_16x16x32_bf16 v[16:19], v[172:175], v[196:199], v[16:19]
	v_mfma_f32_16x16x32_bf16 v[4:7], v[164:167], v[204:207], v[4:7]
	v_mfma_f32_16x16x32_bf16 v[0:3], v[172:175], v[204:207], v[0:3]
	v_mfma_f32_16x16x32_bf16 v[52:55], v[168:171], v[184:187], v[52:55]
	v_mfma_f32_16x16x32_bf16 v[48:51], v[176:179], v[184:187], v[48:51]
	v_mfma_f32_16x16x32_bf16 v[36:39], v[168:171], v[192:195], v[36:39]
	v_mfma_f32_16x16x32_bf16 v[32:35], v[176:179], v[192:195], v[32:35]
	v_mfma_f32_16x16x32_bf16 v[20:23], v[168:171], v[200:203], v[20:23]
	v_mfma_f32_16x16x32_bf16 v[16:19], v[176:179], v[200:203], v[16:19]
	v_mfma_f32_16x16x32_bf16 v[4:7], v[168:171], v[208:211], v[4:7]
	v_mfma_f32_16x16x32_bf16 v[0:3], v[176:179], v[208:211], v[0:3]
	s_setprio 0
	s_barrier
	s_add_i32 s3, 0, 0x18000
	s_add_i32 s59, 0, 0x1c000
	v_add_u32_e32 v160, s3, v147
	v_add_u32_e32 v176, s59, v147
	ds_read_b128 v[140:143], v160
	ds_read_b128 v[152:155], v160 offset:1024
	ds_read_b128 v[156:159], v160 offset:2048
	ds_read_b128 v[160:163], v160 offset:3072
	ds_read_b128 v[164:167], v176
	ds_read_b128 v[168:171], v176 offset:1024
	ds_read_b128 v[172:175], v176 offset:2048
	ds_read_b128 v[176:179], v176 offset:3072
	s_add_u32 s70, s74, 0x80000
	s_addc_u32 s71, s75, 0
	s_mov_b32 m0, s19
	ds_read_b128 v[180:183], v151 offset:32768
	ds_read_b128 v[184:187], v151 offset:33792
	ds_read_b128 v[188:191], v151 offset:34816
	ds_read_b128 v[192:195], v151 offset:35840
	ds_read_b128 v[196:199], v151 offset:36864
	ds_read_b128 v[200:203], v151 offset:37888
	ds_read_b128 v[204:207], v151 offset:38912
	ds_read_b128 v[208:211], v151 offset:39936
	global_load_lds_dwordx4 v128, s[70:71]
	s_mov_b32 m0, s25
	s_nop 0
	global_load_lds_dwordx4 v130, s[70:71]
	s_waitcnt vmcnt(8)
	s_waitcnt lgkmcnt(0)
	s_barrier
	s_setprio 1
	v_mfma_f32_16x16x32_bf16 v[124:127], v[140:143], v[180:183], v[124:127]
	v_mfma_f32_16x16x32_bf16 v[120:123], v[156:159], v[180:183], v[120:123]
	v_mfma_f32_16x16x32_bf16 v[108:111], v[140:143], v[188:191], v[108:111]
	v_mfma_f32_16x16x32_bf16 v[104:107], v[156:159], v[188:191], v[104:107]
	v_mfma_f32_16x16x32_bf16 v[92:95], v[140:143], v[196:199], v[92:95]
	v_mfma_f32_16x16x32_bf16 v[88:91], v[156:159], v[196:199], v[88:91]
	v_mfma_f32_16x16x32_bf16 v[76:79], v[140:143], v[204:207], v[76:79]
	v_mfma_f32_16x16x32_bf16 v[72:75], v[156:159], v[204:207], v[72:75]
	v_mfma_f32_16x16x32_bf16 v[124:127], v[152:155], v[184:187], v[124:127]
	v_mfma_f32_16x16x32_bf16 v[120:123], v[160:163], v[184:187], v[120:123]
	v_mfma_f32_16x16x32_bf16 v[108:111], v[152:155], v[192:195], v[108:111]
	v_mfma_f32_16x16x32_bf16 v[104:107], v[160:163], v[192:195], v[104:107]
	v_mfma_f32_16x16x32_bf16 v[92:95], v[152:155], v[200:203], v[92:95]
	v_mfma_f32_16x16x32_bf16 v[88:91], v[160:163], v[200:203], v[88:91]
	v_mfma_f32_16x16x32_bf16 v[76:79], v[152:155], v[208:211], v[76:79]
	v_mfma_f32_16x16x32_bf16 v[72:75], v[160:163], v[208:211], v[72:75]
	v_mfma_f32_16x16x32_bf16 v[116:119], v[164:167], v[180:183], v[116:119]
	v_mfma_f32_16x16x32_bf16 v[112:115], v[172:175], v[180:183], v[112:115]
	v_mfma_f32_16x16x32_bf16 v[100:103], v[164:167], v[188:191], v[100:103]
	v_mfma_f32_16x16x32_bf16 v[96:99], v[172:175], v[188:191], v[96:99]
	v_mfma_f32_16x16x32_bf16 v[84:87], v[164:167], v[196:199], v[84:87]
	v_mfma_f32_16x16x32_bf16 v[80:83], v[172:175], v[196:199], v[80:83]
	v_mfma_f32_16x16x32_bf16 v[68:71], v[164:167], v[204:207], v[68:71]
	v_mfma_f32_16x16x32_bf16 v[64:67], v[172:175], v[204:207], v[64:67]
	v_mfma_f32_16x16x32_bf16 v[116:119], v[168:171], v[184:187], v[116:119]
	v_mfma_f32_16x16x32_bf16 v[112:115], v[176:179], v[184:187], v[112:115]
	v_mfma_f32_16x16x32_bf16 v[100:103], v[168:171], v[192:195], v[100:103]
	v_mfma_f32_16x16x32_bf16 v[96:99], v[176:179], v[192:195], v[96:99]
	v_mfma_f32_16x16x32_bf16 v[84:87], v[168:171], v[200:203], v[84:87]
	v_mfma_f32_16x16x32_bf16 v[80:83], v[176:179], v[200:203], v[80:83]
	v_mfma_f32_16x16x32_bf16 v[68:71], v[168:171], v[208:211], v[68:71]
	v_mfma_f32_16x16x32_bf16 v[64:67], v[176:179], v[208:211], v[64:67]
	s_setprio 0
	s_barrier
	s_add_i32 s3, s3, s8
	s_add_u32 s70, s72, 0x80
	s_addc_u32 s71, s73, 0
	s_mov_b32 m0, s3
	ds_read_b128 v[180:183], v151 offset:49152
	ds_read_b128 v[184:187], v151 offset:50176
	ds_read_b128 v[188:191], v151 offset:51200
	ds_read_b128 v[192:195], v151 offset:52224
	ds_read_b128 v[196:199], v151 offset:53248
	ds_read_b128 v[200:203], v151 offset:54272
	ds_read_b128 v[204:207], v151 offset:55296
	ds_read_b128 v[208:211], v151 offset:56320
	global_load_lds_dwordx4 v128, s[70:71]
	s_add_i32 m0, s3, 0x2000
	s_add_i32 s3, s59, s8
	global_load_lds_dwordx4 v130, s[70:71]
	s_add_u32 s70, s70, 0x80000
	s_addc_u32 s71, s71, 0
	s_mov_b32 m0, s3
	s_nop 0
	global_load_lds_dwordx4 v128, s[70:71]
	s_add_i32 m0, s3, 0x2000
	s_nop 0
	global_load_lds_dwordx4 v130, s[70:71]
	s_add_u32 s74, s74, 0x80
	s_addc_u32 s75, s75, 0
	s_mov_b32 m0, s33
	s_nop 0
	global_load_lds_dwordx4 v128, s[74:75]
	s_mov_b32 m0, s65
	s_nop 0
	global_load_lds_dwordx4 v130, s[74:75]
	s_waitcnt vmcnt(8)
	s_waitcnt lgkmcnt(0)
	s_barrier
	s_setprio 1
	v_mfma_f32_16x16x32_bf16 v[60:63], v[140:143], v[180:183], v[60:63]
	v_mfma_f32_16x16x32_bf16 v[56:59], v[156:159], v[180:183], v[56:59]
	v_mfma_f32_16x16x32_bf16 v[44:47], v[140:143], v[188:191], v[44:47]
	v_mfma_f32_16x16x32_bf16 v[40:43], v[156:159], v[188:191], v[40:43]
	v_mfma_f32_16x16x32_bf16 v[28:31], v[140:143], v[196:199], v[28:31]
	v_mfma_f32_16x16x32_bf16 v[24:27], v[156:159], v[196:199], v[24:27]
	v_mfma_f32_16x16x32_bf16 v[12:15], v[140:143], v[204:207], v[12:15]
	v_mfma_f32_16x16x32_bf16 v[8:11], v[156:159], v[204:207], v[8:11]
	v_mfma_f32_16x16x32_bf16 v[60:63], v[152:155], v[184:187], v[60:63]
	v_mfma_f32_16x16x32_bf16 v[56:59], v[160:163], v[184:187], v[56:59]
	v_mfma_f32_16x16x32_bf16 v[44:47], v[152:155], v[192:195], v[44:47]
	v_mfma_f32_16x16x32_bf16 v[40:43], v[160:163], v[192:195], v[40:43]
	v_mfma_f32_16x16x32_bf16 v[28:31], v[152:155], v[200:203], v[28:31]
	v_mfma_f32_16x16x32_bf16 v[24:27], v[160:163], v[200:203], v[24:27]
	v_mfma_f32_16x16x32_bf16 v[12:15], v[152:155], v[208:211], v[12:15]
	v_mfma_f32_16x16x32_bf16 v[8:11], v[160:163], v[208:211], v[8:11]
	v_mfma_f32_16x16x32_bf16 v[52:55], v[164:167], v[180:183], v[52:55]
	v_mfma_f32_16x16x32_bf16 v[48:51], v[172:175], v[180:183], v[48:51]
	v_mfma_f32_16x16x32_bf16 v[36:39], v[164:167], v[188:191], v[36:39]
	v_mfma_f32_16x16x32_bf16 v[32:35], v[172:175], v[188:191], v[32:35]
	v_mfma_f32_16x16x32_bf16 v[20:23], v[164:167], v[196:199], v[20:23]
	v_mfma_f32_16x16x32_bf16 v[16:19], v[172:175], v[196:199], v[16:19]
	v_mfma_f32_16x16x32_bf16 v[4:7], v[164:167], v[204:207], v[4:7]
	v_mfma_f32_16x16x32_bf16 v[0:3], v[172:175], v[204:207], v[0:3]
	v_mfma_f32_16x16x32_bf16 v[52:55], v[168:171], v[184:187], v[52:55]
	v_mfma_f32_16x16x32_bf16 v[48:51], v[176:179], v[184:187], v[48:51]
	v_mfma_f32_16x16x32_bf16 v[36:39], v[168:171], v[192:195], v[36:39]
	v_mfma_f32_16x16x32_bf16 v[32:35], v[176:179], v[192:195], v[32:35]
	v_mfma_f32_16x16x32_bf16 v[20:23], v[168:171], v[200:203], v[20:23]
	v_mfma_f32_16x16x32_bf16 v[16:19], v[176:179], v[200:203], v[16:19]
	v_mfma_f32_16x16x32_bf16 v[4:7], v[168:171], v[208:211], v[4:7]
	v_mfma_f32_16x16x32_bf16 v[0:3], v[176:179], v[208:211], v[0:3]
	s_setprio 0
	s_add_i32 s57, s57, 2
	s_add_u32 s66, s66, 0x100
	s_addc_u32 s67, s67, 0
	s_add_u32 s50, s50, 0x100
	s_addc_u32 s51, s51, 0
	s_cmp_gt_u32 s57, 29
	s_barrier
	s_cbranch_scc0 .LBB0_2348
	s_and_b64 vcc, exec, s[14:15]
	s_cbranch_vccz .LBB0_2351
	s_barrier

.LBB0_2479:
	ds_read_b128 v[154:157], v150
	ds_read_b128 v[158:161], v150 offset:1024
	ds_read_b128 v[162:165], v150 offset:2048
	ds_read_b128 v[166:169], v150 offset:3072
	ds_read_b128 v[170:173], v151
	ds_read_b128 v[174:177], v151 offset:1024
	ds_read_b128 v[178:181], v151 offset:2048
	ds_read_b128 v[182:185], v151 offset:3072
	s_add_u32 s3, s42, 0xfff80080
	s_addc_u32 s44, s43, -1
	s_cmp_eq_u32 s51, 28
	s_cselect_b32 s49, s0, s44
	s_cselect_b32 s48, s1, s3
	s_cselect_b32 s45, s15, s50
	s_cselect_b32 s44, s17, s41
	s_add_i32 m0, s19, 0xc000
	ds_read_b128 v[186:189], v152
	ds_read_b128 v[190:193], v152 offset:1024
	ds_read_b128 v[194:197], v152 offset:2048
	ds_read_b128 v[198:201], v152 offset:3072
	ds_read_b128 v[202:205], v152 offset:4096
	ds_read_b128 v[206:209], v152 offset:5120
	ds_read_b128 v[210:213], v152 offset:6144
	ds_read_b128 v[214:217], v152 offset:7168
	global_load_lds_dwordx4 v138, s[42:43]
	s_add_i32 m0, s19, 0xe000
	s_nop 0
	global_load_lds_dwordx4 v140, s[42:43]
	s_waitcnt vmcnt(8)
	s_waitcnt lgkmcnt(0)
	s_barrier
	s_setprio 1
	v_mfma_f32_16x16x32_bf16 v[124:127], v[154:157], v[186:189], v[124:127]
	v_mfma_f32_16x16x32_bf16 v[120:123], v[162:165], v[186:189], v[120:123]
	v_mfma_f32_16x16x32_bf16 v[108:111], v[154:157], v[194:197], v[108:111]
	v_mfma_f32_16x16x32_bf16 v[104:107], v[162:165], v[194:197], v[104:107]
	v_mfma_f32_16x16x32_bf16 v[92:95], v[154:157], v[202:205], v[92:95]
	v_mfma_f32_16x16x32_bf16 v[88:91], v[162:165], v[202:205], v[88:91]
	v_mfma_f32_16x16x32_bf16 v[76:79], v[154:157], v[210:213], v[76:79]
	v_mfma_f32_16x16x32_bf16 v[72:75], v[162:165], v[210:213], v[72:75]
	v_mfma_f32_16x16x32_bf16 v[124:127], v[158:161], v[190:193], v[124:127]
	v_mfma_f32_16x16x32_bf16 v[120:123], v[166:169], v[190:193], v[120:123]
	v_mfma_f32_16x16x32_bf16 v[108:111], v[158:161], v[198:201], v[108:111]
	v_mfma_f32_16x16x32_bf16 v[104:107], v[166:169], v[198:201], v[104:107]
	v_mfma_f32_16x16x32_bf16 v[92:95], v[158:161], v[206:209], v[92:95]
	v_mfma_f32_16x16x32_bf16 v[88:91], v[166:169], v[206:209], v[88:91]
	v_mfma_f32_16x16x32_bf16 v[76:79], v[158:161], v[214:217], v[76:79]
	v_mfma_f32_16x16x32_bf16 v[72:75], v[166:169], v[214:217], v[72:75]
	v_mfma_f32_16x16x32_bf16 v[116:119], v[170:173], v[186:189], v[116:119]
	v_mfma_f32_16x16x32_bf16 v[112:115], v[178:181], v[186:189], v[112:115]
	v_mfma_f32_16x16x32_bf16 v[100:103], v[170:173], v[194:197], v[100:103]
	v_mfma_f32_16x16x32_bf16 v[96:99], v[178:181], v[194:197], v[96:99]
	v_mfma_f32_16x16x32_bf16 v[84:87], v[170:173], v[202:205], v[84:87]
	v_mfma_f32_16x16x32_bf16 v[80:83], v[178:181], v[202:205], v[80:83]
	v_mfma_f32_16x16x32_bf16 v[68:71], v[170:173], v[210:213], v[68:71]
	v_mfma_f32_16x16x32_bf16 v[64:67], v[178:181], v[210:213], v[64:67]
	v_mfma_f32_16x16x32_bf16 v[116:119], v[174:177], v[190:193], v[116:119]
	v_mfma_f32_16x16x32_bf16 v[112:115], v[182:185], v[190:193], v[112:115]
	v_mfma_f32_16x16x32_bf16 v[100:103], v[174:177], v[198:201], v[100:103]
	v_mfma_f32_16x16x32_bf16 v[96:99], v[182:185], v[198:201], v[96:99]
	v_mfma_f32_16x16x32_bf16 v[84:87], v[174:177], v[206:209], v[84:87]
	v_mfma_f32_16x16x32_bf16 v[80:83], v[182:185], v[206:209], v[80:83]
	v_mfma_f32_16x16x32_bf16 v[68:71], v[174:177], v[214:217], v[68:71]
	v_mfma_f32_16x16x32_bf16 v[64:67], v[182:185], v[214:217], v[64:67]
	s_setprio 0
	s_barrier
	s_add_i32 s3, s54, s18
	s_mov_b32 m0, s3
	ds_read_b128 v[186:189], v152 offset:16384
	ds_read_b128 v[190:193], v152 offset:17408
	ds_read_b128 v[194:197], v152 offset:18432
	ds_read_b128 v[198:201], v152 offset:19456
	ds_read_b128 v[202:205], v152 offset:20480
	ds_read_b128 v[206:209], v152 offset:21504
	ds_read_b128 v[210:213], v152 offset:22528
	ds_read_b128 v[214:217], v152 offset:23552
	global_load_lds_dwordx4 v130, s[44:45]
	s_add_i32 m0, s3, 0x2000
	s_add_u32 s58, s44, 0x80000
	s_addc_u32 s59, s45, 0
	s_add_i32 s3, s55, s18
	global_load_lds_dwordx4 v134, s[44:45]
	s_mov_b32 m0, s3
	s_nop 0
	global_load_lds_dwordx4 v130, s[58:59]
	s_add_i32 m0, s3, 0x2000
	s_nop 0
	global_load_lds_dwordx4 v134, s[58:59]
	s_mov_b32 m0, s19
	s_nop 0
	global_load_lds_dwordx4 v128, s[48:49]
	s_mov_b32 m0, s25
	s_nop 0
	global_load_lds_dwordx4 v132, s[48:49]
	s_waitcnt vmcnt(8)
	s_waitcnt lgkmcnt(0)
	s_barrier
	s_setprio 1
	v_mfma_f32_16x16x32_bf16 v[60:63], v[154:157], v[186:189], v[60:63]
	v_mfma_f32_16x16x32_bf16 v[56:59], v[162:165], v[186:189], v[56:59]
	v_mfma_f32_16x16x32_bf16 v[44:47], v[154:157], v[194:197], v[44:47]
	v_mfma_f32_16x16x32_bf16 v[40:43], v[162:165], v[194:197], v[40:43]
	v_mfma_f32_16x16x32_bf16 v[28:31], v[154:157], v[202:205], v[28:31]
	v_mfma_f32_16x16x32_bf16 v[24:27], v[162:165], v[202:205], v[24:27]
	v_mfma_f32_16x16x32_bf16 v[12:15], v[154:157], v[210:213], v[12:15]
	v_mfma_f32_16x16x32_bf16 v[8:11], v[162:165], v[210:213], v[8:11]
	v_mfma_f32_16x16x32_bf16 v[60:63], v[158:161], v[190:193], v[60:63]
	v_mfma_f32_16x16x32_bf16 v[56:59], v[166:169], v[190:193], v[56:59]
	v_mfma_f32_16x16x32_bf16 v[44:47], v[158:161], v[198:201], v[44:47]
	v_mfma_f32_16x16x32_bf16 v[40:43], v[166:169], v[198:201], v[40:43]
	v_mfma_f32_16x16x32_bf16 v[28:31], v[158:161], v[206:209], v[28:31]
	v_mfma_f32_16x16x32_bf16 v[24:27], v[166:169], v[206:209], v[24:27]
	v_mfma_f32_16x16x32_bf16 v[12:15], v[158:161], v[214:217], v[12:15]
	v_mfma_f32_16x16x32_bf16 v[8:11], v[166:169], v[214:217], v[8:11]
	v_mfma_f32_16x16x32_bf16 v[52:55], v[170:173], v[186:189], v[52:55]
	v_mfma_f32_16x16x32_bf16 v[48:51], v[178:181], v[186:189], v[48:51]
	v_mfma_f32_16x16x32_bf16 v[36:39], v[170:173], v[194:197], v[36:39]
	v_mfma_f32_16x16x32_bf16 v[32:35], v[178:181], v[194:197], v[32:35]
	v_mfma_f32_16x16x32_bf16 v[20:23], v[170:173], v[202:205], v[20:23]
	v_mfma_f32_16x16x32_bf16 v[16:19], v[178:181], v[202:205], v[16:19]
	v_mfma_f32_16x16x32_bf16 v[4:7], v[170:173], v[210:213], v[4:7]
	v_mfma_f32_16x16x32_bf16 v[0:3], v[178:181], v[210:213], v[0:3]
	v_mfma_f32_16x16x32_bf16 v[52:55], v[174:177], v[190:193], v[52:55]
	v_mfma_f32_16x16x32_bf16 v[48:51], v[182:185], v[190:193], v[48:51]
	v_mfma_f32_16x16x32_bf16 v[36:39], v[174:177], v[198:201], v[36:39]
	v_mfma_f32_16x16x32_bf16 v[32:35], v[182:185], v[198:201], v[32:35]
	v_mfma_f32_16x16x32_bf16 v[20:23], v[174:177], v[206:209], v[20:23]
	v_mfma_f32_16x16x32_bf16 v[16:19], v[182:185], v[206:209], v[16:19]
	v_mfma_f32_16x16x32_bf16 v[4:7], v[174:177], v[214:217], v[4:7]
	v_mfma_f32_16x16x32_bf16 v[0:3], v[182:185], v[214:217], v[0:3]
	s_setprio 0
	s_barrier
	s_add_i32 s3, 0, 0x18000
	v_add_u32_e32 v153, s3, v149
	s_add_i32 s57, 0, 0x1c000
	ds_read_b128 v[154:157], v153
	ds_read_b128 v[158:161], v153 offset:1024
	ds_read_b128 v[162:165], v153 offset:2048
	ds_read_b128 v[166:169], v153 offset:3072
	v_add_u32_e32 v153, s57, v149
	ds_read_b128 v[170:173], v153
	ds_read_b128 v[174:177], v153 offset:1024
	ds_read_b128 v[178:181], v153 offset:2048
	ds_read_b128 v[182:185], v153 offset:3072
	s_add_u32 s48, s48, 0x80000
	s_addc_u32 s49, s49, 0
	s_mov_b32 m0, s27
	ds_read_b128 v[186:189], v152 offset:32768
	ds_read_b128 v[190:193], v152 offset:33792
	ds_read_b128 v[194:197], v152 offset:34816
	ds_read_b128 v[198:201], v152 offset:35840
	ds_read_b128 v[202:205], v152 offset:36864
	ds_read_b128 v[206:209], v152 offset:37888
	ds_read_b128 v[210:213], v152 offset:38912
	ds_read_b128 v[214:217], v152 offset:39936
	global_load_lds_dwordx4 v128, s[48:49]
	s_mov_b32 m0, s33
	s_nop 0
	global_load_lds_dwordx4 v132, s[48:49]
	s_waitcnt vmcnt(8)
	s_waitcnt lgkmcnt(0)
	s_barrier
	s_setprio 1
	v_mfma_f32_16x16x32_bf16 v[124:127], v[154:157], v[186:189], v[124:127]
	v_mfma_f32_16x16x32_bf16 v[120:123], v[162:165], v[186:189], v[120:123]
	v_mfma_f32_16x16x32_bf16 v[108:111], v[154:157], v[194:197], v[108:111]
	v_mfma_f32_16x16x32_bf16 v[104:107], v[162:165], v[194:197], v[104:107]
	v_mfma_f32_16x16x32_bf16 v[92:95], v[154:157], v[202:205], v[92:95]
	v_mfma_f32_16x16x32_bf16 v[88:91], v[162:165], v[202:205], v[88:91]
	v_mfma_f32_16x16x32_bf16 v[76:79], v[154:157], v[210:213], v[76:79]
	v_mfma_f32_16x16x32_bf16 v[72:75], v[162:165], v[210:213], v[72:75]
	v_mfma_f32_16x16x32_bf16 v[124:127], v[158:161], v[190:193], v[124:127]
	v_mfma_f32_16x16x32_bf16 v[120:123], v[166:169], v[190:193], v[120:123]
	v_mfma_f32_16x16x32_bf16 v[108:111], v[158:161], v[198:201], v[108:111]
	v_mfma_f32_16x16x32_bf16 v[104:107], v[166:169], v[198:201], v[104:107]
	v_mfma_f32_16x16x32_bf16 v[92:95], v[158:161], v[206:209], v[92:95]
	v_mfma_f32_16x16x32_bf16 v[88:91], v[166:169], v[206:209], v[88:91]
	v_mfma_f32_16x16x32_bf16 v[76:79], v[158:161], v[214:217], v[76:79]
	v_mfma_f32_16x16x32_bf16 v[72:75], v[166:169], v[214:217], v[72:75]
	v_mfma_f32_16x16x32_bf16 v[116:119], v[170:173], v[186:189], v[116:119]
	v_mfma_f32_16x16x32_bf16 v[112:115], v[178:181], v[186:189], v[112:115]
	v_mfma_f32_16x16x32_bf16 v[100:103], v[170:173], v[194:197], v[100:103]
	v_mfma_f32_16x16x32_bf16 v[96:99], v[178:181], v[194:197], v[96:99]
	v_mfma_f32_16x16x32_bf16 v[84:87], v[170:173], v[202:205], v[84:87]
	v_mfma_f32_16x16x32_bf16 v[80:83], v[178:181], v[202:205], v[80:83]
	v_mfma_f32_16x16x32_bf16 v[68:71], v[170:173], v[210:213], v[68:71]
	v_mfma_f32_16x16x32_bf16 v[64:67], v[178:181], v[210:213], v[64:67]
	v_mfma_f32_16x16x32_bf16 v[116:119], v[174:177], v[190:193], v[116:119]
	v_mfma_f32_16x16x32_bf16 v[112:115], v[182:185], v[190:193], v[112:115]
	v_mfma_f32_16x16x32_bf16 v[100:103], v[174:177], v[198:201], v[100:103]
	v_mfma_f32_16x16x32_bf16 v[96:99], v[182:185], v[198:201], v[96:99]
	v_mfma_f32_16x16x32_bf16 v[84:87], v[174:177], v[206:209], v[84:87]
	v_mfma_f32_16x16x32_bf16 v[80:83], v[182:185], v[206:209], v[80:83]
	v_mfma_f32_16x16x32_bf16 v[68:71], v[174:177], v[214:217], v[68:71]
	v_mfma_f32_16x16x32_bf16 v[64:67], v[182:185], v[214:217], v[64:67]
	s_setprio 0
	s_barrier
	s_add_i32 s3, s3, s18
	s_add_u32 s44, s44, 0x80
	s_addc_u32 s45, s45, 0
	s_mov_b32 m0, s3
	ds_read_b128 v[186:189], v152 offset:49152
	ds_read_b128 v[190:193], v152 offset:50176
	ds_read_b128 v[194:197], v152 offset:51200
	ds_read_b128 v[198:201], v152 offset:52224
	ds_read_b128 v[202:205], v152 offset:53248
	ds_read_b128 v[206:209], v152 offset:54272
	ds_read_b128 v[210:213], v152 offset:55296
	ds_read_b128 v[214:217], v152 offset:56320
	global_load_lds_dwordx4 v130, s[44:45]
	s_add_i32 m0, s3, 0x2000
	s_add_i32 s3, s57, s18
	global_load_lds_dwordx4 v134, s[44:45]
	s_add_u32 s44, s44, 0x80000
	s_addc_u32 s45, s45, 0
	s_mov_b32 m0, s3
	s_nop 0
	global_load_lds_dwordx4 v130, s[44:45]
	s_add_i32 m0, s3, 0x2000
	s_nop 0
	global_load_lds_dwordx4 v134, s[44:45]
	s_add_u32 s48, s48, 0xfff80080
	s_addc_u32 s49, s49, -1
	s_mov_b32 m0, s52
	s_nop 0
	global_load_lds_dwordx4 v128, s[48:49]
	s_mov_b32 m0, s53
	s_nop 0
	global_load_lds_dwordx4 v132, s[48:49]
	s_waitcnt vmcnt(8)
	s_waitcnt lgkmcnt(0)
	s_barrier
	s_setprio 1
	v_mfma_f32_16x16x32_bf16 v[60:63], v[154:157], v[186:189], v[60:63]
	v_mfma_f32_16x16x32_bf16 v[56:59], v[162:165], v[186:189], v[56:59]
	v_mfma_f32_16x16x32_bf16 v[44:47], v[154:157], v[194:197], v[44:47]
	v_mfma_f32_16x16x32_bf16 v[40:43], v[162:165], v[194:197], v[40:43]
	v_mfma_f32_16x16x32_bf16 v[28:31], v[154:157], v[202:205], v[28:31]
	v_mfma_f32_16x16x32_bf16 v[24:27], v[162:165], v[202:205], v[24:27]
	v_mfma_f32_16x16x32_bf16 v[12:15], v[154:157], v[210:213], v[12:15]
	v_mfma_f32_16x16x32_bf16 v[8:11], v[162:165], v[210:213], v[8:11]
	v_mfma_f32_16x16x32_bf16 v[60:63], v[158:161], v[190:193], v[60:63]
	v_mfma_f32_16x16x32_bf16 v[56:59], v[166:169], v[190:193], v[56:59]
	v_mfma_f32_16x16x32_bf16 v[44:47], v[158:161], v[198:201], v[44:47]
	v_mfma_f32_16x16x32_bf16 v[40:43], v[166:169], v[198:201], v[40:43]
	v_mfma_f32_16x16x32_bf16 v[28:31], v[158:161], v[206:209], v[28:31]
	v_mfma_f32_16x16x32_bf16 v[24:27], v[166:169], v[206:209], v[24:27]
	v_mfma_f32_16x16x32_bf16 v[12:15], v[158:161], v[214:217], v[12:15]
	v_mfma_f32_16x16x32_bf16 v[8:11], v[166:169], v[214:217], v[8:11]
	v_mfma_f32_16x16x32_bf16 v[52:55], v[170:173], v[186:189], v[52:55]
	v_mfma_f32_16x16x32_bf16 v[48:51], v[178:181], v[186:189], v[48:51]
	v_mfma_f32_16x16x32_bf16 v[36:39], v[170:173], v[194:197], v[36:39]
	v_mfma_f32_16x16x32_bf16 v[32:35], v[178:181], v[194:197], v[32:35]
	v_mfma_f32_16x16x32_bf16 v[20:23], v[170:173], v[202:205], v[20:23]
	v_mfma_f32_16x16x32_bf16 v[16:19], v[178:181], v[202:205], v[16:19]
	v_mfma_f32_16x16x32_bf16 v[4:7], v[170:173], v[210:213], v[4:7]
	v_mfma_f32_16x16x32_bf16 v[0:3], v[178:181], v[210:213], v[0:3]
	v_mfma_f32_16x16x32_bf16 v[52:55], v[174:177], v[190:193], v[52:55]
	v_mfma_f32_16x16x32_bf16 v[48:51], v[182:185], v[190:193], v[48:51]
	v_mfma_f32_16x16x32_bf16 v[36:39], v[174:177], v[198:201], v[36:39]
	v_mfma_f32_16x16x32_bf16 v[32:35], v[182:185], v[198:201], v[32:35]
	v_mfma_f32_16x16x32_bf16 v[20:23], v[174:177], v[206:209], v[20:23]
	v_mfma_f32_16x16x32_bf16 v[16:19], v[182:185], v[206:209], v[16:19]
	v_mfma_f32_16x16x32_bf16 v[4:7], v[174:177], v[214:217], v[4:7]
	v_mfma_f32_16x16x32_bf16 v[0:3], v[182:185], v[214:217], v[0:3]
	s_setprio 0
	s_add_i32 s51, s51, 2
	s_add_u32 s42, s42, 0x100
	s_addc_u32 s43, s43, 0
	s_add_u32 s41, s41, 0x100
	s_addc_u32 s50, s50, 0
	s_cmp_gt_u32 s51, 29
	s_barrier
	s_cbranch_scc0 .LBB0_2479
	s_and_b64 vcc, exec, s[12:13]
	s_cbranch_vccz .LBB0_2482
	s_barrier

.LBB0_2555:
	ds_read_b128 v[140:143], v149
	ds_read_b128 v[152:155], v149 offset:1024
	ds_read_b128 v[156:159], v149 offset:2048
	ds_read_b128 v[160:163], v149 offset:3072
	ds_read_b128 v[164:167], v150
	ds_read_b128 v[168:171], v150 offset:1024
	ds_read_b128 v[172:175], v150 offset:2048
	ds_read_b128 v[176:179], v150 offset:3072
	s_add_u32 s3, s48, 0xffe00080
	s_addc_u32 s52, s49, -1
	s_cmpk_eq_i32 s64, 0x7c
	s_cselect_b32 s55, s0, s52
	s_cselect_b32 s54, s1, s3
	s_cselect_b32 s53, s35, s51
	s_cselect_b32 s52, s37, s50
	s_add_i32 m0, s27, 0xc000
	ds_read_b128 v[180:183], v151
	ds_read_b128 v[184:187], v151 offset:1024
	ds_read_b128 v[188:191], v151 offset:2048
	ds_read_b128 v[192:195], v151 offset:3072
	ds_read_b128 v[196:199], v151 offset:4096
	ds_read_b128 v[200:203], v151 offset:5120
	ds_read_b128 v[204:207], v151 offset:6144
	ds_read_b128 v[208:211], v151 offset:7168
	global_load_lds_dwordx4 v132, s[48:49]
	s_add_i32 m0, s27, 0xe000
	s_nop 0
	global_load_lds_dwordx4 v134, s[48:49]
	s_waitcnt vmcnt(8)
	s_waitcnt lgkmcnt(0)
	s_barrier
	s_setprio 1
	v_mfma_f32_16x16x32_bf16 v[124:127], v[140:143], v[180:183], v[124:127]
	v_mfma_f32_16x16x32_bf16 v[120:123], v[156:159], v[180:183], v[120:123]
	v_mfma_f32_16x16x32_bf16 v[112:115], v[140:143], v[188:191], v[112:115]
	v_mfma_f32_16x16x32_bf16 v[104:107], v[156:159], v[188:191], v[104:107]
	v_mfma_f32_16x16x32_bf16 v[96:99], v[140:143], v[196:199], v[96:99]
	v_mfma_f32_16x16x32_bf16 v[88:91], v[156:159], v[196:199], v[88:91]
	v_mfma_f32_16x16x32_bf16 v[80:83], v[140:143], v[204:207], v[80:83]
	v_mfma_f32_16x16x32_bf16 v[72:75], v[156:159], v[204:207], v[72:75]
	v_mfma_f32_16x16x32_bf16 v[124:127], v[152:155], v[184:187], v[124:127]
	v_mfma_f32_16x16x32_bf16 v[120:123], v[160:163], v[184:187], v[120:123]
	v_mfma_f32_16x16x32_bf16 v[112:115], v[152:155], v[192:195], v[112:115]
	v_mfma_f32_16x16x32_bf16 v[104:107], v[160:163], v[192:195], v[104:107]
	v_mfma_f32_16x16x32_bf16 v[96:99], v[152:155], v[200:203], v[96:99]
	v_mfma_f32_16x16x32_bf16 v[88:91], v[160:163], v[200:203], v[88:91]
	v_mfma_f32_16x16x32_bf16 v[80:83], v[152:155], v[208:211], v[80:83]
	v_mfma_f32_16x16x32_bf16 v[72:75], v[160:163], v[208:211], v[72:75]
	v_mfma_f32_16x16x32_bf16 v[116:119], v[164:167], v[180:183], v[116:119]
	v_mfma_f32_16x16x32_bf16 v[108:111], v[172:175], v[180:183], v[108:111]
	v_mfma_f32_16x16x32_bf16 v[100:103], v[164:167], v[188:191], v[100:103]
	v_mfma_f32_16x16x32_bf16 v[92:95], v[172:175], v[188:191], v[92:95]
	v_mfma_f32_16x16x32_bf16 v[84:87], v[164:167], v[196:199], v[84:87]
	v_mfma_f32_16x16x32_bf16 v[76:79], v[172:175], v[196:199], v[76:79]
	v_mfma_f32_16x16x32_bf16 v[68:71], v[164:167], v[204:207], v[68:71]
	v_mfma_f32_16x16x32_bf16 v[64:67], v[172:175], v[204:207], v[64:67]
	v_mfma_f32_16x16x32_bf16 v[116:119], v[168:171], v[184:187], v[116:119]
	v_mfma_f32_16x16x32_bf16 v[108:111], v[176:179], v[184:187], v[108:111]
	v_mfma_f32_16x16x32_bf16 v[100:103], v[168:171], v[192:195], v[100:103]
	v_mfma_f32_16x16x32_bf16 v[92:95], v[176:179], v[192:195], v[92:95]
	v_mfma_f32_16x16x32_bf16 v[84:87], v[168:171], v[200:203], v[84:87]
	v_mfma_f32_16x16x32_bf16 v[76:79], v[176:179], v[200:203], v[76:79]
	v_mfma_f32_16x16x32_bf16 v[68:71], v[168:171], v[208:211], v[68:71]
	v_mfma_f32_16x16x32_bf16 v[64:67], v[176:179], v[208:211], v[64:67]
	s_setprio 0
	s_barrier
	s_add_i32 s3, s58, s25
	s_mov_b32 m0, s3
	ds_read_b128 v[180:183], v151 offset:16384
	ds_read_b128 v[184:187], v151 offset:17408
	ds_read_b128 v[188:191], v151 offset:18432
	ds_read_b128 v[192:195], v151 offset:19456
	ds_read_b128 v[196:199], v151 offset:20480
	ds_read_b128 v[200:203], v151 offset:21504
	ds_read_b128 v[204:207], v151 offset:22528
	ds_read_b128 v[208:211], v151 offset:23552
	global_load_lds_dwordx4 v128, s[52:53]
	s_add_i32 m0, s3, 0x2000
	s_add_u32 s66, s52, 0x200000
	s_addc_u32 s67, s53, 0
	s_add_i32 s3, s59, s25
	global_load_lds_dwordx4 v130, s[52:53]
	s_mov_b32 m0, s3
	s_nop 0
	global_load_lds_dwordx4 v128, s[66:67]
	s_add_i32 m0, s3, 0x2000
	s_nop 0
	global_load_lds_dwordx4 v130, s[66:67]
	s_mov_b32 m0, s27
	s_nop 0
	global_load_lds_dwordx4 v128, s[54:55]
	s_mov_b32 m0, s30
	s_nop 0
	global_load_lds_dwordx4 v130, s[54:55]
	s_waitcnt vmcnt(8)
	s_waitcnt lgkmcnt(0)
	s_barrier
	s_setprio 1
	v_mfma_f32_16x16x32_bf16 v[60:63], v[140:143], v[180:183], v[60:63]
	v_mfma_f32_16x16x32_bf16 v[56:59], v[156:159], v[180:183], v[56:59]
	v_mfma_f32_16x16x32_bf16 v[48:51], v[140:143], v[188:191], v[48:51]
	v_mfma_f32_16x16x32_bf16 v[40:43], v[156:159], v[188:191], v[40:43]
	v_mfma_f32_16x16x32_bf16 v[32:35], v[140:143], v[196:199], v[32:35]
	v_mfma_f32_16x16x32_bf16 v[24:27], v[156:159], v[196:199], v[24:27]
	v_mfma_f32_16x16x32_bf16 v[16:19], v[140:143], v[204:207], v[16:19]
	v_mfma_f32_16x16x32_bf16 v[8:11], v[156:159], v[204:207], v[8:11]
	v_mfma_f32_16x16x32_bf16 v[60:63], v[152:155], v[184:187], v[60:63]
	v_mfma_f32_16x16x32_bf16 v[56:59], v[160:163], v[184:187], v[56:59]
	v_mfma_f32_16x16x32_bf16 v[48:51], v[152:155], v[192:195], v[48:51]
	v_mfma_f32_16x16x32_bf16 v[40:43], v[160:163], v[192:195], v[40:43]
	v_mfma_f32_16x16x32_bf16 v[32:35], v[152:155], v[200:203], v[32:35]
	v_mfma_f32_16x16x32_bf16 v[24:27], v[160:163], v[200:203], v[24:27]
	v_mfma_f32_16x16x32_bf16 v[16:19], v[152:155], v[208:211], v[16:19]
	v_mfma_f32_16x16x32_bf16 v[8:11], v[160:163], v[208:211], v[8:11]
	v_mfma_f32_16x16x32_bf16 v[52:55], v[164:167], v[180:183], v[52:55]
	v_mfma_f32_16x16x32_bf16 v[44:47], v[172:175], v[180:183], v[44:47]
	v_mfma_f32_16x16x32_bf16 v[36:39], v[164:167], v[188:191], v[36:39]
	v_mfma_f32_16x16x32_bf16 v[28:31], v[172:175], v[188:191], v[28:31]
	v_mfma_f32_16x16x32_bf16 v[20:23], v[164:167], v[196:199], v[20:23]
	v_mfma_f32_16x16x32_bf16 v[12:15], v[172:175], v[196:199], v[12:15]
	v_mfma_f32_16x16x32_bf16 v[4:7], v[164:167], v[204:207], v[4:7]
	v_mfma_f32_16x16x32_bf16 v[0:3], v[172:175], v[204:207], v[0:3]
	v_mfma_f32_16x16x32_bf16 v[52:55], v[168:171], v[184:187], v[52:55]
	v_mfma_f32_16x16x32_bf16 v[44:47], v[176:179], v[184:187], v[44:47]
	v_mfma_f32_16x16x32_bf16 v[36:39], v[168:171], v[192:195], v[36:39]
	v_mfma_f32_16x16x32_bf16 v[28:31], v[176:179], v[192:195], v[28:31]
	v_mfma_f32_16x16x32_bf16 v[20:23], v[168:171], v[200:203], v[20:23]
	v_mfma_f32_16x16x32_bf16 v[12:15], v[176:179], v[200:203], v[12:15]
	v_mfma_f32_16x16x32_bf16 v[4:7], v[168:171], v[208:211], v[4:7]
	v_mfma_f32_16x16x32_bf16 v[0:3], v[176:179], v[208:211], v[0:3]
	s_setprio 0
	s_barrier
	s_add_i32 s3, 0, 0x18000
	s_add_i32 s65, 0, 0x1c000
	v_add_u32_e32 v160, s3, v147
	v_add_u32_e32 v176, s65, v147
	ds_read_b128 v[140:143], v160
	ds_read_b128 v[152:155], v160 offset:1024
	ds_read_b128 v[156:159], v160 offset:2048
	ds_read_b128 v[160:163], v160 offset:3072
	ds_read_b128 v[164:167], v176
	ds_read_b128 v[168:171], v176 offset:1024
	ds_read_b128 v[172:175], v176 offset:2048
	ds_read_b128 v[176:179], v176 offset:3072
	s_add_u32 s54, s54, 0x200000
	s_addc_u32 s55, s55, 0
	s_mov_b32 m0, s31
	ds_read_b128 v[180:183], v151 offset:32768
	ds_read_b128 v[184:187], v151 offset:33792
	ds_read_b128 v[188:191], v151 offset:34816
	ds_read_b128 v[192:195], v151 offset:35840
	ds_read_b128 v[196:199], v151 offset:36864
	ds_read_b128 v[200:203], v151 offset:37888
	ds_read_b128 v[204:207], v151 offset:38912
	ds_read_b128 v[208:211], v151 offset:39936
	global_load_lds_dwordx4 v128, s[54:55]
	s_mov_b32 m0, s33
	s_nop 0
	global_load_lds_dwordx4 v130, s[54:55]
	s_waitcnt vmcnt(8)
	s_waitcnt lgkmcnt(0)
	s_barrier
	s_setprio 1
	v_mfma_f32_16x16x32_bf16 v[124:127], v[140:143], v[180:183], v[124:127]
	v_mfma_f32_16x16x32_bf16 v[120:123], v[156:159], v[180:183], v[120:123]
	v_mfma_f32_16x16x32_bf16 v[112:115], v[140:143], v[188:191], v[112:115]
	v_mfma_f32_16x16x32_bf16 v[104:107], v[156:159], v[188:191], v[104:107]
	v_mfma_f32_16x16x32_bf16 v[96:99], v[140:143], v[196:199], v[96:99]
	v_mfma_f32_16x16x32_bf16 v[88:91], v[156:159], v[196:199], v[88:91]
	v_mfma_f32_16x16x32_bf16 v[80:83], v[140:143], v[204:207], v[80:83]
	v_mfma_f32_16x16x32_bf16 v[72:75], v[156:159], v[204:207], v[72:75]
	v_mfma_f32_16x16x32_bf16 v[124:127], v[152:155], v[184:187], v[124:127]
	v_mfma_f32_16x16x32_bf16 v[120:123], v[160:163], v[184:187], v[120:123]
	v_mfma_f32_16x16x32_bf16 v[112:115], v[152:155], v[192:195], v[112:115]
	v_mfma_f32_16x16x32_bf16 v[104:107], v[160:163], v[192:195], v[104:107]
	v_mfma_f32_16x16x32_bf16 v[96:99], v[152:155], v[200:203], v[96:99]
	v_mfma_f32_16x16x32_bf16 v[88:91], v[160:163], v[200:203], v[88:91]
	v_mfma_f32_16x16x32_bf16 v[80:83], v[152:155], v[208:211], v[80:83]
	v_mfma_f32_16x16x32_bf16 v[72:75], v[160:163], v[208:211], v[72:75]
	v_mfma_f32_16x16x32_bf16 v[116:119], v[164:167], v[180:183], v[116:119]
	v_mfma_f32_16x16x32_bf16 v[108:111], v[172:175], v[180:183], v[108:111]
	v_mfma_f32_16x16x32_bf16 v[100:103], v[164:167], v[188:191], v[100:103]
	v_mfma_f32_16x16x32_bf16 v[92:95], v[172:175], v[188:191], v[92:95]
	v_mfma_f32_16x16x32_bf16 v[84:87], v[164:167], v[196:199], v[84:87]
	v_mfma_f32_16x16x32_bf16 v[76:79], v[172:175], v[196:199], v[76:79]
	v_mfma_f32_16x16x32_bf16 v[68:71], v[164:167], v[204:207], v[68:71]
	v_mfma_f32_16x16x32_bf16 v[64:67], v[172:175], v[204:207], v[64:67]
	v_mfma_f32_16x16x32_bf16 v[116:119], v[168:171], v[184:187], v[116:119]
	v_mfma_f32_16x16x32_bf16 v[108:111], v[176:179], v[184:187], v[108:111]
	v_mfma_f32_16x16x32_bf16 v[100:103], v[168:171], v[192:195], v[100:103]
	v_mfma_f32_16x16x32_bf16 v[92:95], v[176:179], v[192:195], v[92:95]
	v_mfma_f32_16x16x32_bf16 v[84:87], v[168:171], v[200:203], v[84:87]
	v_mfma_f32_16x16x32_bf16 v[76:79], v[176:179], v[200:203], v[76:79]
	v_mfma_f32_16x16x32_bf16 v[68:71], v[168:171], v[208:211], v[68:71]
	v_mfma_f32_16x16x32_bf16 v[64:67], v[176:179], v[208:211], v[64:67]
	s_setprio 0
	s_barrier
	s_add_i32 s3, s3, s25
	s_add_u32 s52, s52, 0x80
	s_addc_u32 s53, s53, 0
	s_mov_b32 m0, s3
	ds_read_b128 v[180:183], v151 offset:49152
	ds_read_b128 v[184:187], v151 offset:50176
	ds_read_b128 v[188:191], v151 offset:51200
	ds_read_b128 v[192:195], v151 offset:52224
	ds_read_b128 v[196:199], v151 offset:53248
	ds_read_b128 v[200:203], v151 offset:54272
	ds_read_b128 v[204:207], v151 offset:55296
	ds_read_b128 v[208:211], v151 offset:56320
	global_load_lds_dwordx4 v128, s[52:53]
	s_add_i32 m0, s3, 0x2000
	s_add_i32 s3, s65, s25
	global_load_lds_dwordx4 v130, s[52:53]
	s_add_u32 s52, s52, 0x200000
	s_addc_u32 s53, s53, 0
	s_mov_b32 m0, s3
	s_nop 0
	global_load_lds_dwordx4 v128, s[52:53]
	s_add_i32 m0, s3, 0x2000
	s_nop 0
	global_load_lds_dwordx4 v130, s[52:53]
	s_add_u32 s54, s54, 0xffe00080
	s_addc_u32 s55, s55, -1
	s_mov_b32 m0, s56
	s_nop 0
	global_load_lds_dwordx4 v128, s[54:55]
	s_mov_b32 m0, s57
	s_nop 0
	global_load_lds_dwordx4 v130, s[54:55]
	s_waitcnt vmcnt(8)
	s_waitcnt lgkmcnt(0)
	s_barrier
	s_setprio 1
	v_mfma_f32_16x16x32_bf16 v[60:63], v[140:143], v[180:183], v[60:63]
	v_mfma_f32_16x16x32_bf16 v[56:59], v[156:159], v[180:183], v[56:59]
	v_mfma_f32_16x16x32_bf16 v[48:51], v[140:143], v[188:191], v[48:51]
	v_mfma_f32_16x16x32_bf16 v[40:43], v[156:159], v[188:191], v[40:43]
	v_mfma_f32_16x16x32_bf16 v[32:35], v[140:143], v[196:199], v[32:35]
	v_mfma_f32_16x16x32_bf16 v[24:27], v[156:159], v[196:199], v[24:27]
	v_mfma_f32_16x16x32_bf16 v[16:19], v[140:143], v[204:207], v[16:19]
	v_mfma_f32_16x16x32_bf16 v[8:11], v[156:159], v[204:207], v[8:11]
	v_mfma_f32_16x16x32_bf16 v[60:63], v[152:155], v[184:187], v[60:63]
	v_mfma_f32_16x16x32_bf16 v[56:59], v[160:163], v[184:187], v[56:59]
	v_mfma_f32_16x16x32_bf16 v[48:51], v[152:155], v[192:195], v[48:51]
	v_mfma_f32_16x16x32_bf16 v[40:43], v[160:163], v[192:195], v[40:43]
	v_mfma_f32_16x16x32_bf16 v[32:35], v[152:155], v[200:203], v[32:35]
	v_mfma_f32_16x16x32_bf16 v[24:27], v[160:163], v[200:203], v[24:27]
	v_mfma_f32_16x16x32_bf16 v[16:19], v[152:155], v[208:211], v[16:19]
	v_mfma_f32_16x16x32_bf16 v[8:11], v[160:163], v[208:211], v[8:11]
	v_mfma_f32_16x16x32_bf16 v[52:55], v[164:167], v[180:183], v[52:55]
	v_mfma_f32_16x16x32_bf16 v[44:47], v[172:175], v[180:183], v[44:47]
	v_mfma_f32_16x16x32_bf16 v[36:39], v[164:167], v[188:191], v[36:39]
	v_mfma_f32_16x16x32_bf16 v[28:31], v[172:175], v[188:191], v[28:31]
	v_mfma_f32_16x16x32_bf16 v[20:23], v[164:167], v[196:199], v[20:23]
	v_mfma_f32_16x16x32_bf16 v[12:15], v[172:175], v[196:199], v[12:15]
	v_mfma_f32_16x16x32_bf16 v[4:7], v[164:167], v[204:207], v[4:7]
	v_mfma_f32_16x16x32_bf16 v[0:3], v[172:175], v[204:207], v[0:3]
	v_mfma_f32_16x16x32_bf16 v[52:55], v[168:171], v[184:187], v[52:55]
	v_mfma_f32_16x16x32_bf16 v[44:47], v[176:179], v[184:187], v[44:47]
	v_mfma_f32_16x16x32_bf16 v[36:39], v[168:171], v[192:195], v[36:39]
	v_mfma_f32_16x16x32_bf16 v[28:31], v[176:179], v[192:195], v[28:31]
	v_mfma_f32_16x16x32_bf16 v[20:23], v[168:171], v[200:203], v[20:23]
	v_mfma_f32_16x16x32_bf16 v[12:15], v[176:179], v[200:203], v[12:15]
	v_mfma_f32_16x16x32_bf16 v[4:7], v[168:171], v[208:211], v[4:7]
	v_mfma_f32_16x16x32_bf16 v[0:3], v[176:179], v[208:211], v[0:3]
	s_setprio 0
	s_add_i32 s64, s64, 2
	s_add_u32 s48, s48, 0x100
	s_addc_u32 s49, s49, 0
	s_add_u32 s50, s50, 0x100
	s_addc_u32 s51, s51, 0
	s_cmpk_gt_u32 s64, 0x7d
	s_barrier
	s_cbranch_scc0 .LBB0_2555
	s_and_b64 vcc, exec, s[10:11]
	s_cbranch_vccz .LBB0_2558
	s_barrier
